# row-scale loads of the 4 scale epilogues hoisted before the K-loop (no vmcnt(0) at epilogue start) + mixer0 rewrite
# speedup vs baseline: 1.0082x; 1.0046x over previous
;     __device__ __forceinline__ void operator()(const f32x4 (&acc)[2][2][4][2], const Unit& u, int wr, int wc, int fr, int fq) const {
;     ...
; #pragma unroll
;         for (int ai = 0; ai < 2; ++ai)
; #pragma unroll
;             for (int m = 0; m < 4; ++m) rsv[ai][m] = ss[row0 + ai * HALF + m * 16];
; template <class Epi, class Sched, bool ALIGN_EPI = false, bool SP2 = false>
; __device__ __forceinline__ void gemm_phase(PG8_LAS unsigned char* lds, const Gemm g, const Sched& S, const Epi& E) {
;     ...
; #pragma unroll
;         for (int a = 0; a < 2; ++a)
; #pragma unroll
;             for (int b = 0; b < 2; ++b)
; #pragma unroll
;                 for (int m = 0; m < 4; ++m)
; #pragma unroll
;                     for (int n = 0; n < 2; ++n) acc[a][b][m][n] = (f32x4){0.f, 0.f, 0.f, 0.f};
;         cur = nxt; cA = nA; cB = nB; ++ui;
.LBB0_104:
	s_ashr_i32 s91, s90, 31
	s_lshl_b64 s[6:7], s[90:91], 19
	s_add_u32 s92, s30, s6
	s_addc_u32 s93, s31, s7
	s_and_b64 s[6:7], s[2:3], exec
	s_cselect_b32 s1, s93, s97
	s_cselect_b32 s9, s92, s96
	s_ashr_i32 s89, s88, 31
	s_lshl_b64 s[6:7], s[88:89], 19
	s_add_u32 s6, s8, s6
	s_addc_u32 s7, s52, s7
	s_and_b64 s[12:13], s[2:3], exec
	s_cselect_b32 s12, s7, s95
	s_cselect_b32 s13, s6, s94
	s_add_u32 s96, s96, 0x40080
	s_addc_u32 s97, s97, 0
	s_add_u32 s14, s94, 0x100
	v_mov_b32_e32 v0, 0
	s_addc_u32 s15, s95, 0
	s_mov_b32 s16, -2
	v_mov_b32_e32 v1, v0
	v_mov_b32_e32 v2, v0
	v_mov_b32_e32 v3, v0
	v_mov_b32_e32 v4, v0
	v_mov_b32_e32 v5, v0
	v_mov_b32_e32 v6, v0
	v_mov_b32_e32 v7, v0
	v_mov_b32_e32 v16, v0
	v_mov_b32_e32 v17, v0
	v_mov_b32_e32 v18, v0
	v_mov_b32_e32 v19, v0
	v_mov_b32_e32 v20, v0
	v_mov_b32_e32 v21, v0
	v_mov_b32_e32 v22, v0
	v_mov_b32_e32 v23, v0
	v_mov_b32_e32 v32, v0
	v_mov_b32_e32 v33, v0
	v_mov_b32_e32 v34, v0
	v_mov_b32_e32 v35, v0
	v_mov_b32_e32 v36, v0
	v_mov_b32_e32 v37, v0
	v_mov_b32_e32 v38, v0
	v_mov_b32_e32 v39, v0
	v_mov_b32_e32 v48, v0
	v_mov_b32_e32 v49, v0
	v_mov_b32_e32 v50, v0
	v_mov_b32_e32 v51, v0
	v_mov_b32_e32 v52, v0
	v_mov_b32_e32 v53, v0
	v_mov_b32_e32 v54, v0
	v_mov_b32_e32 v55, v0
	v_mov_b32_e32 v8, v0
	v_mov_b32_e32 v9, v0
	v_mov_b32_e32 v10, v0
	v_mov_b32_e32 v11, v0
	v_mov_b32_e32 v12, v0
	v_mov_b32_e32 v13, v0
	v_mov_b32_e32 v14, v0
	v_mov_b32_e32 v15, v0
	v_mov_b32_e32 v24, v0
	v_mov_b32_e32 v25, v0
	v_mov_b32_e32 v26, v0
	v_mov_b32_e32 v27, v0
	v_mov_b32_e32 v28, v0
	v_mov_b32_e32 v29, v0
	v_mov_b32_e32 v30, v0
	v_mov_b32_e32 v31, v0
	v_mov_b32_e32 v40, v0
	v_mov_b32_e32 v41, v0
	v_mov_b32_e32 v42, v0
	v_mov_b32_e32 v43, v0
	v_mov_b32_e32 v44, v0
	v_mov_b32_e32 v45, v0
	v_mov_b32_e32 v46, v0
	v_mov_b32_e32 v47, v0
	v_mov_b32_e32 v56, v0
	v_mov_b32_e32 v57, v0
	v_mov_b32_e32 v58, v0
	v_mov_b32_e32 v59, v0
	v_mov_b32_e32 v60, v0
	v_mov_b32_e32 v61, v0
	v_mov_b32_e32 v62, v0
	v_mov_b32_e32 v63, v0
	v_mov_b32_e32 v64, v0
	v_mov_b32_e32 v65, v0
	v_mov_b32_e32 v66, v0
	v_mov_b32_e32 v67, v0
	v_mov_b32_e32 v68, v0
	v_mov_b32_e32 v69, v0
	v_mov_b32_e32 v70, v0
	v_mov_b32_e32 v71, v0
	v_mov_b32_e32 v80, v0
	v_mov_b32_e32 v81, v0
	v_mov_b32_e32 v82, v0
	v_mov_b32_e32 v83, v0
	v_mov_b32_e32 v84, v0
	v_mov_b32_e32 v85, v0
	v_mov_b32_e32 v86, v0
	v_mov_b32_e32 v87, v0
	v_mov_b32_e32 v96, v0
	v_mov_b32_e32 v97, v0
	v_mov_b32_e32 v98, v0
	v_mov_b32_e32 v99, v0
	v_mov_b32_e32 v100, v0
	v_mov_b32_e32 v101, v0
	v_mov_b32_e32 v102, v0
	v_mov_b32_e32 v103, v0
	v_mov_b32_e32 v112, v0
	v_mov_b32_e32 v113, v0
	v_mov_b32_e32 v114, v0
	v_mov_b32_e32 v115, v0
	v_mov_b32_e32 v116, v0
	v_mov_b32_e32 v117, v0
	v_mov_b32_e32 v118, v0
	v_mov_b32_e32 v119, v0
	v_mov_b32_e32 v72, v0
	v_mov_b32_e32 v73, v0
	v_mov_b32_e32 v74, v0
	v_mov_b32_e32 v75, v0
	v_mov_b32_e32 v76, v0
	v_mov_b32_e32 v77, v0
	v_mov_b32_e32 v78, v0
	v_mov_b32_e32 v79, v0
	v_mov_b32_e32 v88, v0
	v_mov_b32_e32 v89, v0
	v_mov_b32_e32 v90, v0
	v_mov_b32_e32 v91, v0
	v_mov_b32_e32 v92, v0
	v_mov_b32_e32 v93, v0
	v_mov_b32_e32 v94, v0
	v_mov_b32_e32 v95, v0
	v_mov_b32_e32 v104, v0
	v_mov_b32_e32 v105, v0
	v_mov_b32_e32 v106, v0
	v_mov_b32_e32 v107, v0
	v_mov_b32_e32 v108, v0
	v_mov_b32_e32 v109, v0
	v_mov_b32_e32 v110, v0
	v_mov_b32_e32 v111, v0
	v_mov_b32_e32 v120, v0
	v_mov_b32_e32 v121, v0
	v_mov_b32_e32 v122, v0
	v_mov_b32_e32 v123, v0
	v_mov_b32_e32 v124, v0
	v_mov_b32_e32 v125, v0
	v_mov_b32_e32 v126, v0
	v_mov_b32_e32 v127, v0
	v_lshl_add_u32 v236, s0, 8, v139
	v_ashrrev_i32_e32 v237, 31, v236
	v_lshl_add_u64 v[236:237], v[236:237], 2, s[72:73]
	global_load_dword v228, v[236:237], off
	global_load_dword v229, v[236:237], off offset:64
	global_load_dword v230, v[236:237], off offset:128
	global_load_dword v231, v[236:237], off offset:192
	global_load_dword v232, v[236:237], off offset:512
	global_load_dword v233, v[236:237], off offset:576
	global_load_dword v234, v[236:237], off offset:640
	global_load_dword v235, v[236:237], off offset:704

; __device__ __forceinline__ unsigned cvt_pk_bf16(float lo, float hi) { unsigned r; asm volatile("v_cvt_pk_bf16_f32 %0, %1, %2" : "=v"(r) : "v"(lo), "v"(hi)); return r; }
;     __device__ __forceinline__ void operator()(const f32x4 (&acc)[2][2][4][2], const Unit& u, int wr, int wc, int fr, int fq) const {
;     ...
;         for (int ai = 0; ai < 2; ++ai)
; #pragma unroll
;             for (int m = 0; m < 4; ++m) {
;                 const int row = row0 + ai * HALF + m * 16;
;                 const float rs = rsv[ai][m];
;                 bf16_t* rowp = O + (size_t)row * 1536;
;                 const f32x4 a0 = acc[ai][0][m][0] * rs, a1 = acc[ai][0][m][1] * rs, b0 = acc[ai][1][m][0] * rs, b1 = acc[ai][1][m][1] * rs;
;                 if (u.pn < 2) {
;                     u32x4 w; w.x = cvt_pk_bf16(a0[0], a0[1]); w.y = cvt_pk_bf16(a0[2], a0[3]); w.z = cvt_pk_bf16(a1[0], a1[1]); w.w = cvt_pk_bf16(a1[2], a1[3]);
;                     *(u32x4*)(rowp + u.pn * 256 + wcol) = w;
;                     w.x = cvt_pk_bf16(b0[0], b0[1]); w.y = cvt_pk_bf16(b0[2], b0[3]); w.z = cvt_pk_bf16(b1[0], b1[1]); w.w = cvt_pk_bf16(b1[2], b1[3]);
;                     *(u32x4*)(rowp + u.pn * 256 + 128 + wcol) = w;
;                 } else {
;                     f32x4 r0, r1;
;                     if (u.pn < 6) { r0 = a0 * b0; r1 = a1 * b1; }
;                     else {
; #pragma unroll
;                         for (int j = 0; j < 4; ++j) { r0[j] = a0[j] * __builtin_amdgcn_rcpf(1.0f + __expf(-b0[j])); r1[j] = a1[j] * __builtin_amdgcn_rcpf(1.0f + __expf(-b1[j])); }
.LBB0_108:
	v_lshl_add_u32 v148, s0, 8, v139
	v_mov_b64_e32 v[150:151], s[34:35]
	s_cmp_gt_i32 s50, 1
	v_mad_i64_i32 v[150:151], s[0:1], v148, s64, v[150:151]
	s_cselect_b64 s[94:95], -1, 0
	s_mov_b64 s[0:1], -1
	s_and_b64 vcc, exec, s[94:95]
	v_fmamk_f32 v136, v228, 0x3a800000, v164
	v_rsq_f32_e32 v136, v136
	s_nop 0
	v_pk_mul_f32 v[126:127], v[126:127], v[136:137] op_sel_hi:[1,0]
	v_pk_mul_f32 v[154:155], v[124:125], v[136:137] op_sel_hi:[1,0]
	v_pk_mul_f32 v[124:125], v[122:123], v[136:137] op_sel_hi:[1,0]
	v_pk_mul_f32 v[152:153], v[120:121], v[136:137] op_sel_hi:[1,0]
	v_pk_mul_f32 v[118:119], v[118:119], v[136:137] op_sel_hi:[1,0]
	v_pk_mul_f32 v[122:123], v[116:117], v[136:137] op_sel_hi:[1,0]
	v_pk_mul_f32 v[116:117], v[114:115], v[136:137] op_sel_hi:[1,0]
	v_pk_mul_f32 v[120:121], v[112:113], v[136:137] op_sel_hi:[1,0]
	s_cbranch_vccz .LBB0_112
	s_cmp_lt_u32 s50, 6
	v_mov_b32_e32 v112, v122
	v_mov_b32_e32 v113, v123
	v_mov_b32_e32 v156, v118
	v_mov_b32_e32 v157, v119
	v_mov_b32_e32 v114, v120
	v_mov_b32_e32 v115, v121
	v_mov_b32_e32 v158, v116
	v_mov_b32_e32 v159, v117
	s_cbranch_scc1 .LBB0_111
	v_mul_f32_e32 v113, 0xbfb8aa3b, v120
	v_mul_f32_e32 v114, 0xbfb8aa3b, v123
	v_exp_f32_e32 v113, v113
	v_exp_f32_e32 v115, v114
	v_mul_f32_e32 v114, 0xbfb8aa3b, v121
	v_exp_f32_e32 v136, v114
	v_add_f32_e32 v113, 1.0, v113
	v_rcp_f32_e32 v114, v113
	v_add_f32_e32 v113, 1.0, v115
	v_add_f32_e32 v115, 1.0, v136
	v_mul_f32_e32 v136, 0xbfb8aa3b, v118
	v_exp_f32_e32 v136, v136
	v_mul_f32_e32 v156, 0xbfb8aa3b, v116
	v_exp_f32_e32 v157, v156
	v_mul_f32_e32 v112, 0xbfb8aa3b, v122
	v_add_f32_e32 v136, 1.0, v136
	v_rcp_f32_e32 v156, v136
	v_add_f32_e32 v136, 1.0, v157
	v_mul_f32_e32 v157, 0xbfb8aa3b, v119
	v_exp_f32_e32 v157, v157
	v_mul_f32_e32 v158, 0xbfb8aa3b, v117
	v_exp_f32_e32 v112, v112
	v_exp_f32_e32 v159, v158
	v_rcp_f32_e32 v158, v136
	v_add_f32_e32 v136, 1.0, v157
	v_add_f32_e32 v112, 1.0, v112
	v_rcp_f32_e32 v157, v136
	v_add_f32_e32 v136, 1.0, v159
	v_rcp_f32_e32 v112, v112
	v_rcp_f32_e32 v113, v113
	v_rcp_f32_e32 v115, v115
	v_rcp_f32_e32 v159, v136

; __device__ __forceinline__ unsigned cvt_pk_bf16(float lo, float hi) { unsigned r; asm volatile("v_cvt_pk_bf16_f32 %0, %1, %2" : "=v"(r) : "v"(lo), "v"(hi)); return r; }
;     __device__ __forceinline__ void operator()(const f32x4 (&acc)[2][2][4][2], const Unit& u, int wr, int wc, int fr, int fq) const {
;     ...
;         for (int ai = 0; ai < 2; ++ai)
; #pragma unroll
;             for (int m = 0; m < 4; ++m) {
;                 const int row = row0 + ai * HALF + m * 16;
;                 const float rs = rsv[ai][m];
;                 bf16_t* rowp = O + (size_t)row * 1536;
;                 const f32x4 a0 = acc[ai][0][m][0] * rs, a1 = acc[ai][0][m][1] * rs, b0 = acc[ai][1][m][0] * rs, b1 = acc[ai][1][m][1] * rs;
;                 if (u.pn < 2) {
;                     u32x4 w; w.x = cvt_pk_bf16(a0[0], a0[1]); w.y = cvt_pk_bf16(a0[2], a0[3]); w.z = cvt_pk_bf16(a1[0], a1[1]); w.w = cvt_pk_bf16(a1[2], a1[3]);
;                     *(u32x4*)(rowp + u.pn * 256 + wcol) = w;
;                     w.x = cvt_pk_bf16(b0[0], b0[1]); w.y = cvt_pk_bf16(b0[2], b0[3]); w.z = cvt_pk_bf16(b1[0], b1[1]); w.w = cvt_pk_bf16(b1[2], b1[3]);
;                     *(u32x4*)(rowp + u.pn * 256 + 128 + wcol) = w;
;                 } else {
;                     f32x4 r0, r1;
;                     if (u.pn < 6) { r0 = a0 * b0; r1 = a1 * b1; }
;                     else {
; #pragma unroll
;                         for (int j = 0; j < 4; ++j) { r0[j] = a0[j] * __builtin_amdgcn_rcpf(1.0f + __expf(-b0[j])); r1[j] = a1[j] * __builtin_amdgcn_rcpf(1.0f + __expf(-b1[j])); }
;                     }
;                     u32x4 w; w.x = cvt_pk_bf16(r0[0], r0[1]); w.y = cvt_pk_bf16(r0[2], r0[3]); w.z = cvt_pk_bf16(r1[0], r1[1]); w.w = cvt_pk_bf16(r1[2], r1[3]);
;                     *(u32x4*)(rowp + (u.pn < 6 ? 512 + (u.pn - 2) * 128 : 1024 + (u.pn - 6) * 128) + wcol) = w;
.LBB0_114:
	v_fmamk_f32 v116, v229, 0x3a800000, v164
	v_rsq_f32_e32 v118, v116
	v_lshl_add_u64 v[116:117], v[156:157], 0, v[136:137]
	v_or_b32_e32 v119, 16, v148
	global_store_dwordx4 v[116:117], v[112:115], off
	v_pk_mul_f32 v[110:111], v[110:111], v[118:119] op_sel_hi:[1,0]
	v_pk_mul_f32 v[116:117], v[108:109], v[118:119] op_sel_hi:[1,0]
	v_mov_b64_e32 v[112:113], s[34:35]
	v_mad_i64_i32 v[112:113], s[0:1], v119, s64, v[112:113]
	v_pk_mul_f32 v[114:115], v[104:105], v[118:119] op_sel_hi:[1,0]
	v_pk_mul_f32 v[104:105], v[96:97], v[118:119] op_sel_hi:[1,0]
	v_cndmask_b32_e64 v96, 0, 1, s[94:95]
	v_pk_mul_f32 v[108:109], v[106:107], v[118:119] op_sel_hi:[1,0]
	v_pk_mul_f32 v[102:103], v[102:103], v[118:119] op_sel_hi:[1,0]
	v_pk_mul_f32 v[106:107], v[100:101], v[118:119] op_sel_hi:[1,0]
	v_pk_mul_f32 v[100:101], v[98:99], v[118:119] op_sel_hi:[1,0]
	v_cmp_ne_u32_e64 s[0:1], 1, v96
	s_andn2_b64 vcc, exec, s[94:95]
	s_mov_b64 s[28:29], -1
	s_cbranch_vccnz .LBB0_118
	s_cmp_lt_u32 s50, 6
	v_mov_b32_e32 v96, v106
	v_mov_b32_e32 v97, v107
	v_mov_b32_e32 v118, v102
	v_mov_b32_e32 v119, v103
	v_mov_b32_e32 v98, v104
	v_mov_b32_e32 v99, v105
	v_mov_b32_e32 v120, v100
	v_mov_b32_e32 v121, v101
	s_cbranch_scc1 .LBB0_117
	v_mul_f32_e32 v97, 0xbfb8aa3b, v104
	v_mul_f32_e32 v98, 0xbfb8aa3b, v107
	v_exp_f32_e32 v97, v97
	v_exp_f32_e32 v99, v98
	v_mul_f32_e32 v98, 0xbfb8aa3b, v105
	v_exp_f32_e32 v118, v98
	v_add_f32_e32 v97, 1.0, v97
	v_mul_f32_e32 v119, 0xbfb8aa3b, v100
	v_mul_f32_e32 v120, 0xbfb8aa3b, v103
	v_mul_f32_e32 v96, 0xbfb8aa3b, v106
	v_rcp_f32_e32 v98, v97
	v_add_f32_e32 v97, 1.0, v99
	v_add_f32_e32 v99, 1.0, v118
	v_mul_f32_e32 v118, 0xbfb8aa3b, v102
	v_exp_f32_e32 v119, v119
	v_exp_f32_e32 v121, v120
	v_mul_f32_e32 v120, 0xbfb8aa3b, v101
	v_exp_f32_e32 v96, v96
	v_exp_f32_e32 v118, v118
	v_exp_f32_e32 v122, v120
	v_add_f32_e32 v119, 1.0, v119
	v_add_f32_e32 v96, 1.0, v96
	v_add_f32_e32 v118, 1.0, v118
	v_rcp_f32_e32 v120, v119
	v_add_f32_e32 v119, 1.0, v121
	v_add_f32_e32 v121, 1.0, v122
	v_rcp_f32_e32 v96, v96
	v_rcp_f32_e32 v97, v97
	v_rcp_f32_e32 v99, v99
	v_rcp_f32_e32 v118, v118
	v_rcp_f32_e32 v119, v119
	v_rcp_f32_e32 v121, v121

; __device__ __forceinline__ unsigned cvt_pk_bf16(float lo, float hi) { unsigned r; asm volatile("v_cvt_pk_bf16_f32 %0, %1, %2" : "=v"(r) : "v"(lo), "v"(hi)); return r; }
;     __device__ __forceinline__ void operator()(const f32x4 (&acc)[2][2][4][2], const Unit& u, int wr, int wc, int fr, int fq) const {
;     ...
;         for (int ai = 0; ai < 2; ++ai)
; #pragma unroll
;             for (int m = 0; m < 4; ++m) {
;                 const int row = row0 + ai * HALF + m * 16;
;                 const float rs = rsv[ai][m];
;                 bf16_t* rowp = O + (size_t)row * 1536;
;                 const f32x4 a0 = acc[ai][0][m][0] * rs, a1 = acc[ai][0][m][1] * rs, b0 = acc[ai][1][m][0] * rs, b1 = acc[ai][1][m][1] * rs;
;                 if (u.pn < 2) {
;                     u32x4 w; w.x = cvt_pk_bf16(a0[0], a0[1]); w.y = cvt_pk_bf16(a0[2], a0[3]); w.z = cvt_pk_bf16(a1[0], a1[1]); w.w = cvt_pk_bf16(a1[2], a1[3]);
;                     *(u32x4*)(rowp + u.pn * 256 + wcol) = w;
;                     w.x = cvt_pk_bf16(b0[0], b0[1]); w.y = cvt_pk_bf16(b0[2], b0[3]); w.z = cvt_pk_bf16(b1[0], b1[1]); w.w = cvt_pk_bf16(b1[2], b1[3]);
;                     *(u32x4*)(rowp + u.pn * 256 + 128 + wcol) = w;
;                 } else {
;                     f32x4 r0, r1;
;                     if (u.pn < 6) { r0 = a0 * b0; r1 = a1 * b1; }
;                     else {
; #pragma unroll
;                         for (int j = 0; j < 4; ++j) { r0[j] = a0[j] * __builtin_amdgcn_rcpf(1.0f + __expf(-b0[j])); r1[j] = a1[j] * __builtin_amdgcn_rcpf(1.0f + __expf(-b1[j])); }
;                     }
;                     u32x4 w; w.x = cvt_pk_bf16(r0[0], r0[1]); w.y = cvt_pk_bf16(r0[2], r0[3]); w.z = cvt_pk_bf16(r1[0], r1[1]); w.w = cvt_pk_bf16(r1[2], r1[3]);
;                     *(u32x4*)(rowp + (u.pn < 6 ? 512 + (u.pn - 2) * 128 : 1024 + (u.pn - 6) * 128) + wcol) = w;
.LBB0_120:
	v_fmamk_f32 v100, v230, 0x3a800000, v164
	v_rsq_f32_e32 v102, v100
	v_lshl_add_u64 v[100:101], v[118:119], 0, v[136:137]
	v_or_b32_e32 v103, 32, v148
	global_store_dwordx4 v[100:101], v[96:99], off
	v_pk_mul_f32 v[94:95], v[94:95], v[102:103] op_sel_hi:[1,0]
	v_pk_mul_f32 v[100:101], v[92:93], v[102:103] op_sel_hi:[1,0]
	v_mov_b64_e32 v[96:97], s[34:35]
	v_mad_i64_i32 v[96:97], s[12:13], v103, s64, v[96:97]
	v_pk_mul_f32 v[92:93], v[90:91], v[102:103] op_sel_hi:[1,0]
	v_pk_mul_f32 v[98:99], v[88:89], v[102:103] op_sel_hi:[1,0]
	v_pk_mul_f32 v[86:87], v[86:87], v[102:103] op_sel_hi:[1,0]
	v_pk_mul_f32 v[90:91], v[84:85], v[102:103] op_sel_hi:[1,0]
	v_pk_mul_f32 v[84:85], v[82:83], v[102:103] op_sel_hi:[1,0]
	v_pk_mul_f32 v[88:89], v[80:81], v[102:103] op_sel_hi:[1,0]
	s_and_b64 vcc, exec, s[0:1]
	s_mov_b64 s[28:29], -1
	s_cbranch_vccnz .LBB0_124
	s_cmp_lt_u32 s50, 6
	v_mov_b32_e32 v80, v90
	v_mov_b32_e32 v81, v91
	v_mov_b32_e32 v102, v86
	v_mov_b32_e32 v103, v87
	v_mov_b32_e32 v82, v88
	v_mov_b32_e32 v83, v89
	v_mov_b32_e32 v104, v84
	v_mov_b32_e32 v105, v85
	s_cbranch_scc1 .LBB0_123
	v_mul_f32_e32 v81, 0xbfb8aa3b, v88
	v_mul_f32_e32 v82, 0xbfb8aa3b, v91
	v_exp_f32_e32 v81, v81
	v_exp_f32_e32 v83, v82
	v_mul_f32_e32 v82, 0xbfb8aa3b, v89
	v_exp_f32_e32 v102, v82
	v_add_f32_e32 v81, 1.0, v81
	v_mul_f32_e32 v103, 0xbfb8aa3b, v84
	v_mul_f32_e32 v104, 0xbfb8aa3b, v87
	v_mul_f32_e32 v80, 0xbfb8aa3b, v90
	v_rcp_f32_e32 v82, v81
	v_add_f32_e32 v81, 1.0, v83
	v_add_f32_e32 v83, 1.0, v102
	v_mul_f32_e32 v102, 0xbfb8aa3b, v86
	v_exp_f32_e32 v103, v103
	v_exp_f32_e32 v105, v104
	v_mul_f32_e32 v104, 0xbfb8aa3b, v85
	v_exp_f32_e32 v80, v80
	v_exp_f32_e32 v102, v102
	v_exp_f32_e32 v106, v104
	v_add_f32_e32 v103, 1.0, v103
	v_add_f32_e32 v80, 1.0, v80
	v_add_f32_e32 v102, 1.0, v102
	v_rcp_f32_e32 v104, v103
	v_add_f32_e32 v103, 1.0, v105
	v_add_f32_e32 v105, 1.0, v106
	v_rcp_f32_e32 v80, v80
	v_rcp_f32_e32 v81, v81
	v_rcp_f32_e32 v83, v83
	v_rcp_f32_e32 v102, v102
	v_rcp_f32_e32 v103, v103
	v_rcp_f32_e32 v105, v105

; __device__ __forceinline__ unsigned cvt_pk_bf16(float lo, float hi) { unsigned r; asm volatile("v_cvt_pk_bf16_f32 %0, %1, %2" : "=v"(r) : "v"(lo), "v"(hi)); return r; }
;     __device__ __forceinline__ void operator()(const f32x4 (&acc)[2][2][4][2], const Unit& u, int wr, int wc, int fr, int fq) const {
;     ...
;         for (int ai = 0; ai < 2; ++ai)
; #pragma unroll
;             for (int m = 0; m < 4; ++m) {
;                 const int row = row0 + ai * HALF + m * 16;
;                 const float rs = rsv[ai][m];
;                 bf16_t* rowp = O + (size_t)row * 1536;
;                 const f32x4 a0 = acc[ai][0][m][0] * rs, a1 = acc[ai][0][m][1] * rs, b0 = acc[ai][1][m][0] * rs, b1 = acc[ai][1][m][1] * rs;
;                 if (u.pn < 2) {
;                     u32x4 w; w.x = cvt_pk_bf16(a0[0], a0[1]); w.y = cvt_pk_bf16(a0[2], a0[3]); w.z = cvt_pk_bf16(a1[0], a1[1]); w.w = cvt_pk_bf16(a1[2], a1[3]);
;                     *(u32x4*)(rowp + u.pn * 256 + wcol) = w;
;                     w.x = cvt_pk_bf16(b0[0], b0[1]); w.y = cvt_pk_bf16(b0[2], b0[3]); w.z = cvt_pk_bf16(b1[0], b1[1]); w.w = cvt_pk_bf16(b1[2], b1[3]);
;                     *(u32x4*)(rowp + u.pn * 256 + 128 + wcol) = w;
;                 } else {
;                     f32x4 r0, r1;
;                     if (u.pn < 6) { r0 = a0 * b0; r1 = a1 * b1; }
;                     else {
; #pragma unroll
;                         for (int j = 0; j < 4; ++j) { r0[j] = a0[j] * __builtin_amdgcn_rcpf(1.0f + __expf(-b0[j])); r1[j] = a1[j] * __builtin_amdgcn_rcpf(1.0f + __expf(-b1[j])); }
;                     }
;                     u32x4 w; w.x = cvt_pk_bf16(r0[0], r0[1]); w.y = cvt_pk_bf16(r0[2], r0[3]); w.z = cvt_pk_bf16(r1[0], r1[1]); w.w = cvt_pk_bf16(r1[2], r1[3]);
;                     *(u32x4*)(rowp + (u.pn < 6 ? 512 + (u.pn - 2) * 128 : 1024 + (u.pn - 6) * 128) + wcol) = w;
.LBB0_126:
	v_fmamk_f32 v84, v231, 0x3a800000, v164
	v_rsq_f32_e32 v86, v84
	v_lshl_add_u64 v[84:85], v[102:103], 0, v[136:137]
	v_or_b32_e32 v87, 48, v148
	global_store_dwordx4 v[84:85], v[80:83], off
	v_pk_mul_f32 v[78:79], v[78:79], v[86:87] op_sel_hi:[1,0]
	v_pk_mul_f32 v[84:85], v[76:77], v[86:87] op_sel_hi:[1,0]
	v_mov_b64_e32 v[80:81], s[34:35]
	v_mad_i64_i32 v[80:81], s[12:13], v87, s64, v[80:81]
	v_pk_mul_f32 v[76:77], v[74:75], v[86:87] op_sel_hi:[1,0]
	v_pk_mul_f32 v[82:83], v[72:73], v[86:87] op_sel_hi:[1,0]
	v_pk_mul_f32 v[70:71], v[70:71], v[86:87] op_sel_hi:[1,0]
	v_pk_mul_f32 v[74:75], v[68:69], v[86:87] op_sel_hi:[1,0]
	v_pk_mul_f32 v[68:69], v[66:67], v[86:87] op_sel_hi:[1,0]
	v_pk_mul_f32 v[72:73], v[64:65], v[86:87] op_sel_hi:[1,0]
	s_and_b64 vcc, exec, s[0:1]
	s_mov_b64 s[28:29], -1
	s_cbranch_vccnz .LBB0_130
	s_cmp_lt_u32 s50, 6
	v_mov_b32_e32 v64, v74
	v_mov_b32_e32 v65, v75
	v_mov_b32_e32 v86, v70
	v_mov_b32_e32 v87, v71
	v_mov_b32_e32 v66, v72
	v_mov_b32_e32 v67, v73
	v_mov_b32_e32 v88, v68
	v_mov_b32_e32 v89, v69
	s_cbranch_scc1 .LBB0_129
	v_mul_f32_e32 v65, 0xbfb8aa3b, v72
	v_mul_f32_e32 v66, 0xbfb8aa3b, v75
	v_exp_f32_e32 v65, v65
	v_exp_f32_e32 v67, v66
	v_mul_f32_e32 v66, 0xbfb8aa3b, v73
	v_exp_f32_e32 v86, v66
	v_add_f32_e32 v65, 1.0, v65
	v_mul_f32_e32 v87, 0xbfb8aa3b, v68
	v_mul_f32_e32 v88, 0xbfb8aa3b, v71
	v_mul_f32_e32 v64, 0xbfb8aa3b, v74
	v_rcp_f32_e32 v66, v65
	v_add_f32_e32 v65, 1.0, v67
	v_add_f32_e32 v67, 1.0, v86
	v_mul_f32_e32 v86, 0xbfb8aa3b, v70
	v_exp_f32_e32 v87, v87
	v_exp_f32_e32 v89, v88
	v_mul_f32_e32 v88, 0xbfb8aa3b, v69
	v_exp_f32_e32 v64, v64
	v_exp_f32_e32 v86, v86
	v_exp_f32_e32 v90, v88
	v_add_f32_e32 v87, 1.0, v87
	v_add_f32_e32 v64, 1.0, v64
	v_add_f32_e32 v86, 1.0, v86
	v_rcp_f32_e32 v88, v87
	v_add_f32_e32 v87, 1.0, v89
	v_add_f32_e32 v89, 1.0, v90
	v_rcp_f32_e32 v64, v64
	v_rcp_f32_e32 v65, v65
	v_rcp_f32_e32 v67, v67
	v_rcp_f32_e32 v86, v86
	v_rcp_f32_e32 v87, v87
	v_rcp_f32_e32 v89, v89

; __device__ __forceinline__ unsigned cvt_pk_bf16(float lo, float hi) { unsigned r; asm volatile("v_cvt_pk_bf16_f32 %0, %1, %2" : "=v"(r) : "v"(lo), "v"(hi)); return r; }
;     __device__ __forceinline__ void operator()(const f32x4 (&acc)[2][2][4][2], const Unit& u, int wr, int wc, int fr, int fq) const {
;     ...
;         for (int ai = 0; ai < 2; ++ai)
; #pragma unroll
;             for (int m = 0; m < 4; ++m) {
;                 const int row = row0 + ai * HALF + m * 16;
;                 const float rs = rsv[ai][m];
;                 bf16_t* rowp = O + (size_t)row * 1536;
;                 const f32x4 a0 = acc[ai][0][m][0] * rs, a1 = acc[ai][0][m][1] * rs, b0 = acc[ai][1][m][0] * rs, b1 = acc[ai][1][m][1] * rs;
;                 if (u.pn < 2) {
;                     u32x4 w; w.x = cvt_pk_bf16(a0[0], a0[1]); w.y = cvt_pk_bf16(a0[2], a0[3]); w.z = cvt_pk_bf16(a1[0], a1[1]); w.w = cvt_pk_bf16(a1[2], a1[3]);
;                     *(u32x4*)(rowp + u.pn * 256 + wcol) = w;
;                     w.x = cvt_pk_bf16(b0[0], b0[1]); w.y = cvt_pk_bf16(b0[2], b0[3]); w.z = cvt_pk_bf16(b1[0], b1[1]); w.w = cvt_pk_bf16(b1[2], b1[3]);
;                     *(u32x4*)(rowp + u.pn * 256 + 128 + wcol) = w;
;                 } else {
;                     f32x4 r0, r1;
;                     if (u.pn < 6) { r0 = a0 * b0; r1 = a1 * b1; }
;                     else {
; #pragma unroll
;                         for (int j = 0; j < 4; ++j) { r0[j] = a0[j] * __builtin_amdgcn_rcpf(1.0f + __expf(-b0[j])); r1[j] = a1[j] * __builtin_amdgcn_rcpf(1.0f + __expf(-b1[j])); }
;                     }
;                     u32x4 w; w.x = cvt_pk_bf16(r0[0], r0[1]); w.y = cvt_pk_bf16(r0[2], r0[3]); w.z = cvt_pk_bf16(r1[0], r1[1]); w.w = cvt_pk_bf16(r1[2], r1[3]);
;                     *(u32x4*)(rowp + (u.pn < 6 ? 512 + (u.pn - 2) * 128 : 1024 + (u.pn - 6) * 128) + wcol) = w;
.LBB0_132:
	v_fmamk_f32 v68, v232, 0x3a800000, v164
	v_rsq_f32_e32 v70, v68
	v_lshl_add_u64 v[68:69], v[86:87], 0, v[136:137]
	v_add_u32_e32 v71, 0x80, v148
	global_store_dwordx4 v[68:69], v[64:67], off
	v_pk_mul_f32 v[62:63], v[62:63], v[70:71] op_sel_hi:[1,0]
	v_pk_mul_f32 v[68:69], v[60:61], v[70:71] op_sel_hi:[1,0]
	v_mov_b64_e32 v[64:65], s[34:35]
	v_mad_i64_i32 v[64:65], s[12:13], v71, s64, v[64:65]
	v_pk_mul_f32 v[60:61], v[58:59], v[70:71] op_sel_hi:[1,0]
	v_pk_mul_f32 v[66:67], v[56:57], v[70:71] op_sel_hi:[1,0]
	v_pk_mul_f32 v[54:55], v[54:55], v[70:71] op_sel_hi:[1,0]
	v_pk_mul_f32 v[58:59], v[52:53], v[70:71] op_sel_hi:[1,0]
	v_pk_mul_f32 v[52:53], v[50:51], v[70:71] op_sel_hi:[1,0]
	v_pk_mul_f32 v[56:57], v[48:49], v[70:71] op_sel_hi:[1,0]
	s_and_b64 vcc, exec, s[0:1]
	s_mov_b64 s[28:29], -1
	s_cbranch_vccnz .LBB0_136
	s_cmp_lt_u32 s50, 6
	v_mov_b32_e32 v48, v58
	v_mov_b32_e32 v49, v59
	v_mov_b32_e32 v70, v54
	v_mov_b32_e32 v71, v55
	v_mov_b32_e32 v50, v56
	v_mov_b32_e32 v51, v57
	v_mov_b32_e32 v72, v52
	v_mov_b32_e32 v73, v53
	s_cbranch_scc1 .LBB0_135
	v_mul_f32_e32 v49, 0xbfb8aa3b, v56
	v_mul_f32_e32 v50, 0xbfb8aa3b, v59
	v_exp_f32_e32 v49, v49
	v_exp_f32_e32 v51, v50
	v_mul_f32_e32 v50, 0xbfb8aa3b, v57
	v_exp_f32_e32 v70, v50
	v_add_f32_e32 v49, 1.0, v49
	v_mul_f32_e32 v71, 0xbfb8aa3b, v52
	v_mul_f32_e32 v72, 0xbfb8aa3b, v55
	v_mul_f32_e32 v48, 0xbfb8aa3b, v58
	v_rcp_f32_e32 v50, v49
	v_add_f32_e32 v49, 1.0, v51
	v_add_f32_e32 v51, 1.0, v70
	v_mul_f32_e32 v70, 0xbfb8aa3b, v54
	v_exp_f32_e32 v71, v71
	v_exp_f32_e32 v73, v72
	v_mul_f32_e32 v72, 0xbfb8aa3b, v53
	v_exp_f32_e32 v48, v48
	v_exp_f32_e32 v70, v70
	v_exp_f32_e32 v74, v72
	v_add_f32_e32 v71, 1.0, v71
	v_add_f32_e32 v48, 1.0, v48
	v_add_f32_e32 v70, 1.0, v70
	v_rcp_f32_e32 v72, v71
	v_add_f32_e32 v71, 1.0, v73
	v_add_f32_e32 v73, 1.0, v74
	v_rcp_f32_e32 v48, v48
	v_rcp_f32_e32 v49, v49
	v_rcp_f32_e32 v51, v51
	v_rcp_f32_e32 v70, v70
	v_rcp_f32_e32 v71, v71
	v_rcp_f32_e32 v73, v73

; __device__ __forceinline__ unsigned cvt_pk_bf16(float lo, float hi) { unsigned r; asm volatile("v_cvt_pk_bf16_f32 %0, %1, %2" : "=v"(r) : "v"(lo), "v"(hi)); return r; }
;     __device__ __forceinline__ void operator()(const f32x4 (&acc)[2][2][4][2], const Unit& u, int wr, int wc, int fr, int fq) const {
;     ...
;         for (int ai = 0; ai < 2; ++ai)
; #pragma unroll
;             for (int m = 0; m < 4; ++m) {
;                 const int row = row0 + ai * HALF + m * 16;
;                 const float rs = rsv[ai][m];
;                 bf16_t* rowp = O + (size_t)row * 1536;
;                 const f32x4 a0 = acc[ai][0][m][0] * rs, a1 = acc[ai][0][m][1] * rs, b0 = acc[ai][1][m][0] * rs, b1 = acc[ai][1][m][1] * rs;
;                 if (u.pn < 2) {
;                     u32x4 w; w.x = cvt_pk_bf16(a0[0], a0[1]); w.y = cvt_pk_bf16(a0[2], a0[3]); w.z = cvt_pk_bf16(a1[0], a1[1]); w.w = cvt_pk_bf16(a1[2], a1[3]);
;                     *(u32x4*)(rowp + u.pn * 256 + wcol) = w;
;                     w.x = cvt_pk_bf16(b0[0], b0[1]); w.y = cvt_pk_bf16(b0[2], b0[3]); w.z = cvt_pk_bf16(b1[0], b1[1]); w.w = cvt_pk_bf16(b1[2], b1[3]);
;                     *(u32x4*)(rowp + u.pn * 256 + 128 + wcol) = w;
;                 } else {
;                     f32x4 r0, r1;
;                     if (u.pn < 6) { r0 = a0 * b0; r1 = a1 * b1; }
;                     else {
; #pragma unroll
;                         for (int j = 0; j < 4; ++j) { r0[j] = a0[j] * __builtin_amdgcn_rcpf(1.0f + __expf(-b0[j])); r1[j] = a1[j] * __builtin_amdgcn_rcpf(1.0f + __expf(-b1[j])); }
;                     }
;                     u32x4 w; w.x = cvt_pk_bf16(r0[0], r0[1]); w.y = cvt_pk_bf16(r0[2], r0[3]); w.z = cvt_pk_bf16(r1[0], r1[1]); w.w = cvt_pk_bf16(r1[2], r1[3]);
;                     *(u32x4*)(rowp + (u.pn < 6 ? 512 + (u.pn - 2) * 128 : 1024 + (u.pn - 6) * 128) + wcol) = w;
.LBB0_138:
	v_fmamk_f32 v52, v233, 0x3a800000, v164
	v_rsq_f32_e32 v54, v52
	v_lshl_add_u64 v[52:53], v[70:71], 0, v[136:137]
	v_add_u32_e32 v55, 0x90, v148
	global_store_dwordx4 v[52:53], v[48:51], off
	v_pk_mul_f32 v[46:47], v[46:47], v[54:55] op_sel_hi:[1,0]
	v_pk_mul_f32 v[52:53], v[44:45], v[54:55] op_sel_hi:[1,0]
	v_mov_b64_e32 v[48:49], s[34:35]
	v_mad_i64_i32 v[48:49], s[12:13], v55, s64, v[48:49]
	v_pk_mul_f32 v[44:45], v[42:43], v[54:55] op_sel_hi:[1,0]
	v_pk_mul_f32 v[50:51], v[40:41], v[54:55] op_sel_hi:[1,0]
	v_pk_mul_f32 v[38:39], v[38:39], v[54:55] op_sel_hi:[1,0]
	v_pk_mul_f32 v[42:43], v[36:37], v[54:55] op_sel_hi:[1,0]
	v_pk_mul_f32 v[36:37], v[34:35], v[54:55] op_sel_hi:[1,0]
	v_pk_mul_f32 v[40:41], v[32:33], v[54:55] op_sel_hi:[1,0]
	s_and_b64 vcc, exec, s[0:1]
	s_mov_b64 s[28:29], -1
	s_cbranch_vccnz .LBB0_142
	s_cmp_lt_u32 s50, 6
	v_mov_b32_e32 v32, v42
	v_mov_b32_e32 v33, v43
	v_mov_b32_e32 v54, v38
	v_mov_b32_e32 v55, v39
	v_mov_b32_e32 v34, v40
	v_mov_b32_e32 v35, v41
	v_mov_b32_e32 v56, v36
	v_mov_b32_e32 v57, v37
	s_cbranch_scc1 .LBB0_141
	v_mul_f32_e32 v33, 0xbfb8aa3b, v40
	v_mul_f32_e32 v34, 0xbfb8aa3b, v43
	v_exp_f32_e32 v33, v33
	v_exp_f32_e32 v35, v34
	v_mul_f32_e32 v34, 0xbfb8aa3b, v41
	v_exp_f32_e32 v54, v34
	v_add_f32_e32 v33, 1.0, v33
	v_mul_f32_e32 v55, 0xbfb8aa3b, v36
	v_mul_f32_e32 v56, 0xbfb8aa3b, v39
	v_mul_f32_e32 v32, 0xbfb8aa3b, v42
	v_rcp_f32_e32 v34, v33
	v_add_f32_e32 v33, 1.0, v35
	v_add_f32_e32 v35, 1.0, v54
	v_mul_f32_e32 v54, 0xbfb8aa3b, v38
	v_exp_f32_e32 v55, v55
	v_exp_f32_e32 v57, v56
	v_mul_f32_e32 v56, 0xbfb8aa3b, v37
	v_exp_f32_e32 v32, v32
	v_exp_f32_e32 v54, v54
	v_exp_f32_e32 v58, v56
	v_add_f32_e32 v55, 1.0, v55
	v_add_f32_e32 v32, 1.0, v32
	v_add_f32_e32 v54, 1.0, v54
	v_rcp_f32_e32 v56, v55
	v_add_f32_e32 v55, 1.0, v57
	v_add_f32_e32 v57, 1.0, v58
	v_rcp_f32_e32 v32, v32
	v_rcp_f32_e32 v33, v33
	v_rcp_f32_e32 v35, v35
	v_rcp_f32_e32 v54, v54
	v_rcp_f32_e32 v55, v55
	v_rcp_f32_e32 v57, v57

; __device__ __forceinline__ unsigned cvt_pk_bf16(float lo, float hi) { unsigned r; asm volatile("v_cvt_pk_bf16_f32 %0, %1, %2" : "=v"(r) : "v"(lo), "v"(hi)); return r; }
;     __device__ __forceinline__ void operator()(const f32x4 (&acc)[2][2][4][2], const Unit& u, int wr, int wc, int fr, int fq) const {
;     ...
;         for (int ai = 0; ai < 2; ++ai)
; #pragma unroll
;             for (int m = 0; m < 4; ++m) {
;                 const int row = row0 + ai * HALF + m * 16;
;                 const float rs = rsv[ai][m];
;                 bf16_t* rowp = O + (size_t)row * 1536;
;                 const f32x4 a0 = acc[ai][0][m][0] * rs, a1 = acc[ai][0][m][1] * rs, b0 = acc[ai][1][m][0] * rs, b1 = acc[ai][1][m][1] * rs;
;                 if (u.pn < 2) {
;                     u32x4 w; w.x = cvt_pk_bf16(a0[0], a0[1]); w.y = cvt_pk_bf16(a0[2], a0[3]); w.z = cvt_pk_bf16(a1[0], a1[1]); w.w = cvt_pk_bf16(a1[2], a1[3]);
;                     *(u32x4*)(rowp + u.pn * 256 + wcol) = w;
;                     w.x = cvt_pk_bf16(b0[0], b0[1]); w.y = cvt_pk_bf16(b0[2], b0[3]); w.z = cvt_pk_bf16(b1[0], b1[1]); w.w = cvt_pk_bf16(b1[2], b1[3]);
;                     *(u32x4*)(rowp + u.pn * 256 + 128 + wcol) = w;
;                 } else {
;                     f32x4 r0, r1;
;                     if (u.pn < 6) { r0 = a0 * b0; r1 = a1 * b1; }
;                     else {
; #pragma unroll
;                         for (int j = 0; j < 4; ++j) { r0[j] = a0[j] * __builtin_amdgcn_rcpf(1.0f + __expf(-b0[j])); r1[j] = a1[j] * __builtin_amdgcn_rcpf(1.0f + __expf(-b1[j])); }
;                     }
;                     u32x4 w; w.x = cvt_pk_bf16(r0[0], r0[1]); w.y = cvt_pk_bf16(r0[2], r0[3]); w.z = cvt_pk_bf16(r1[0], r1[1]); w.w = cvt_pk_bf16(r1[2], r1[3]);
;                     *(u32x4*)(rowp + (u.pn < 6 ? 512 + (u.pn - 2) * 128 : 1024 + (u.pn - 6) * 128) + wcol) = w;
.LBB0_144:
	v_fmamk_f32 v36, v234, 0x3a800000, v164
	v_rsq_f32_e32 v38, v36
	v_lshl_add_u64 v[36:37], v[54:55], 0, v[136:137]
	v_add_u32_e32 v39, 0xa0, v148
	global_store_dwordx4 v[36:37], v[32:35], off
	v_pk_mul_f32 v[30:31], v[30:31], v[38:39] op_sel_hi:[1,0]
	v_pk_mul_f32 v[36:37], v[28:29], v[38:39] op_sel_hi:[1,0]
	v_mov_b64_e32 v[32:33], s[34:35]
	v_mad_i64_i32 v[32:33], s[12:13], v39, s64, v[32:33]
	v_pk_mul_f32 v[28:29], v[26:27], v[38:39] op_sel_hi:[1,0]
	v_pk_mul_f32 v[34:35], v[24:25], v[38:39] op_sel_hi:[1,0]
	v_pk_mul_f32 v[22:23], v[22:23], v[38:39] op_sel_hi:[1,0]
	v_pk_mul_f32 v[26:27], v[20:21], v[38:39] op_sel_hi:[1,0]
	v_pk_mul_f32 v[20:21], v[18:19], v[38:39] op_sel_hi:[1,0]
	v_pk_mul_f32 v[24:25], v[16:17], v[38:39] op_sel_hi:[1,0]
	s_and_b64 vcc, exec, s[0:1]
	s_mov_b64 s[28:29], -1
	s_cbranch_vccnz .LBB0_148
	s_cmp_lt_u32 s50, 6
	v_mov_b32_e32 v16, v26
	v_mov_b32_e32 v17, v27
	v_mov_b32_e32 v38, v22
	v_mov_b32_e32 v39, v23
	v_mov_b32_e32 v18, v24
	v_mov_b32_e32 v19, v25
	v_mov_b32_e32 v40, v20
	v_mov_b32_e32 v41, v21
	s_cbranch_scc1 .LBB0_147
	v_mul_f32_e32 v17, 0xbfb8aa3b, v24
	v_mul_f32_e32 v18, 0xbfb8aa3b, v27
	v_exp_f32_e32 v17, v17
	v_exp_f32_e32 v19, v18
	v_mul_f32_e32 v18, 0xbfb8aa3b, v25
	v_exp_f32_e32 v38, v18
	v_add_f32_e32 v17, 1.0, v17
	v_mul_f32_e32 v39, 0xbfb8aa3b, v20
	v_mul_f32_e32 v40, 0xbfb8aa3b, v23
	v_mul_f32_e32 v16, 0xbfb8aa3b, v26
	v_rcp_f32_e32 v18, v17
	v_add_f32_e32 v17, 1.0, v19
	v_add_f32_e32 v19, 1.0, v38
	v_mul_f32_e32 v38, 0xbfb8aa3b, v22
	v_exp_f32_e32 v39, v39
	v_exp_f32_e32 v41, v40
	v_mul_f32_e32 v40, 0xbfb8aa3b, v21
	v_exp_f32_e32 v16, v16
	v_exp_f32_e32 v38, v38
	v_exp_f32_e32 v42, v40
	v_add_f32_e32 v39, 1.0, v39
	v_add_f32_e32 v16, 1.0, v16
	v_add_f32_e32 v38, 1.0, v38
	v_rcp_f32_e32 v40, v39
	v_add_f32_e32 v39, 1.0, v41
	v_add_f32_e32 v41, 1.0, v42
	v_rcp_f32_e32 v16, v16
	v_rcp_f32_e32 v17, v17
	v_rcp_f32_e32 v19, v19
	v_rcp_f32_e32 v38, v38
	v_rcp_f32_e32 v39, v39
	v_rcp_f32_e32 v41, v41

; __device__ __forceinline__ unsigned cvt_pk_bf16(float lo, float hi) { unsigned r; asm volatile("v_cvt_pk_bf16_f32 %0, %1, %2" : "=v"(r) : "v"(lo), "v"(hi)); return r; }
;     __device__ __forceinline__ void operator()(const f32x4 (&acc)[2][2][4][2], const Unit& u, int wr, int wc, int fr, int fq) const {
;     ...
;         for (int ai = 0; ai < 2; ++ai)
; #pragma unroll
;             for (int m = 0; m < 4; ++m) {
;                 const int row = row0 + ai * HALF + m * 16;
;                 const float rs = rsv[ai][m];
;                 bf16_t* rowp = O + (size_t)row * 1536;
;                 const f32x4 a0 = acc[ai][0][m][0] * rs, a1 = acc[ai][0][m][1] * rs, b0 = acc[ai][1][m][0] * rs, b1 = acc[ai][1][m][1] * rs;
;                 if (u.pn < 2) {
;                     u32x4 w; w.x = cvt_pk_bf16(a0[0], a0[1]); w.y = cvt_pk_bf16(a0[2], a0[3]); w.z = cvt_pk_bf16(a1[0], a1[1]); w.w = cvt_pk_bf16(a1[2], a1[3]);
;                     *(u32x4*)(rowp + u.pn * 256 + wcol) = w;
;                     w.x = cvt_pk_bf16(b0[0], b0[1]); w.y = cvt_pk_bf16(b0[2], b0[3]); w.z = cvt_pk_bf16(b1[0], b1[1]); w.w = cvt_pk_bf16(b1[2], b1[3]);
;                     *(u32x4*)(rowp + u.pn * 256 + 128 + wcol) = w;
;                 } else {
;                     f32x4 r0, r1;
;                     if (u.pn < 6) { r0 = a0 * b0; r1 = a1 * b1; }
;                     else {
; #pragma unroll
;                         for (int j = 0; j < 4; ++j) { r0[j] = a0[j] * __builtin_amdgcn_rcpf(1.0f + __expf(-b0[j])); r1[j] = a1[j] * __builtin_amdgcn_rcpf(1.0f + __expf(-b1[j])); }
;                     }
;                     u32x4 w; w.x = cvt_pk_bf16(r0[0], r0[1]); w.y = cvt_pk_bf16(r0[2], r0[3]); w.z = cvt_pk_bf16(r1[0], r1[1]); w.w = cvt_pk_bf16(r1[2], r1[3]);
;                     *(u32x4*)(rowp + (u.pn < 6 ? 512 + (u.pn - 2) * 128 : 1024 + (u.pn - 6) * 128) + wcol) = w;
.LBB0_150:
	v_fmamk_f32 v20, v235, 0x3a800000, v164
	v_rsq_f32_e32 v22, v20
	v_lshl_add_u64 v[20:21], v[38:39], 0, v[136:137]
	v_add_u32_e32 v23, 0xb0, v148
	global_store_dwordx4 v[20:21], v[16:19], off
	v_pk_mul_f32 v[14:15], v[14:15], v[22:23] op_sel_hi:[1,0]
	v_pk_mul_f32 v[20:21], v[12:13], v[22:23] op_sel_hi:[1,0]
	v_mov_b64_e32 v[16:17], s[34:35]
	v_mad_i64_i32 v[16:17], s[12:13], v23, s64, v[16:17]
	v_pk_mul_f32 v[12:13], v[10:11], v[22:23] op_sel_hi:[1,0]
	v_pk_mul_f32 v[18:19], v[8:9], v[22:23] op_sel_hi:[1,0]
	v_pk_mul_f32 v[6:7], v[6:7], v[22:23] op_sel_hi:[1,0]
	v_pk_mul_f32 v[10:11], v[4:5], v[22:23] op_sel_hi:[1,0]
	v_pk_mul_f32 v[4:5], v[2:3], v[22:23] op_sel_hi:[1,0]
	v_pk_mul_f32 v[8:9], v[0:1], v[22:23] op_sel_hi:[1,0]
	s_and_b64 vcc, exec, s[0:1]
	s_mov_b64 s[0:1], -1
	s_cbranch_vccnz .LBB0_154
	s_cmp_lt_u32 s50, 6
	v_mov_b32_e32 v0, v10
	v_mov_b32_e32 v1, v11
	v_mov_b32_e32 v22, v6
	v_mov_b32_e32 v23, v7
	v_mov_b32_e32 v2, v8
	v_mov_b32_e32 v3, v9
	v_mov_b32_e32 v24, v4
	v_mov_b32_e32 v25, v5
	s_cbranch_scc1 .LBB0_153
	v_mul_f32_e32 v1, 0xbfb8aa3b, v8
	v_mul_f32_e32 v2, 0xbfb8aa3b, v11
	v_exp_f32_e32 v1, v1
	v_exp_f32_e32 v3, v2
	v_mul_f32_e32 v2, 0xbfb8aa3b, v9
	v_exp_f32_e32 v22, v2
	v_add_f32_e32 v1, 1.0, v1
	v_mul_f32_e32 v23, 0xbfb8aa3b, v4
	v_mul_f32_e32 v24, 0xbfb8aa3b, v7
	v_mul_f32_e32 v0, 0xbfb8aa3b, v10
	v_rcp_f32_e32 v2, v1
	v_add_f32_e32 v1, 1.0, v3
	v_add_f32_e32 v3, 1.0, v22
	v_mul_f32_e32 v22, 0xbfb8aa3b, v6
	v_exp_f32_e32 v23, v23
	v_exp_f32_e32 v25, v24
	v_mul_f32_e32 v24, 0xbfb8aa3b, v5
	v_exp_f32_e32 v0, v0
	v_exp_f32_e32 v22, v22
	v_exp_f32_e32 v26, v24
	v_add_f32_e32 v23, 1.0, v23
	v_add_f32_e32 v0, 1.0, v0
	v_add_f32_e32 v22, 1.0, v22
	v_rcp_f32_e32 v24, v23
	v_add_f32_e32 v23, 1.0, v25
	v_add_f32_e32 v25, 1.0, v26
	v_rcp_f32_e32 v0, v0
	v_rcp_f32_e32 v1, v1
	v_rcp_f32_e32 v3, v3
	v_rcp_f32_e32 v22, v22
	v_rcp_f32_e32 v23, v23
	v_rcp_f32_e32 v25, v25

;     __device__ __forceinline__ void operator()(const f32x4 (&acc)[2][2][4][2], const Unit& u, int wr, int wc, int fr, int fq) const {
;     ...
; #pragma unroll
;         for (int ai = 0; ai < 2; ++ai)
; #pragma unroll
;             for (int m = 0; m < 4; ++m) rsv[ai][m] = ss[row0 + ai * HALF + m * 16];
; template <class Epi, class Sched, bool ALIGN_EPI = false, bool SP2 = false>
; __device__ __forceinline__ void gemm_phase(PG8_LAS unsigned char* lds, const Gemm g, const Sched& S, const Epi& E) {
;     ...
; #pragma unroll
;         for (int a = 0; a < 2; ++a)
; #pragma unroll
;             for (int b = 0; b < 2; ++b)
; #pragma unroll
;                 for (int m = 0; m < 4; ++m)
; #pragma unroll
;                     for (int n = 0; n < 2; ++n) acc[a][b][m][n] = (f32x4){0.f, 0.f, 0.f, 0.f};
;         cur = nxt; cA = nA; cB = nB; ++ui;
.LBB0_489:
	s_ashr_i32 s63, s62, 31
	s_lshl_b64 s[6:7], s[62:63], 19
	s_add_u32 s64, s30, s6
	s_addc_u32 s65, s31, s7
	s_and_b64 s[6:7], exec, s[4:5]
	s_cselect_b32 s19, s81, s65
	s_cselect_b32 s20, s80, s64
	s_ashr_i32 s61, s60, 31
	s_lshl_b64 s[6:7], s[60:61], 19
	s_add_u32 s76, s38, s6
	s_addc_u32 s77, s39, s7
	s_and_b64 s[6:7], exec, s[4:5]
	s_cselect_b32 s21, s83, s77
	s_cselect_b32 s22, s82, s76
	v_mov_b32_e32 v0, 0
	s_cmp_lt_i32 s62, 64
	s_mov_b32 s23, 0
	s_cselect_b64 s[84:85], -1, 0
	v_mov_b32_e32 v1, v0
	v_mov_b32_e32 v2, v0
	v_mov_b32_e32 v3, v0
	v_mov_b32_e32 v4, v0
	v_mov_b32_e32 v5, v0
	v_mov_b32_e32 v6, v0
	v_mov_b32_e32 v7, v0
	v_mov_b32_e32 v16, v0
	v_mov_b32_e32 v17, v0
	v_mov_b32_e32 v18, v0
	v_mov_b32_e32 v19, v0
	v_mov_b32_e32 v20, v0
	v_mov_b32_e32 v21, v0
	v_mov_b32_e32 v22, v0
	v_mov_b32_e32 v23, v0
	v_mov_b32_e32 v32, v0
	v_mov_b32_e32 v33, v0
	v_mov_b32_e32 v34, v0
	v_mov_b32_e32 v35, v0
	v_mov_b32_e32 v36, v0
	v_mov_b32_e32 v37, v0
	v_mov_b32_e32 v38, v0
	v_mov_b32_e32 v39, v0
	v_mov_b32_e32 v48, v0
	v_mov_b32_e32 v49, v0
	v_mov_b32_e32 v50, v0
	v_mov_b32_e32 v51, v0
	v_mov_b32_e32 v52, v0
	v_mov_b32_e32 v53, v0
	v_mov_b32_e32 v54, v0
	v_mov_b32_e32 v55, v0
	v_mov_b32_e32 v8, v0
	v_mov_b32_e32 v9, v0
	v_mov_b32_e32 v10, v0
	v_mov_b32_e32 v11, v0
	v_mov_b32_e32 v12, v0
	v_mov_b32_e32 v13, v0
	v_mov_b32_e32 v14, v0
	v_mov_b32_e32 v15, v0
	v_mov_b32_e32 v24, v0
	v_mov_b32_e32 v25, v0
	v_mov_b32_e32 v26, v0
	v_mov_b32_e32 v27, v0
	v_mov_b32_e32 v28, v0
	v_mov_b32_e32 v29, v0
	v_mov_b32_e32 v30, v0
	v_mov_b32_e32 v31, v0
	v_mov_b32_e32 v40, v0
	v_mov_b32_e32 v41, v0
	v_mov_b32_e32 v42, v0
	v_mov_b32_e32 v43, v0
	v_mov_b32_e32 v44, v0
	v_mov_b32_e32 v45, v0
	v_mov_b32_e32 v46, v0
	v_mov_b32_e32 v47, v0
	v_mov_b32_e32 v56, v0
	v_mov_b32_e32 v57, v0
	v_mov_b32_e32 v58, v0
	v_mov_b32_e32 v59, v0
	v_mov_b32_e32 v60, v0
	v_mov_b32_e32 v61, v0
	v_mov_b32_e32 v62, v0
	v_mov_b32_e32 v63, v0
	v_mov_b32_e32 v64, v0
	v_mov_b32_e32 v65, v0
	v_mov_b32_e32 v66, v0
	v_mov_b32_e32 v67, v0
	v_mov_b32_e32 v68, v0
	v_mov_b32_e32 v69, v0
	v_mov_b32_e32 v70, v0
	v_mov_b32_e32 v71, v0
	v_mov_b32_e32 v80, v0
	v_mov_b32_e32 v81, v0
	v_mov_b32_e32 v82, v0
	v_mov_b32_e32 v83, v0
	v_mov_b32_e32 v84, v0
	v_mov_b32_e32 v85, v0
	v_mov_b32_e32 v86, v0
	v_mov_b32_e32 v87, v0
	v_mov_b32_e32 v96, v0
	v_mov_b32_e32 v97, v0
	v_mov_b32_e32 v98, v0
	v_mov_b32_e32 v99, v0
	v_mov_b32_e32 v100, v0
	v_mov_b32_e32 v101, v0
	v_mov_b32_e32 v102, v0
	v_mov_b32_e32 v103, v0
	v_mov_b32_e32 v112, v0
	v_mov_b32_e32 v113, v0
	v_mov_b32_e32 v114, v0
	v_mov_b32_e32 v115, v0
	v_mov_b32_e32 v116, v0
	v_mov_b32_e32 v117, v0
	v_mov_b32_e32 v118, v0
	v_mov_b32_e32 v119, v0
	v_mov_b32_e32 v72, v0
	v_mov_b32_e32 v73, v0
	v_mov_b32_e32 v74, v0
	v_mov_b32_e32 v75, v0
	v_mov_b32_e32 v76, v0
	v_mov_b32_e32 v77, v0
	v_mov_b32_e32 v78, v0
	v_mov_b32_e32 v79, v0
	v_mov_b32_e32 v88, v0
	v_mov_b32_e32 v89, v0
	v_mov_b32_e32 v90, v0
	v_mov_b32_e32 v91, v0
	v_mov_b32_e32 v92, v0
	v_mov_b32_e32 v93, v0
	v_mov_b32_e32 v94, v0
	v_mov_b32_e32 v95, v0
	v_mov_b32_e32 v104, v0
	v_mov_b32_e32 v105, v0
	v_mov_b32_e32 v106, v0
	v_mov_b32_e32 v107, v0
	v_mov_b32_e32 v108, v0
	v_mov_b32_e32 v109, v0
	v_mov_b32_e32 v110, v0
	v_mov_b32_e32 v111, v0
	v_mov_b32_e32 v120, v0
	v_mov_b32_e32 v121, v0
	v_mov_b32_e32 v122, v0
	v_mov_b32_e32 v123, v0
	v_mov_b32_e32 v124, v0
	v_mov_b32_e32 v125, v0
	v_mov_b32_e32 v126, v0
	v_mov_b32_e32 v127, v0
	v_lshl_add_u32 v236, s78, 8, v138
	v_ashrrev_i32_e32 v237, 31, v236
	v_lshl_add_u64 v[236:237], v[236:237], 2, s[42:43]
	global_load_dword v228, v[236:237], off
	global_load_dword v229, v[236:237], off offset:64
	global_load_dword v230, v[236:237], off offset:128
	global_load_dword v231, v[236:237], off offset:192
	global_load_dword v232, v[236:237], off offset:512
	global_load_dword v233, v[236:237], off offset:576
	global_load_dword v234, v[236:237], off offset:640
	global_load_dword v235, v[236:237], off offset:704
	s_branch .LBB0_493

; __device__ __forceinline__ unsigned cvt_pk_bf16(float lo, float hi) { unsigned r; asm volatile("v_cvt_pk_bf16_f32 %0, %1, %2" : "=v"(r) : "v"(lo), "v"(hi)); return r; }
;     __device__ __forceinline__ void operator()(const f32x4 (&acc)[2][2][4][2], const Unit& u, int wr, int wc, int fr, int fq) const {
;     ...
;         for (int ai = 0; ai < 2; ++ai)
; #pragma unroll
;             for (int m = 0; m < 4; ++m) rsv[ai][m] = __builtin_amdgcn_rsqf(rsv[ai][m] * (1.0f / 1024.0f) + RMS_EPS);
; #pragma unroll
;         for (int ai = 0; ai < 2; ++ai)
; #pragma unroll
;             for (int m = 0; m < 4; ++m) {
;                 if (ai == 1 && !whole) continue;
;                 const int row = row0 + ai * HALF + m * 16;
;                 const float rs = rsv[ai][m];
;                 float s1 = 0.f, s2 = 0.f;
;                 bf16_t* rowp = BLK ? O + ((size_t)u.pm * (ldc >> 6) + (size_t)(col0 >> 6)) * 16384 + (size_t)((col0 >> 5) & 1) * 8192 + (size_t)(row - u.pm * BM) * 32 + (col0 & 31) : O + (size_t)row * ldc + col0;
; #pragma unroll
;                 for (int bj = 0; bj < 2; ++bj) {
;                     if (bj == 1 && !whole) continue;
;                     f32x4 v0 = acc[ai][bj][m][0] * rs, v1 = acc[ai][bj][m][1] * rs;
;                     if (ACT == 1) {
; #pragma unroll
;                         for (int j = 0; j < 4; ++j) { const float a = fmaxf(v0[j], 0.f), b = fmaxf(v1[j], 0.f); v0[j] = a * a; v1[j] = b * b; }
;                     }
;                     u32x4 w; w.x = cvt_pk_bf16(v0[0], v0[1]); w.y = cvt_pk_bf16(v0[2], v0[3]); w.z = cvt_pk_bf16(v1[0], v1[1]); w.w = cvt_pk_bf16(v1[2], v1[3]);
;                     *(u32x4*)(rowp + (BLK ? bj * 2 * 16384 : bj * HALF)) = w;
.LBB0_501:
	s_lshl_b32 s6, s78, 8
	v_add_u32_e32 v150, s6, v138
	v_or_b32_e32 v160, 16, v150
	v_or_b32_e32 v158, 32, v150
	v_ashrrev_i32_e32 v161, 31, v160
	v_ashrrev_i32_e32 v159, 31, v158
	v_or_b32_e32 v154, 48, v150
	v_ashrrev_i32_e32 v151, 31, v150
	v_lshl_add_u64 v[152:153], v[160:161], 2, s[42:43]
	v_lshl_add_u64 v[156:157], v[158:159], 2, s[42:43]
	v_ashrrev_i32_e32 v155, 31, v154
	v_lshl_add_u64 v[150:151], v[150:151], 2, s[42:43]
	v_lshl_add_u64 v[162:163], v[154:155], 2, s[42:43]
	s_nop 0
	s_nop 0
	s_nop 0
	s_lshl_b32 s4, s18, 8
	s_or_b32 s7, s4, s96
	s_ashr_i32 s18, s7, 6
	s_ashr_i32 s79, s78, 31
	s_ashr_i32 s19, s18, 31
	s_lshl_b64 s[4:5], s[78:79], 21
	s_lshl_b64 s[18:19], s[18:19], 15
	s_add_u32 s4, s34, s4
	s_addc_u32 s5, s35, s5
	s_add_u32 s4, s4, s18
	s_addc_u32 s5, s5, s19
	s_add_u32 s4, s4, s16
	s_addc_u32 s5, s5, 0
	v_lshl_add_u64 v[150:151], s[4:5], 0, v[140:141]
	v_lshl_add_u64 v[162:163], v[150:151], 0, v[136:137]
	v_fmamk_f32 v146, v232, 0x3a800000, v149
	v_fmamk_f32 v148, v233, 0x3a800000, v149
	v_fmamk_f32 v151, v234, 0x3a800000, v149
	v_rsq_f32_e32 v150, v148
	v_rsq_f32_e32 v148, v151
	v_fmamk_f32 v155, v235, 0x3a800000, v149
	v_fmamk_f32 v159, v229, 0x3a800000, v149
	v_fmamk_f32 v151, v228, 0x3a800000, v149
	v_rsq_f32_e32 v164, v151
	v_rsq_f32_e32 v166, v159
	v_fmamk_f32 v153, v230, 0x3a800000, v149
	v_rsq_f32_e32 v152, v146
	v_pk_mul_f32 v[126:127], v[126:127], v[164:165] op_sel_hi:[1,0]
	v_pk_mul_f32 v[124:125], v[124:125], v[164:165] op_sel_hi:[1,0]
	v_pk_mul_f32 v[116:117], v[116:117], v[164:165] op_sel_hi:[1,0]
	v_pk_mul_f32 v[112:113], v[112:113], v[164:165] op_sel_hi:[1,0]
	v_pk_mul_f32 v[122:123], v[122:123], v[164:165] op_sel_hi:[1,0]
	v_pk_mul_f32 v[120:121], v[120:121], v[164:165] op_sel_hi:[1,0]
	v_pk_mul_f32 v[114:115], v[114:115], v[164:165] op_sel_hi:[1,0]
	v_max_f32_e32 v124, 0, v124
	v_max_f32_e32 v125, 0, v125
	v_max_f32_e32 v126, 0, v126
	v_max_f32_e32 v127, 0, v127
	v_max_f32_e32 v116, 0, v116
	v_max_f32_e32 v112, 0, v112
	v_pk_mul_f32 v[118:119], v[118:119], v[164:165] op_sel_hi:[1,0]
	v_max_f32_e32 v120, 0, v120
	v_max_f32_e32 v121, 0, v121
	v_max_f32_e32 v122, 0, v122
	v_max_f32_e32 v123, 0, v123
	v_max_f32_e32 v117, 0, v117
	v_max_f32_e32 v113, 0, v113
	v_max_f32_e32 v114, 0, v114
	v_max_f32_e32 v151, 0, v115
	v_mul_f32_e32 v115, v124, v124
	v_mul_f32_e32 v124, v125, v125
	v_mul_f32_e32 v125, v126, v126
	v_mul_f32_e32 v126, v127, v127
	v_mul_f32_e32 v116, v116, v116
	v_mul_f32_e32 v127, v112, v112
	v_cvt_pk_bf16_f32 v112, v115, v124
	v_rsq_f32_e32 v146, v155
	v_rsq_f32_e32 v168, v153
	v_max_f32_e32 v119, 0, v119
	v_mul_f32_e32 v120, v120, v120
	v_mul_f32_e32 v121, v121, v121
	v_mul_f32_e32 v122, v122, v122
	v_mul_f32_e32 v123, v123, v123
	v_mul_f32_e32 v117, v117, v117
	v_mul_f32_e32 v153, v113, v113
	v_mul_f32_e32 v155, v114, v114
	v_cvt_pk_bf16_f32 v113, v125, v126
	v_cvt_pk_bf16_f32 v114, v120, v121
	v_cvt_pk_bf16_f32 v115, v122, v123
	global_store_dwordx4 v[162:163], v[112:115], off
	v_max_f32_e32 v118, 0, v118
	v_mul_f32_e32 v118, v118, v118
	v_cvt_pk_bf16_f32 v112, v116, v117
	v_add_co_u32_e32 v116, vcc, s95, v162
	v_mul_f32_e32 v113, v119, v119
	v_mul_f32_e32 v115, v151, v151
	v_addc_co_u32_e32 v117, vcc, 0, v163, vcc
	v_cvt_pk_bf16_f32 v113, v118, v113
	v_cvt_pk_bf16_f32 v114, v127, v153
	v_cvt_pk_bf16_f32 v115, v155, v115
	global_store_dwordx4 v[116:117], v[112:115], off
	v_pk_mul_f32 v[104:105], v[104:105], v[166:167] op_sel_hi:[1,0]
	v_pk_mul_f32 v[108:109], v[108:109], v[166:167] op_sel_hi:[1,0]
	v_subrev_u32_e32 v112, s6, v160
	v_ashrrev_i32_e32 v113, 31, v112
	v_pk_mul_f32 v[106:107], v[106:107], v[166:167] op_sel_hi:[1,0]
	v_max_f32_e32 v104, 0, v104
	v_lshlrev_b64 v[112:113], 6, v[112:113]
	v_pk_mul_f32 v[110:111], v[110:111], v[166:167] op_sel_hi:[1,0]
	v_mul_f32_e32 v114, v104, v104
	v_max_f32_e32 v104, 0, v109
	v_max_f32_e32 v105, 0, v105
	v_max_f32_e32 v106, 0, v106
	v_lshl_add_u64 v[112:113], s[4:5], 0, v[112:113]
	v_max_f32_e32 v108, 0, v108
	v_mul_f32_e32 v104, v104, v104
	v_mul_f32_e32 v109, v105, v105
	v_max_f32_e32 v105, 0, v110
	v_mul_f32_e32 v110, v106, v106
	v_max_f32_e32 v106, 0, v111
	v_max_f32_e32 v107, 0, v107
	v_pk_mul_f32 v[96:97], v[96:97], v[166:167] op_sel_hi:[1,0]
	v_lshl_add_u64 v[112:113], v[112:113], 0, v[136:137]
	v_mul_f32_e32 v108, v108, v108
	v_mul_f32_e32 v105, v105, v105
	v_mul_f32_e32 v106, v106, v106
	v_mul_f32_e32 v107, v107, v107
	v_cvt_pk_bf16_f32 v104, v108, v104
	v_pk_mul_f32 v[100:101], v[100:101], v[166:167] op_sel_hi:[1,0]
	v_pk_mul_f32 v[98:99], v[98:99], v[166:167] op_sel_hi:[1,0]
	v_max_f32_e32 v96, 0, v96
	v_cvt_pk_bf16_f32 v105, v105, v106
	v_cvt_pk_bf16_f32 v106, v114, v109
	v_cvt_pk_bf16_f32 v107, v110, v107
	global_store_dwordx4 v[112:113], v[104:107], off
	v_pk_mul_f32 v[102:103], v[102:103], v[166:167] op_sel_hi:[1,0]
	v_max_f32_e32 v100, 0, v100
	v_mul_f32_e32 v104, v96, v96
	v_max_f32_e32 v96, 0, v101
	v_max_f32_e32 v97, 0, v97
	v_max_f32_e32 v98, 0, v98
	v_mul_f32_e32 v100, v100, v100
	v_mul_f32_e32 v96, v96, v96
	v_mul_f32_e32 v101, v97, v97
	v_max_f32_e32 v97, 0, v102
	v_mul_f32_e32 v102, v98, v98
	v_max_f32_e32 v98, 0, v103
	v_mul_f32_e32 v97, v97, v97
	v_max_f32_e32 v99, 0, v99
	v_mul_f32_e32 v98, v98, v98
	v_cvt_pk_bf16_f32 v96, v100, v96
	v_add_co_u32_e32 v100, vcc, s95, v112
	v_mul_f32_e32 v99, v99, v99
	v_cvt_pk_bf16_f32 v97, v97, v98
	v_cvt_pk_bf16_f32 v98, v104, v101
	s_nop 0
	v_addc_co_u32_e32 v101, vcc, 0, v113, vcc
	v_cvt_pk_bf16_f32 v99, v102, v99
	global_store_dwordx4 v[100:101], v[96:99], off
	v_pk_mul_f32 v[88:89], v[88:89], v[168:169] op_sel_hi:[1,0]
	v_pk_mul_f32 v[92:93], v[92:93], v[168:169] op_sel_hi:[1,0]
; __device__ __forceinline__ unsigned cvt_pk_bf16(float lo, float hi) { unsigned r; asm volatile("v_cvt_pk_bf16_f32 %0, %1, %2" : "=v"(r) : "v"(lo), "v"(hi)); return r; }
;     __device__ __forceinline__ void operator()(const f32x4 (&acc)[2][2][4][2], const Unit& u, int wr, int wc, int fr, int fq) const {
;     ...
;         for (int ai = 0; ai < 2; ++ai)
; #pragma unroll
;             for (int m = 0; m < 4; ++m) {
;                 if (ai == 1 && !whole) continue;
;                 const int row = row0 + ai * HALF + m * 16;
;                 const float rs = rsv[ai][m];
;                 float s1 = 0.f, s2 = 0.f;
;                 bf16_t* rowp = BLK ? O + ((size_t)u.pm * (ldc >> 6) + (size_t)(col0 >> 6)) * 16384 + (size_t)((col0 >> 5) & 1) * 8192 + (size_t)(row - u.pm * BM) * 32 + (col0 & 31) : O + (size_t)row * ldc + col0;
; #pragma unroll
;                 for (int bj = 0; bj < 2; ++bj) {
;                     if (bj == 1 && !whole) continue;
;                     f32x4 v0 = acc[ai][bj][m][0] * rs, v1 = acc[ai][bj][m][1] * rs;
;                     if (ACT == 1) {
; #pragma unroll
;                         for (int j = 0; j < 4; ++j) { const float a = fmaxf(v0[j], 0.f), b = fmaxf(v1[j], 0.f); v0[j] = a * a; v1[j] = b * b; }
;                     }
;                     u32x4 w; w.x = cvt_pk_bf16(v0[0], v0[1]); w.y = cvt_pk_bf16(v0[2], v0[3]); w.z = cvt_pk_bf16(v1[0], v1[1]); w.w = cvt_pk_bf16(v1[2], v1[3]);
;                     *(u32x4*)(rowp + (BLK ? bj * 2 * 16384 : bj * HALF)) = w;
	v_subrev_u32_e32 v96, s6, v158
	v_ashrrev_i32_e32 v97, 31, v96
	v_pk_mul_f32 v[90:91], v[90:91], v[168:169] op_sel_hi:[1,0]
	v_max_f32_e32 v88, 0, v88
	v_lshlrev_b64 v[96:97], 6, v[96:97]
	v_pk_mul_f32 v[94:95], v[94:95], v[168:169] op_sel_hi:[1,0]
	v_mul_f32_e32 v98, v88, v88
	v_max_f32_e32 v88, 0, v93
	v_max_f32_e32 v89, 0, v89
	v_max_f32_e32 v90, 0, v90
	v_lshl_add_u64 v[96:97], s[4:5], 0, v[96:97]
	v_max_f32_e32 v92, 0, v92
	v_mul_f32_e32 v88, v88, v88
	v_mul_f32_e32 v93, v89, v89
	v_max_f32_e32 v89, 0, v94
	v_mul_f32_e32 v94, v90, v90
	v_max_f32_e32 v90, 0, v95
	v_max_f32_e32 v91, 0, v91
	v_pk_mul_f32 v[80:81], v[80:81], v[168:169] op_sel_hi:[1,0]
	v_fmamk_f32 v156, v231, 0x3a800000, v149
	v_lshl_add_u64 v[96:97], v[96:97], 0, v[136:137]
	v_mul_f32_e32 v92, v92, v92
	v_mul_f32_e32 v89, v89, v89
	v_mul_f32_e32 v90, v90, v90
	v_mul_f32_e32 v91, v91, v91
	v_cvt_pk_bf16_f32 v88, v92, v88
	v_pk_mul_f32 v[84:85], v[84:85], v[168:169] op_sel_hi:[1,0]
	v_pk_mul_f32 v[82:83], v[82:83], v[168:169] op_sel_hi:[1,0]
	v_max_f32_e32 v80, 0, v80
	v_rsq_f32_e32 v156, v156
	v_cvt_pk_bf16_f32 v89, v89, v90
	v_cvt_pk_bf16_f32 v90, v98, v93
	v_cvt_pk_bf16_f32 v91, v94, v91
	global_store_dwordx4 v[96:97], v[88:91], off
	v_pk_mul_f32 v[86:87], v[86:87], v[168:169] op_sel_hi:[1,0]
	v_max_f32_e32 v84, 0, v84
	v_mul_f32_e32 v88, v80, v80
	v_max_f32_e32 v80, 0, v85
	v_max_f32_e32 v81, 0, v81
	v_max_f32_e32 v82, 0, v82
	v_mul_f32_e32 v84, v84, v84
	v_mul_f32_e32 v80, v80, v80
	v_mul_f32_e32 v85, v81, v81
	v_max_f32_e32 v81, 0, v86
	v_mul_f32_e32 v86, v82, v82
	v_max_f32_e32 v82, 0, v87
	v_mul_f32_e32 v81, v81, v81
	v_max_f32_e32 v83, 0, v83
	v_mul_f32_e32 v82, v82, v82
	v_cvt_pk_bf16_f32 v80, v84, v80
	v_add_co_u32_e32 v84, vcc, s95, v96
	v_mul_f32_e32 v83, v83, v83
	v_cvt_pk_bf16_f32 v81, v81, v82
	v_cvt_pk_bf16_f32 v82, v88, v85
	s_nop 0
	v_addc_co_u32_e32 v85, vcc, 0, v97, vcc
	v_cvt_pk_bf16_f32 v83, v86, v83
	global_store_dwordx4 v[84:85], v[80:83], off
	v_pk_mul_f32 v[72:73], v[72:73], v[156:157] op_sel_hi:[1,0]
	v_pk_mul_f32 v[76:77], v[76:77], v[156:157] op_sel_hi:[1,0]
	v_subrev_u32_e32 v80, s6, v154
	v_ashrrev_i32_e32 v81, 31, v80
	v_pk_mul_f32 v[74:75], v[74:75], v[156:157] op_sel_hi:[1,0]
	v_max_f32_e32 v72, 0, v72
	v_lshlrev_b64 v[80:81], 6, v[80:81]
	v_pk_mul_f32 v[78:79], v[78:79], v[156:157] op_sel_hi:[1,0]
	v_mul_f32_e32 v82, v72, v72
	v_max_f32_e32 v72, 0, v77
	v_max_f32_e32 v73, 0, v73
	v_max_f32_e32 v74, 0, v74
	v_lshl_add_u64 v[80:81], s[4:5], 0, v[80:81]
	v_max_f32_e32 v76, 0, v76
	v_mul_f32_e32 v72, v72, v72
	v_mul_f32_e32 v77, v73, v73
	v_max_f32_e32 v73, 0, v78
	v_mul_f32_e32 v78, v74, v74
	v_max_f32_e32 v74, 0, v79
	v_max_f32_e32 v75, 0, v75
	v_pk_mul_f32 v[64:65], v[64:65], v[156:157] op_sel_hi:[1,0]
	v_lshl_add_u64 v[80:81], v[80:81], 0, v[136:137]
	v_mul_f32_e32 v76, v76, v76
	v_mul_f32_e32 v73, v73, v73
	v_mul_f32_e32 v74, v74, v74
	v_mul_f32_e32 v75, v75, v75
	v_cvt_pk_bf16_f32 v72, v76, v72
	v_pk_mul_f32 v[68:69], v[68:69], v[156:157] op_sel_hi:[1,0]
	v_pk_mul_f32 v[66:67], v[66:67], v[156:157] op_sel_hi:[1,0]
	v_max_f32_e32 v64, 0, v64
	v_cvt_pk_bf16_f32 v73, v73, v74
	v_cvt_pk_bf16_f32 v74, v82, v77
	v_cvt_pk_bf16_f32 v75, v78, v75
	global_store_dwordx4 v[80:81], v[72:75], off
	v_pk_mul_f32 v[70:71], v[70:71], v[156:157] op_sel_hi:[1,0]
	v_max_f32_e32 v68, 0, v68
	v_mul_f32_e32 v72, v64, v64
	v_max_f32_e32 v64, 0, v69
	v_max_f32_e32 v65, 0, v65
	v_max_f32_e32 v66, 0, v66
	v_mul_f32_e32 v68, v68, v68
	v_mul_f32_e32 v64, v64, v64
	v_mul_f32_e32 v69, v65, v65
	v_max_f32_e32 v65, 0, v70
	v_mul_f32_e32 v70, v66, v66
	v_max_f32_e32 v66, 0, v71
	v_mul_f32_e32 v65, v65, v65
	v_max_f32_e32 v67, 0, v67
	v_mul_f32_e32 v66, v66, v66
	v_cvt_pk_bf16_f32 v64, v68, v64
	v_add_co_u32_e32 v68, vcc, s95, v80
	v_mul_f32_e32 v67, v67, v67
	v_cvt_pk_bf16_f32 v65, v65, v66
	v_cvt_pk_bf16_f32 v66, v72, v69
	s_nop 0
	v_addc_co_u32_e32 v69, vcc, 0, v81, vcc
	v_cvt_pk_bf16_f32 v67, v70, v67
	global_store_dwordx4 v[68:69], v[64:67], off
	v_pk_mul_f32 v[56:57], v[56:57], v[152:153] op_sel_hi:[1,0]
	v_pk_mul_f32 v[60:61], v[60:61], v[152:153] op_sel_hi:[1,0]
	v_add_u32_e32 v64, 0x80, v138
	v_ashrrev_i32_e32 v65, 31, v64
	v_pk_mul_f32 v[58:59], v[58:59], v[152:153] op_sel_hi:[1,0]
	v_max_f32_e32 v56, 0, v56
	v_lshlrev_b64 v[64:65], 6, v[64:65]
	v_pk_mul_f32 v[62:63], v[62:63], v[152:153] op_sel_hi:[1,0]
	v_mul_f32_e32 v66, v56, v56
	v_max_f32_e32 v56, 0, v61
	v_max_f32_e32 v57, 0, v57
	v_max_f32_e32 v58, 0, v58
	v_lshl_add_u64 v[64:65], s[4:5], 0, v[64:65]
	v_max_f32_e32 v60, 0, v60
	v_mul_f32_e32 v56, v56, v56
	v_mul_f32_e32 v61, v57, v57
	v_max_f32_e32 v57, 0, v62
	v_mul_f32_e32 v62, v58, v58
	v_max_f32_e32 v58, 0, v63
	v_max_f32_e32 v59, 0, v59
	v_pk_mul_f32 v[48:49], v[48:49], v[152:153] op_sel_hi:[1,0]
	v_lshl_add_u64 v[64:65], v[64:65], 0, v[136:137]
	v_mul_f32_e32 v60, v60, v60
	v_mul_f32_e32 v57, v57, v57
	v_mul_f32_e32 v58, v58, v58
	v_mul_f32_e32 v59, v59, v59
	v_cvt_pk_bf16_f32 v56, v60, v56
	v_pk_mul_f32 v[52:53], v[52:53], v[152:153] op_sel_hi:[1,0]
	v_pk_mul_f32 v[50:51], v[50:51], v[152:153] op_sel_hi:[1,0]
	v_max_f32_e32 v48, 0, v48
	v_cvt_pk_bf16_f32 v57, v57, v58
	v_cvt_pk_bf16_f32 v58, v66, v61
	v_cvt_pk_bf16_f32 v59, v62, v59
	global_store_dwordx4 v[64:65], v[56:59], off
	v_pk_mul_f32 v[54:55], v[54:55], v[152:153] op_sel_hi:[1,0]
	v_max_f32_e32 v52, 0, v52
	v_mul_f32_e32 v56, v48, v48
	v_max_f32_e32 v48, 0, v53
	v_max_f32_e32 v49, 0, v49
	v_max_f32_e32 v50, 0, v50
	v_mul_f32_e32 v52, v52, v52
	v_mul_f32_e32 v48, v48, v48
	v_mul_f32_e32 v53, v49, v49
	v_max_f32_e32 v49, 0, v54
	v_mul_f32_e32 v54, v50, v50
	v_max_f32_e32 v50, 0, v55
; __device__ __forceinline__ unsigned cvt_pk_bf16(float lo, float hi) { unsigned r; asm volatile("v_cvt_pk_bf16_f32 %0, %1, %2" : "=v"(r) : "v"(lo), "v"(hi)); return r; }
; #define PG8_BAR __builtin_amdgcn_s_barrier()
;     __device__ __forceinline__ void operator()(const f32x4 (&acc)[2][2][4][2], const Unit& u, int wr, int wc, int fr, int fq) const {
;     ...
;         for (int ai = 0; ai < 2; ++ai)
; #pragma unroll
;             for (int m = 0; m < 4; ++m) {
;                 if (ai == 1 && !whole) continue;
;                 const int row = row0 + ai * HALF + m * 16;
;                 const float rs = rsv[ai][m];
;                 float s1 = 0.f, s2 = 0.f;
;                 bf16_t* rowp = BLK ? O + ((size_t)u.pm * (ldc >> 6) + (size_t)(col0 >> 6)) * 16384 + (size_t)((col0 >> 5) & 1) * 8192 + (size_t)(row - u.pm * BM) * 32 + (col0 & 31) : O + (size_t)row * ldc + col0;
; #pragma unroll
;                 for (int bj = 0; bj < 2; ++bj) {
;                     if (bj == 1 && !whole) continue;
;                     f32x4 v0 = acc[ai][bj][m][0] * rs, v1 = acc[ai][bj][m][1] * rs;
;                     if (ACT == 1) {
; #pragma unroll
;                         for (int j = 0; j < 4; ++j) { const float a = fmaxf(v0[j], 0.f), b = fmaxf(v1[j], 0.f); v0[j] = a * a; v1[j] = b * b; }
;                     }
;                     u32x4 w; w.x = cvt_pk_bf16(v0[0], v0[1]); w.y = cvt_pk_bf16(v0[2], v0[3]); w.z = cvt_pk_bf16(v1[0], v1[1]); w.w = cvt_pk_bf16(v1[2], v1[3]);
;                     *(u32x4*)(rowp + (BLK ? bj * 2 * 16384 : bj * HALF)) = w;
; template <class Epi, class Sched, bool ALIGN_EPI = false, bool SP2 = false>
; __device__ __forceinline__ void gemm_phase(PG8_LAS unsigned char* lds, const Gemm g, const Sched& S, const Epi& E) {
;     ...
;         if (!has_next) break;
; #pragma unroll
;         for (int a = 0; a < 2; ++a)
; #pragma unroll
;             for (int b = 0; b < 2; ++b)
; #pragma unroll
;                 for (int m = 0; m < 4; ++m)
; #pragma unroll
;                     for (int n = 0; n < 2; ++n) acc[a][b][m][n] = (f32x4){0.f, 0.f, 0.f, 0.f};
;         cur = nxt; cA = nA; cB = nB; ++ui;
;         if constexpr (ALIGN_EPI) { if (wr == 1) PG8_BAR; }
	v_mul_f32_e32 v49, v49, v49
	v_max_f32_e32 v51, 0, v51
	v_mul_f32_e32 v50, v50, v50
	v_cvt_pk_bf16_f32 v48, v52, v48
	v_add_co_u32_e32 v52, vcc, s95, v64
	v_mul_f32_e32 v51, v51, v51
	v_cvt_pk_bf16_f32 v49, v49, v50
	v_cvt_pk_bf16_f32 v50, v56, v53
	s_nop 0
	v_addc_co_u32_e32 v53, vcc, 0, v65, vcc
	v_cvt_pk_bf16_f32 v51, v54, v51
	global_store_dwordx4 v[52:53], v[48:51], off
	v_pk_mul_f32 v[40:41], v[40:41], v[150:151] op_sel_hi:[1,0]
	v_pk_mul_f32 v[44:45], v[44:45], v[150:151] op_sel_hi:[1,0]
	v_add_u32_e32 v48, 0x90, v138
	v_ashrrev_i32_e32 v49, 31, v48
	v_pk_mul_f32 v[42:43], v[42:43], v[150:151] op_sel_hi:[1,0]
	v_max_f32_e32 v40, 0, v40
	v_lshlrev_b64 v[48:49], 6, v[48:49]
	v_pk_mul_f32 v[46:47], v[46:47], v[150:151] op_sel_hi:[1,0]
	v_mul_f32_e32 v50, v40, v40
	v_max_f32_e32 v40, 0, v45
	v_max_f32_e32 v41, 0, v41
	v_max_f32_e32 v42, 0, v42
	v_lshl_add_u64 v[48:49], s[4:5], 0, v[48:49]
	v_max_f32_e32 v44, 0, v44
	v_mul_f32_e32 v40, v40, v40
	v_mul_f32_e32 v45, v41, v41
	v_max_f32_e32 v41, 0, v46
	v_mul_f32_e32 v46, v42, v42
	v_max_f32_e32 v42, 0, v47
	v_max_f32_e32 v43, 0, v43
	v_pk_mul_f32 v[32:33], v[32:33], v[150:151] op_sel_hi:[1,0]
	v_lshl_add_u64 v[48:49], v[48:49], 0, v[136:137]
	v_mul_f32_e32 v44, v44, v44
	v_mul_f32_e32 v41, v41, v41
	v_mul_f32_e32 v42, v42, v42
	v_mul_f32_e32 v43, v43, v43
	v_cvt_pk_bf16_f32 v40, v44, v40
	v_pk_mul_f32 v[36:37], v[36:37], v[150:151] op_sel_hi:[1,0]
	v_pk_mul_f32 v[34:35], v[34:35], v[150:151] op_sel_hi:[1,0]
	v_max_f32_e32 v32, 0, v32
	v_cvt_pk_bf16_f32 v41, v41, v42
	v_cvt_pk_bf16_f32 v42, v50, v45
	v_cvt_pk_bf16_f32 v43, v46, v43
	global_store_dwordx4 v[48:49], v[40:43], off
	v_pk_mul_f32 v[38:39], v[38:39], v[150:151] op_sel_hi:[1,0]
	v_max_f32_e32 v36, 0, v36
	v_mul_f32_e32 v40, v32, v32
	v_max_f32_e32 v32, 0, v37
	v_max_f32_e32 v33, 0, v33
	v_max_f32_e32 v34, 0, v34
	v_mul_f32_e32 v36, v36, v36
	v_mul_f32_e32 v32, v32, v32
	v_mul_f32_e32 v37, v33, v33
	v_max_f32_e32 v33, 0, v38
	v_mul_f32_e32 v38, v34, v34
	v_max_f32_e32 v34, 0, v39
	v_mul_f32_e32 v33, v33, v33
	v_max_f32_e32 v35, 0, v35
	v_mul_f32_e32 v34, v34, v34
	v_cvt_pk_bf16_f32 v32, v36, v32
	v_add_co_u32_e32 v36, vcc, s95, v48
	v_mul_f32_e32 v35, v35, v35
	v_cvt_pk_bf16_f32 v33, v33, v34
	v_cvt_pk_bf16_f32 v34, v40, v37
	s_nop 0
	v_addc_co_u32_e32 v37, vcc, 0, v49, vcc
	v_cvt_pk_bf16_f32 v35, v38, v35
	global_store_dwordx4 v[36:37], v[32:35], off
	v_pk_mul_f32 v[24:25], v[24:25], v[148:149] op_sel_hi:[1,0]
	v_pk_mul_f32 v[28:29], v[28:29], v[148:149] op_sel_hi:[1,0]
	v_add_u32_e32 v32, 0xa0, v138
	v_ashrrev_i32_e32 v33, 31, v32
	v_pk_mul_f32 v[26:27], v[26:27], v[148:149] op_sel_hi:[1,0]
	v_max_f32_e32 v24, 0, v24
	v_lshlrev_b64 v[32:33], 6, v[32:33]
	v_pk_mul_f32 v[30:31], v[30:31], v[148:149] op_sel_hi:[1,0]
	v_mul_f32_e32 v34, v24, v24
	v_max_f32_e32 v24, 0, v29
	v_max_f32_e32 v25, 0, v25
	v_max_f32_e32 v26, 0, v26
	v_lshl_add_u64 v[32:33], s[4:5], 0, v[32:33]
	v_max_f32_e32 v28, 0, v28
	v_mul_f32_e32 v24, v24, v24
	v_mul_f32_e32 v29, v25, v25
	v_max_f32_e32 v25, 0, v30
	v_mul_f32_e32 v30, v26, v26
	v_max_f32_e32 v26, 0, v31
	v_max_f32_e32 v27, 0, v27
	v_pk_mul_f32 v[16:17], v[16:17], v[148:149] op_sel_hi:[1,0]
	v_lshl_add_u64 v[32:33], v[32:33], 0, v[136:137]
	v_mul_f32_e32 v28, v28, v28
	v_mul_f32_e32 v25, v25, v25
	v_mul_f32_e32 v26, v26, v26
	v_mul_f32_e32 v27, v27, v27
	v_cvt_pk_bf16_f32 v24, v28, v24
	v_pk_mul_f32 v[20:21], v[20:21], v[148:149] op_sel_hi:[1,0]
	v_pk_mul_f32 v[18:19], v[18:19], v[148:149] op_sel_hi:[1,0]
	v_max_f32_e32 v16, 0, v16
	v_cvt_pk_bf16_f32 v25, v25, v26
	v_cvt_pk_bf16_f32 v26, v34, v29
	v_cvt_pk_bf16_f32 v27, v30, v27
	global_store_dwordx4 v[32:33], v[24:27], off
	v_pk_mul_f32 v[22:23], v[22:23], v[148:149] op_sel_hi:[1,0]
	v_max_f32_e32 v20, 0, v20
	v_mul_f32_e32 v24, v16, v16
	v_max_f32_e32 v16, 0, v21
	v_max_f32_e32 v17, 0, v17
	v_max_f32_e32 v18, 0, v18
	v_mul_f32_e32 v20, v20, v20
	v_mul_f32_e32 v16, v16, v16
	v_mul_f32_e32 v21, v17, v17
	v_max_f32_e32 v17, 0, v22
	v_mul_f32_e32 v22, v18, v18
	v_max_f32_e32 v18, 0, v23
	v_mul_f32_e32 v17, v17, v17
	v_max_f32_e32 v19, 0, v19
	v_mul_f32_e32 v18, v18, v18
	v_cvt_pk_bf16_f32 v16, v20, v16
	v_add_co_u32_e32 v20, vcc, s95, v32
	v_mul_f32_e32 v19, v19, v19
	v_cvt_pk_bf16_f32 v17, v17, v18
	v_cvt_pk_bf16_f32 v18, v24, v21
	s_nop 0
	v_addc_co_u32_e32 v21, vcc, 0, v33, vcc
	v_cvt_pk_bf16_f32 v19, v22, v19
	global_store_dwordx4 v[20:21], v[16:19], off
	v_pk_mul_f32 v[8:9], v[8:9], v[146:147] op_sel_hi:[1,0]
	v_pk_mul_f32 v[12:13], v[12:13], v[146:147] op_sel_hi:[1,0]
	v_add_u32_e32 v16, 0xb0, v138
	v_ashrrev_i32_e32 v17, 31, v16
	v_pk_mul_f32 v[10:11], v[10:11], v[146:147] op_sel_hi:[1,0]
	v_max_f32_e32 v8, 0, v8
	v_lshlrev_b64 v[16:17], 6, v[16:17]
	v_pk_mul_f32 v[14:15], v[14:15], v[146:147] op_sel_hi:[1,0]
	v_mul_f32_e32 v18, v8, v8
	v_max_f32_e32 v8, 0, v13
	v_max_f32_e32 v9, 0, v9
	v_max_f32_e32 v10, 0, v10
	v_lshl_add_u64 v[16:17], s[4:5], 0, v[16:17]
	v_max_f32_e32 v12, 0, v12
	v_mul_f32_e32 v8, v8, v8
	v_mul_f32_e32 v13, v9, v9
	v_max_f32_e32 v9, 0, v14
	v_mul_f32_e32 v14, v10, v10
	v_max_f32_e32 v10, 0, v15
	v_max_f32_e32 v11, 0, v11
	v_pk_mul_f32 v[0:1], v[0:1], v[146:147] op_sel_hi:[1,0]
	v_lshl_add_u64 v[16:17], v[16:17], 0, v[136:137]
	v_mul_f32_e32 v12, v12, v12
	v_mul_f32_e32 v9, v9, v9
	v_mul_f32_e32 v10, v10, v10
	v_mul_f32_e32 v11, v11, v11
	v_cvt_pk_bf16_f32 v8, v12, v8
	v_pk_mul_f32 v[4:5], v[4:5], v[146:147] op_sel_hi:[1,0]
	v_pk_mul_f32 v[2:3], v[2:3], v[146:147] op_sel_hi:[1,0]
	v_max_f32_e32 v0, 0, v0
	v_cvt_pk_bf16_f32 v9, v9, v10
	v_cvt_pk_bf16_f32 v10, v18, v13
	v_cvt_pk_bf16_f32 v11, v14, v11
	global_store_dwordx4 v[16:17], v[8:11], off
	v_pk_mul_f32 v[6:7], v[6:7], v[146:147] op_sel_hi:[1,0]
	v_max_f32_e32 v4, 0, v4
	v_mul_f32_e32 v8, v0, v0
	v_max_f32_e32 v0, 0, v5
	v_max_f32_e32 v1, 0, v1
	v_max_f32_e32 v2, 0, v2
	v_mul_f32_e32 v4, v4, v4
	v_mul_f32_e32 v0, v0, v0
	v_mul_f32_e32 v5, v1, v1
	v_max_f32_e32 v1, 0, v6
	v_mul_f32_e32 v6, v2, v2
	v_max_f32_e32 v2, 0, v7
	v_mul_f32_e32 v1, v1, v1
	v_mul_f32_e32 v2, v2, v2
	v_cvt_pk_bf16_f32 v0, v4, v0
	v_add_co_u32_e32 v4, vcc, 0x10000, v16
	v_max_f32_e32 v3, 0, v3
	v_cvt_pk_bf16_f32 v1, v1, v2
	v_cvt_pk_bf16_f32 v2, v8, v5
	s_nop 0
	v_addc_co_u32_e32 v5, vcc, 0, v17, vcc
	v_mul_f32_e32 v3, v3, v3
	s_andn2_b64 vcc, exec, s[2:3]
	s_mov_b64 s[2:3], -1
	v_cvt_pk_bf16_f32 v3, v6, v3
	global_store_dwordx4 v[4:5], v[0:3], off
	s_cbranch_vccnz .LBB0_486
	s_andn2_b64 vcc, exec, s[54:55]
	s_cbranch_vccnz .LBB0_485
	s_barrier
	s_branch .LBB0_485

;     __device__ __forceinline__ void operator()(const f32x4 (&acc)[2][2][4][2], const Unit& u, int wr, int wc, int fr, int fq) const {
;     ...
; #pragma unroll
;         for (int ai = 0; ai < 2; ++ai)
; #pragma unroll
;             for (int m = 0; m < 4; ++m) rsv[ai][m] = ss[row0 + ai * HALF + m * 16];
; template <class Epi, class Sched, bool ALIGN_EPI = false, bool SP2 = false>
; __device__ __forceinline__ void gemm_phase(PG8_LAS unsigned char* lds, const Gemm g, const Sched& S, const Epi& E) {
;     ...
; #pragma unroll
;         for (int a = 0; a < 2; ++a)
; #pragma unroll
;             for (int b = 0; b < 2; ++b)
; #pragma unroll
;                 for (int m = 0; m < 4; ++m)
; #pragma unroll
;                     for (int n = 0; n < 2; ++n) acc[a][b][m][n] = (f32x4){0.f, 0.f, 0.f, 0.f};
;         cur = nxt; cA = nA; cB = nB; ++ui;
.LBB0_744:
	s_ashr_i32 s59, s58, 31
	s_lshl_b64 s[14:15], s[58:59], 19
	s_add_u32 s60, s30, s14
	s_addc_u32 s61, s31, s15
	s_and_b64 s[14:15], s[4:5], exec
	s_cselect_b32 s1, s61, s7
	s_cselect_b32 s9, s60, s6
	s_ashr_i32 s57, s56, 31
	s_lshl_b64 s[14:15], s[56:57], 19
	s_add_u32 s62, s8, s14
	s_addc_u32 s63, s78, s15
	s_and_b64 s[14:15], s[4:5], exec
	s_cselect_b32 s14, s63, s77
	s_cselect_b32 s15, s62, s76
	s_add_u32 s66, s6, 0x40080
	s_addc_u32 s67, s7, 0
	s_add_u32 s16, s76, 0x100
	v_mov_b32_e32 v0, 0
	s_addc_u32 s17, s77, 0
	s_mov_b32 s18, -2
	s_waitcnt lgkmcnt(0)
	v_mov_b32_e32 v1, v0
	v_mov_b32_e32 v2, v0
	v_mov_b32_e32 v3, v0
	v_mov_b32_e32 v4, v0
	v_mov_b32_e32 v5, v0
	v_mov_b32_e32 v6, v0
	v_mov_b32_e32 v7, v0
	v_mov_b32_e32 v16, v0
	v_mov_b32_e32 v17, v0
	v_mov_b32_e32 v18, v0
	v_mov_b32_e32 v19, v0
	v_mov_b32_e32 v20, v0
	v_mov_b32_e32 v21, v0
	v_mov_b32_e32 v22, v0
	v_mov_b32_e32 v23, v0
	v_mov_b32_e32 v32, v0
	v_mov_b32_e32 v33, v0
	v_mov_b32_e32 v34, v0
	v_mov_b32_e32 v35, v0
	v_mov_b32_e32 v36, v0
	v_mov_b32_e32 v37, v0
	v_mov_b32_e32 v38, v0
	v_mov_b32_e32 v39, v0
	v_mov_b32_e32 v48, v0
	v_mov_b32_e32 v49, v0
	v_mov_b32_e32 v50, v0
	v_mov_b32_e32 v51, v0
	v_mov_b32_e32 v52, v0
	v_mov_b32_e32 v53, v0
	v_mov_b32_e32 v54, v0
	v_mov_b32_e32 v55, v0
	v_mov_b32_e32 v8, v0
	v_mov_b32_e32 v9, v0
	v_mov_b32_e32 v10, v0
	v_mov_b32_e32 v11, v0
	v_mov_b32_e32 v12, v0
	v_mov_b32_e32 v13, v0
	v_mov_b32_e32 v14, v0
	v_mov_b32_e32 v15, v0
	v_mov_b32_e32 v24, v0
	v_mov_b32_e32 v25, v0
	v_mov_b32_e32 v26, v0
	v_mov_b32_e32 v27, v0
	v_mov_b32_e32 v28, v0
	v_mov_b32_e32 v29, v0
	v_mov_b32_e32 v30, v0
	v_mov_b32_e32 v31, v0
	v_mov_b32_e32 v40, v0
	v_mov_b32_e32 v41, v0
	v_mov_b32_e32 v42, v0
	v_mov_b32_e32 v43, v0
	v_mov_b32_e32 v44, v0
	v_mov_b32_e32 v45, v0
	v_mov_b32_e32 v46, v0
	v_mov_b32_e32 v47, v0
	v_mov_b32_e32 v56, v0
	v_mov_b32_e32 v57, v0
	v_mov_b32_e32 v58, v0
	v_mov_b32_e32 v59, v0
	v_mov_b32_e32 v60, v0
	v_mov_b32_e32 v61, v0
	v_mov_b32_e32 v62, v0
	v_mov_b32_e32 v63, v0
	v_mov_b32_e32 v64, v0
	v_mov_b32_e32 v65, v0
	v_mov_b32_e32 v66, v0
	v_mov_b32_e32 v67, v0
	v_mov_b32_e32 v68, v0
	v_mov_b32_e32 v69, v0
	v_mov_b32_e32 v70, v0
	v_mov_b32_e32 v71, v0
	v_mov_b32_e32 v80, v0
	v_mov_b32_e32 v81, v0
	v_mov_b32_e32 v82, v0
	v_mov_b32_e32 v83, v0
	v_mov_b32_e32 v84, v0
	v_mov_b32_e32 v85, v0
	v_mov_b32_e32 v86, v0
	v_mov_b32_e32 v87, v0
	v_mov_b32_e32 v96, v0
	v_mov_b32_e32 v97, v0
	v_mov_b32_e32 v98, v0
	v_mov_b32_e32 v99, v0
	v_mov_b32_e32 v100, v0
	v_mov_b32_e32 v101, v0
	v_mov_b32_e32 v102, v0
	v_mov_b32_e32 v103, v0
	v_mov_b32_e32 v112, v0
	v_mov_b32_e32 v113, v0
	v_mov_b32_e32 v114, v0
	v_mov_b32_e32 v115, v0
	v_mov_b32_e32 v116, v0
	v_mov_b32_e32 v117, v0
	v_mov_b32_e32 v118, v0
	v_mov_b32_e32 v119, v0
	v_mov_b32_e32 v72, v0
	v_mov_b32_e32 v73, v0
	v_mov_b32_e32 v74, v0
	v_mov_b32_e32 v75, v0
	v_mov_b32_e32 v76, v0
	v_mov_b32_e32 v77, v0
	v_mov_b32_e32 v78, v0
	v_mov_b32_e32 v79, v0
	v_mov_b32_e32 v88, v0
	v_mov_b32_e32 v89, v0
	v_mov_b32_e32 v90, v0
	v_mov_b32_e32 v91, v0
	v_mov_b32_e32 v92, v0
	v_mov_b32_e32 v93, v0
	v_mov_b32_e32 v94, v0
	v_mov_b32_e32 v95, v0
	v_mov_b32_e32 v104, v0
	v_mov_b32_e32 v105, v0
	v_mov_b32_e32 v106, v0
	v_mov_b32_e32 v107, v0
	v_mov_b32_e32 v108, v0
	v_mov_b32_e32 v109, v0
	v_mov_b32_e32 v110, v0
	v_mov_b32_e32 v111, v0
	v_mov_b32_e32 v120, v0
	v_mov_b32_e32 v121, v0
	v_mov_b32_e32 v122, v0
	v_mov_b32_e32 v123, v0
	v_mov_b32_e32 v124, v0
	v_mov_b32_e32 v125, v0
	v_mov_b32_e32 v126, v0
	v_mov_b32_e32 v127, v0
	v_lshl_add_u32 v236, s64, 8, v162
	v_ashrrev_i32_e32 v237, 31, v236
	v_lshl_add_u64 v[236:237], v[236:237], 2, s[38:39]
	global_load_dword v228, v[236:237], off
	global_load_dword v229, v[236:237], off offset:64
	global_load_dword v230, v[236:237], off offset:128
	global_load_dword v231, v[236:237], off offset:192
	global_load_dword v232, v[236:237], off offset:512
	global_load_dword v233, v[236:237], off offset:576
	global_load_dword v234, v[236:237], off offset:640
	global_load_dword v235, v[236:237], off offset:704

;     __device__ __forceinline__ void operator()(const f32x4 (&acc)[2][2][4][2], const Unit& u, int wr, int wc, int fr, int fq) const {
;     ...
; #pragma unroll
;         for (int ai = 0; ai < 2; ++ai)
; #pragma unroll
;             for (int m = 0; m < 4; ++m) rsv[ai][m] = ss[row0 + ai * HALF + m * 16];
; #pragma unroll
;         for (int ai = 0; ai < 2; ++ai)
; #pragma unroll
;             for (int m = 0; m < 4; ++m) rsv[ai][m] = __builtin_amdgcn_rsqf(rsv[ai][m] * (1.0f / 1024.0f) + RMS_EPS);
; #pragma unroll
;         for (int ai = 0; ai < 2; ++ai)
; #pragma unroll
;             for (int m = 0; m < 4; ++m) {
;                 if (ai == 1 && !whole) continue;
;                 const int row = row0 + ai * HALF + m * 16;
;                 const float rs = rsv[ai][m];
;                 float s1 = 0.f, s2 = 0.f;
;                 bf16_t* rowp = BLK ? O + ((size_t)u.pm * (ldc >> 6) + (size_t)(col0 >> 6)) * 16384 + (size_t)((col0 >> 5) & 1) * 8192 + (size_t)(row - u.pm * BM) * 32 + (col0 & 31) : O + (size_t)row * ldc + col0;
; #pragma unroll
;                 for (int bj = 0; bj < 2; ++bj) {
;                     if (bj == 1 && !whole) continue;
;                     f32x4 v0 = acc[ai][bj][m][0] * rs, v1 = acc[ai][bj][m][1] * rs;
;                     if (ACT == 1) {
; #pragma unroll
;                         for (int j = 0; j < 4; ++j) { const float a = fmaxf(v0[j], 0.f), b = fmaxf(v1[j], 0.f); v0[j] = a * a; v1[j] = b * b; }
;                     }
;                     u32x4 w; w.x = cvt_pk_bf16(v0[0], v0[1]); w.y = cvt_pk_bf16(v0[2], v0[3]); w.z = cvt_pk_bf16(v1[0], v1[1]); w.w = cvt_pk_bf16(v1[2], v1[3]);
;                     *(u32x4*)(rowp + (BLK ? bj * 2 * 16384 : bj * HALF)) = w;
;                     if (STATS) { s1 += (v0[0] + v0[1]) + (v0[2] + v0[3]) + (v1[0] + v1[1]) + (v1[2] + v1[3]);
;                         s2 += (v0[0] * v0[0] + v0[1] * v0[1]) + (v0[2] * v0[2] + v0[3] * v0[3]) + (v1[0] * v1[0] + v1[1] * v1[1]) + (v1[2] * v1[2] + v1[3] * v1[3]); }
;                 }
;                 if (STATS && u.pn >= stat_pn0) {
;                     s1 += __shfl_xor(s1, 16); s1 += __shfl_xor(s1, 32); s2 += __shfl_xor(s2, 16); s2 += __shfl_xor(s2, 32);
;                     if (fq == 0) { atomicAdd(st1 + row, s1); atomicAdd(st2 + row, s2); }
;                 }
.LBB0_748:
	v_lshl_add_u32 v160, s64, 8, v162
	v_ashrrev_i32_e32 v161, 31, v160
	v_or_b32_e32 v158, 16, v160
	v_lshl_add_u64 v[144:145], v[160:161], 2, s[38:39]
	v_or_b32_e32 v156, 32, v160
	v_or_b32_e32 v154, 48, v160
	v_ashrrev_i32_e32 v159, 31, v158
	v_ashrrev_i32_e32 v157, 31, v156
	v_ashrrev_i32_e32 v155, 31, v154
	v_add_u32_e32 v152, 0x80, v160
	v_add_u32_e32 v150, 0x90, v160
	v_add_u32_e32 v146, 0xa0, v160
	v_add_u32_e32 v144, 0xb0, v160
	v_lshl_add_u64 v[148:149], v[158:159], 2, s[38:39]
	v_lshl_add_u64 v[170:171], v[156:157], 2, s[38:39]
	v_lshl_add_u64 v[172:173], v[154:155], 2, s[38:39]
	v_ashrrev_i32_e32 v153, 31, v152
	v_ashrrev_i32_e32 v151, 31, v150
	v_ashrrev_i32_e32 v147, 31, v146
	v_ashrrev_i32_e32 v145, 31, v144
	v_lshl_add_u64 v[178:179], v[152:153], 2, s[38:39]
	v_lshl_add_u64 v[180:181], v[150:151], 2, s[38:39]
	v_lshl_add_u64 v[182:183], v[146:147], 2, s[38:39]
	v_lshl_add_u64 v[184:185], v[144:145], 2, s[38:39]
	s_nop 0
	v_lshl_or_b32 v148, s0, 8, v164
	v_mov_b64_e32 v[178:179], s[34:35]
	s_cmp_gt_i32 s0, 3
	v_ashrrev_i32_e32 v149, 31, v148
	v_mad_i64_i32 v[178:179], s[6:7], v160, s93, v[178:179]
	s_cselect_b64 s[6:7], -1, 0
	v_lshl_add_u64 v[182:183], v[148:149], 1, v[178:179]
	s_cmp_lt_i32 s0, 4
	v_fmamk_f32 v177, v228, 0x3a800000, v168
	v_rsq_f32_e32 v180, v177
	s_nop 0
	v_pk_mul_f32 v[126:127], v[126:127], v[180:181] op_sel_hi:[1,0]
	v_pk_mul_f32 v[124:125], v[124:125], v[180:181] op_sel_hi:[1,0]
	v_pk_mul_f32 v[122:123], v[122:123], v[180:181] op_sel_hi:[1,0]
	v_pk_mul_f32 v[120:121], v[120:121], v[180:181] op_sel_hi:[1,0]
	v_pk_mul_f32 v[118:119], v[118:119], v[180:181] op_sel_hi:[1,0]
	v_pk_mul_f32 v[116:117], v[116:117], v[180:181] op_sel_hi:[1,0]
	v_pk_mul_f32 v[114:115], v[114:115], v[180:181] op_sel_hi:[1,0]
	v_pk_mul_f32 v[112:113], v[112:113], v[180:181] op_sel_hi:[1,0]
	v_cvt_pk_bf16_f32 v178, v124, v125
	v_cvt_pk_bf16_f32 v179, v126, v127
	v_cvt_pk_bf16_f32 v180, v120, v121
	v_cvt_pk_bf16_f32 v181, v122, v123
	global_store_dwordx4 v[182:183], v[178:181], off
	s_nop 1
	v_cvt_pk_bf16_f32 v178, v116, v117
	v_cvt_pk_bf16_f32 v179, v118, v119
	v_cvt_pk_bf16_f32 v180, v112, v113
	v_cvt_pk_bf16_f32 v181, v114, v115
	global_store_dwordx4 v[182:183], v[178:181], off offset:256
	s_cbranch_scc1 .LBB0_752
	s_nop 0
	v_mul_f32_e32 v178, v125, v125
	v_mul_f32_e32 v179, v127, v127
	v_fmac_f32_e32 v178, v124, v124
	v_fmac_f32_e32 v179, v126, v126
	v_add_f32_e32 v178, v178, v179
	v_mul_f32_e32 v179, v121, v121
	v_mul_f32_e32 v177, v123, v123
	v_fmac_f32_e32 v179, v120, v120
	v_fmac_f32_e32 v177, v122, v122
	v_add_f32_e32 v178, v179, v178
	v_add_f32_e32 v177, v177, v178
	v_mul_f32_e32 v178, v115, v115
	v_mul_f32_e32 v179, v117, v117
	v_mul_f32_e32 v180, v119, v119
	v_fmac_f32_e32 v178, v114, v114
	v_fmac_f32_e32 v179, v116, v116
	v_fmac_f32_e32 v180, v118, v118
	v_add_f32_e32 v114, v114, v115
	v_add_f32_e32 v115, v116, v117
	v_add_f32_e32 v116, v118, v119
	v_add_f32_e32 v179, v179, v180
	v_mul_f32_e32 v180, v113, v113
	v_add_f32_e32 v122, v122, v123
	v_add_f32_e32 v123, v124, v125
	v_add_f32_e32 v124, v126, v127
	v_add_f32_e32 v115, v115, v116
	v_add_f32_e32 v113, v112, v113
	v_add_f32_e32 v123, v123, v124
	v_add_f32_e32 v120, v120, v121
	v_add_f32_e32 v113, v113, v115
	v_and_b32_e32 v115, 64, v169
	v_add_f32_e32 v120, v120, v123
	v_add_f32_e32 v113, v114, v113
	v_xor_b32_e32 v114, 16, v169
	v_add_u32_e32 v115, 64, v115
	v_add_f32_e32 v120, v122, v120
	v_cmp_lt_i32_e32 vcc, v114, v115
	v_add_f32_e32 v120, 0, v120
	v_add_f32_e32 v113, v113, v120
	v_cndmask_b32_e32 v114, v169, v114, vcc
	v_lshlrev_b32_e32 v114, 2, v114
	v_fmac_f32_e32 v180, v112, v112
	ds_bpermute_b32 v116, v114, v113
	v_add_f32_e32 v112, v180, v179
	v_add_f32_e32 v112, v178, v112
	v_add_f32_e32 v117, v177, v112
	ds_bpermute_b32 v114, v114, v117
	s_waitcnt lgkmcnt(1)
	v_add_f32_e32 v112, v113, v116
	v_xor_b32_e32 v113, 32, v169
	v_cmp_lt_i32_e32 vcc, v113, v115
	s_waitcnt lgkmcnt(0)
	v_add_f32_e32 v114, v117, v114
	v_cndmask_b32_e32 v113, v169, v113, vcc
	v_lshlrev_b32_e32 v115, 2, v113
	ds_bpermute_b32 v113, v115, v112
	ds_bpermute_b32 v115, v115, v114
	s_and_saveexec_b64 s[0:1], s[2:3]
	s_cbranch_execz .LBB0_751
	s_waitcnt lgkmcnt(1)
	v_add_f32_e32 v117, v112, v113
	v_lshlrev_b64 v[112:113], 2, v[160:161]
	s_waitcnt lgkmcnt(0)
	v_add_f32_e32 v116, v114, v115
	v_lshl_add_u64 v[114:115], s[46:47], 0, v[112:113]
	v_lshl_add_u64 v[112:113], s[50:51], 0, v[112:113]
	global_atomic_add_f32 v[114:115], v117, off
	global_atomic_add_f32 v[112:113], v116, off

; __device__ __forceinline__ unsigned cvt_pk_bf16(float lo, float hi) { unsigned r; asm volatile("v_cvt_pk_bf16_f32 %0, %1, %2" : "=v"(r) : "v"(lo), "v"(hi)); return r; }
;     __device__ __forceinline__ void operator()(const f32x4 (&acc)[2][2][4][2], const Unit& u, int wr, int wc, int fr, int fq) const {
;     ...
;             for (int m = 0; m < 4; ++m) {
;                 if (ai == 1 && !whole) continue;
;                 const int row = row0 + ai * HALF + m * 16;
;                 const float rs = rsv[ai][m];
;                 float s1 = 0.f, s2 = 0.f;
;                 bf16_t* rowp = BLK ? O + ((size_t)u.pm * (ldc >> 6) + (size_t)(col0 >> 6)) * 16384 + (size_t)((col0 >> 5) & 1) * 8192 + (size_t)(row - u.pm * BM) * 32 + (col0 & 31) : O + (size_t)row * ldc + col0;
; #pragma unroll
;                 for (int bj = 0; bj < 2; ++bj) {
;                     if (bj == 1 && !whole) continue;
;                     f32x4 v0 = acc[ai][bj][m][0] * rs, v1 = acc[ai][bj][m][1] * rs;
;                     if (ACT == 1) {
; #pragma unroll
;                         for (int j = 0; j < 4; ++j) { const float a = fmaxf(v0[j], 0.f), b = fmaxf(v1[j], 0.f); v0[j] = a * a; v1[j] = b * b; }
;                     }
;                     u32x4 w; w.x = cvt_pk_bf16(v0[0], v0[1]); w.y = cvt_pk_bf16(v0[2], v0[3]); w.z = cvt_pk_bf16(v1[0], v1[1]); w.w = cvt_pk_bf16(v1[2], v1[3]);
;                     *(u32x4*)(rowp + (BLK ? bj * 2 * 16384 : bj * HALF)) = w;
;                     if (STATS) { s1 += (v0[0] + v0[1]) + (v0[2] + v0[3]) + (v1[0] + v1[1]) + (v1[2] + v1[3]);
;                         s2 += (v0[0] * v0[0] + v0[1] * v0[1]) + (v0[2] * v0[2] + v0[3] * v0[3]) + (v1[0] * v1[0] + v1[1] * v1[1]) + (v1[2] * v1[2] + v1[3] * v1[3]); }
;                 }
;                 if (STATS && u.pn >= stat_pn0) {
;                     s1 += __shfl_xor(s1, 16); s1 += __shfl_xor(s1, 32); s2 += __shfl_xor(s2, 16); s2 += __shfl_xor(s2, 32);
;                     if (fq == 0) { atomicAdd(st1 + row, s1); atomicAdd(st2 + row, s2); }
;                 }
.LBB0_752:
	v_fmamk_f32 v112, v229, 0x3a800000, v168
	v_rsq_f32_e32 v116, v112
	s_waitcnt lgkmcnt(1)
	v_mov_b64_e32 v[112:113], s[34:35]
	v_mad_i64_i32 v[112:113], s[0:1], v158, s93, v[112:113]
	v_pk_mul_f32 v[110:111], v[110:111], v[116:117] op_sel_hi:[1,0]
	v_pk_mul_f32 v[108:109], v[108:109], v[116:117] op_sel_hi:[1,0]
	v_pk_mul_f32 v[106:107], v[106:107], v[116:117] op_sel_hi:[1,0]
	v_pk_mul_f32 v[104:105], v[104:105], v[116:117] op_sel_hi:[1,0]
	v_pk_mul_f32 v[102:103], v[102:103], v[116:117] op_sel_hi:[1,0]
	v_pk_mul_f32 v[100:101], v[100:101], v[116:117] op_sel_hi:[1,0]
	v_pk_mul_f32 v[98:99], v[98:99], v[116:117] op_sel_hi:[1,0]
	v_pk_mul_f32 v[96:97], v[96:97], v[116:117] op_sel_hi:[1,0]
	v_cndmask_b32_e64 v116, 0, 1, s[6:7]
	v_lshl_add_u64 v[118:119], v[148:149], 1, v[112:113]
	v_cvt_pk_bf16_f32 v112, v108, v109
	v_cvt_pk_bf16_f32 v113, v110, v111
	v_cvt_pk_bf16_f32 v114, v104, v105
	s_waitcnt lgkmcnt(0)
	v_cvt_pk_bf16_f32 v115, v106, v107
	v_cmp_ne_u32_e64 s[0:1], 1, v116
	s_andn2_b64 vcc, exec, s[6:7]
	global_store_dwordx4 v[118:119], v[112:115], off
	s_nop 1
	v_cvt_pk_bf16_f32 v112, v100, v101
	v_cvt_pk_bf16_f32 v113, v102, v103
	v_cvt_pk_bf16_f32 v114, v96, v97
	v_cvt_pk_bf16_f32 v115, v98, v99
	global_store_dwordx4 v[118:119], v[112:115], off offset:256
	s_cbranch_vccnz .LBB0_756
	s_nop 0
	v_mul_f32_e32 v113, v109, v109
	v_mul_f32_e32 v114, v111, v111
	v_fmac_f32_e32 v113, v108, v108
	v_fmac_f32_e32 v114, v110, v110
	v_add_f32_e32 v113, v113, v114
	v_mul_f32_e32 v114, v105, v105
	v_mul_f32_e32 v112, v107, v107
	v_fmac_f32_e32 v114, v104, v104
	v_fmac_f32_e32 v112, v106, v106
	v_add_f32_e32 v113, v114, v113
	v_add_f32_e32 v112, v112, v113
	v_mul_f32_e32 v113, v99, v99
	v_mul_f32_e32 v114, v101, v101
	v_mul_f32_e32 v115, v103, v103
	v_fmac_f32_e32 v113, v98, v98
	v_fmac_f32_e32 v114, v100, v100
	v_fmac_f32_e32 v115, v102, v102
	v_add_f32_e32 v98, v98, v99
	v_add_f32_e32 v99, v100, v101
	v_add_f32_e32 v100, v102, v103
	v_add_f32_e32 v114, v114, v115
	v_mul_f32_e32 v115, v97, v97
	v_add_f32_e32 v106, v106, v107
	v_add_f32_e32 v107, v108, v109
	v_add_f32_e32 v108, v110, v111
	v_add_f32_e32 v99, v99, v100
	v_add_f32_e32 v97, v96, v97
	v_add_f32_e32 v107, v107, v108
	v_add_f32_e32 v104, v104, v105
	v_add_f32_e32 v97, v97, v99
	v_and_b32_e32 v99, 64, v169
	v_add_f32_e32 v104, v104, v107
	v_add_f32_e32 v97, v98, v97
	v_xor_b32_e32 v98, 16, v169
	v_add_u32_e32 v99, 64, v99
	v_add_f32_e32 v104, v106, v104
	v_cmp_lt_i32_e32 vcc, v98, v99
	v_add_f32_e32 v104, 0, v104
	v_add_f32_e32 v97, v97, v104
	v_cndmask_b32_e32 v98, v169, v98, vcc
	v_lshlrev_b32_e32 v98, 2, v98
	v_fmac_f32_e32 v115, v96, v96
	ds_bpermute_b32 v100, v98, v97
	v_add_f32_e32 v96, v115, v114
	v_add_f32_e32 v96, v113, v96
	v_add_f32_e32 v101, v112, v96
	ds_bpermute_b32 v98, v98, v101
	s_waitcnt lgkmcnt(1)
	v_add_f32_e32 v96, v97, v100
	v_xor_b32_e32 v97, 32, v169
	v_cmp_lt_i32_e32 vcc, v97, v99
	s_waitcnt lgkmcnt(0)
	v_add_f32_e32 v98, v101, v98
	v_cndmask_b32_e32 v97, v169, v97, vcc
	v_lshlrev_b32_e32 v99, 2, v97
	ds_bpermute_b32 v97, v99, v96
	ds_bpermute_b32 v99, v99, v98
	s_and_saveexec_b64 s[6:7], s[2:3]
	s_cbranch_execz .LBB0_755
	s_waitcnt lgkmcnt(1)
	v_add_f32_e32 v101, v96, v97
	v_lshlrev_b64 v[96:97], 2, v[158:159]
	s_waitcnt lgkmcnt(0)
	v_add_f32_e32 v100, v98, v99
	v_lshl_add_u64 v[98:99], s[46:47], 0, v[96:97]
	v_lshl_add_u64 v[96:97], s[50:51], 0, v[96:97]
	global_atomic_add_f32 v[98:99], v101, off
	global_atomic_add_f32 v[96:97], v100, off

; __device__ __forceinline__ unsigned cvt_pk_bf16(float lo, float hi) { unsigned r; asm volatile("v_cvt_pk_bf16_f32 %0, %1, %2" : "=v"(r) : "v"(lo), "v"(hi)); return r; }
;     __device__ __forceinline__ void operator()(const f32x4 (&acc)[2][2][4][2], const Unit& u, int wr, int wc, int fr, int fq) const {
;     ...
;             for (int m = 0; m < 4; ++m) {
;                 if (ai == 1 && !whole) continue;
;                 const int row = row0 + ai * HALF + m * 16;
;                 const float rs = rsv[ai][m];
;                 float s1 = 0.f, s2 = 0.f;
;                 bf16_t* rowp = BLK ? O + ((size_t)u.pm * (ldc >> 6) + (size_t)(col0 >> 6)) * 16384 + (size_t)((col0 >> 5) & 1) * 8192 + (size_t)(row - u.pm * BM) * 32 + (col0 & 31) : O + (size_t)row * ldc + col0;
; #pragma unroll
;                 for (int bj = 0; bj < 2; ++bj) {
;                     if (bj == 1 && !whole) continue;
;                     f32x4 v0 = acc[ai][bj][m][0] * rs, v1 = acc[ai][bj][m][1] * rs;
;                     if (ACT == 1) {
; #pragma unroll
;                         for (int j = 0; j < 4; ++j) { const float a = fmaxf(v0[j], 0.f), b = fmaxf(v1[j], 0.f); v0[j] = a * a; v1[j] = b * b; }
;                     }
;                     u32x4 w; w.x = cvt_pk_bf16(v0[0], v0[1]); w.y = cvt_pk_bf16(v0[2], v0[3]); w.z = cvt_pk_bf16(v1[0], v1[1]); w.w = cvt_pk_bf16(v1[2], v1[3]);
;                     *(u32x4*)(rowp + (BLK ? bj * 2 * 16384 : bj * HALF)) = w;
;                     if (STATS) { s1 += (v0[0] + v0[1]) + (v0[2] + v0[3]) + (v1[0] + v1[1]) + (v1[2] + v1[3]);
;                         s2 += (v0[0] * v0[0] + v0[1] * v0[1]) + (v0[2] * v0[2] + v0[3] * v0[3]) + (v1[0] * v1[0] + v1[1] * v1[1]) + (v1[2] * v1[2] + v1[3] * v1[3]); }
;                 }
;                 if (STATS && u.pn >= stat_pn0) {
;                     s1 += __shfl_xor(s1, 16); s1 += __shfl_xor(s1, 32); s2 += __shfl_xor(s2, 16); s2 += __shfl_xor(s2, 32);
;                     if (fq == 0) { atomicAdd(st1 + row, s1); atomicAdd(st2 + row, s2); }
;                 }
.LBB0_756:
	v_fmamk_f32 v96, v230, 0x3a800000, v168
	v_rsq_f32_e32 v100, v96
	s_waitcnt lgkmcnt(1)
	v_mov_b64_e32 v[96:97], s[34:35]
	v_mad_i64_i32 v[96:97], s[6:7], v156, s93, v[96:97]
	v_lshl_add_u64 v[102:103], v[148:149], 1, v[96:97]
	v_pk_mul_f32 v[94:95], v[94:95], v[100:101] op_sel_hi:[1,0]
	v_pk_mul_f32 v[92:93], v[92:93], v[100:101] op_sel_hi:[1,0]
	v_pk_mul_f32 v[90:91], v[90:91], v[100:101] op_sel_hi:[1,0]
	v_pk_mul_f32 v[88:89], v[88:89], v[100:101] op_sel_hi:[1,0]
	v_cvt_pk_bf16_f32 v96, v92, v93
	v_cvt_pk_bf16_f32 v97, v94, v95
	v_pk_mul_f32 v[86:87], v[86:87], v[100:101] op_sel_hi:[1,0]
	v_cvt_pk_bf16_f32 v98, v88, v89
	s_waitcnt lgkmcnt(0)
	v_cvt_pk_bf16_f32 v99, v90, v91
	v_pk_mul_f32 v[84:85], v[84:85], v[100:101] op_sel_hi:[1,0]
	v_pk_mul_f32 v[82:83], v[82:83], v[100:101] op_sel_hi:[1,0]
	v_pk_mul_f32 v[80:81], v[80:81], v[100:101] op_sel_hi:[1,0]
	s_and_b64 vcc, exec, s[0:1]
	global_store_dwordx4 v[102:103], v[96:99], off
	s_nop 1
	v_cvt_pk_bf16_f32 v96, v84, v85
	v_cvt_pk_bf16_f32 v97, v86, v87
	v_cvt_pk_bf16_f32 v98, v80, v81
	v_cvt_pk_bf16_f32 v99, v82, v83
	global_store_dwordx4 v[102:103], v[96:99], off offset:256
	s_cbranch_vccnz .LBB0_760
	s_nop 0
	v_mul_f32_e32 v97, v93, v93
	v_mul_f32_e32 v98, v95, v95
	v_fmac_f32_e32 v97, v92, v92
	v_fmac_f32_e32 v98, v94, v94
	v_add_f32_e32 v97, v97, v98
	v_mul_f32_e32 v98, v89, v89
	v_mul_f32_e32 v96, v91, v91
	v_fmac_f32_e32 v98, v88, v88
	v_fmac_f32_e32 v96, v90, v90
	v_add_f32_e32 v97, v98, v97
	v_add_f32_e32 v96, v96, v97
	v_mul_f32_e32 v97, v83, v83
	v_mul_f32_e32 v98, v85, v85
	v_mul_f32_e32 v99, v87, v87
	v_fmac_f32_e32 v97, v82, v82
	v_fmac_f32_e32 v98, v84, v84
	v_fmac_f32_e32 v99, v86, v86
	v_add_f32_e32 v82, v82, v83
	v_add_f32_e32 v83, v84, v85
	v_add_f32_e32 v84, v86, v87
	v_add_f32_e32 v98, v98, v99
	v_mul_f32_e32 v99, v81, v81
	v_add_f32_e32 v90, v90, v91
	v_add_f32_e32 v91, v92, v93
	v_add_f32_e32 v92, v94, v95
	v_add_f32_e32 v83, v83, v84
	v_add_f32_e32 v81, v80, v81
	v_add_f32_e32 v91, v91, v92
	v_add_f32_e32 v88, v88, v89
	v_add_f32_e32 v81, v81, v83
	v_and_b32_e32 v83, 64, v169
	v_add_f32_e32 v88, v88, v91
	v_add_f32_e32 v81, v82, v81
	v_xor_b32_e32 v82, 16, v169
	v_add_u32_e32 v83, 64, v83
	v_add_f32_e32 v88, v90, v88
	v_cmp_lt_i32_e32 vcc, v82, v83
	v_add_f32_e32 v88, 0, v88
	v_add_f32_e32 v81, v81, v88
	v_cndmask_b32_e32 v82, v169, v82, vcc
	v_lshlrev_b32_e32 v82, 2, v82
	v_fmac_f32_e32 v99, v80, v80
	ds_bpermute_b32 v84, v82, v81
	v_add_f32_e32 v80, v99, v98
	v_add_f32_e32 v80, v97, v80
	v_add_f32_e32 v85, v96, v80
	ds_bpermute_b32 v82, v82, v85
	s_waitcnt lgkmcnt(1)
	v_add_f32_e32 v80, v81, v84
	v_xor_b32_e32 v81, 32, v169
	v_cmp_lt_i32_e32 vcc, v81, v83
	s_waitcnt lgkmcnt(0)
	v_add_f32_e32 v82, v85, v82
	v_cndmask_b32_e32 v81, v169, v81, vcc
	v_lshlrev_b32_e32 v83, 2, v81
	ds_bpermute_b32 v81, v83, v80
	ds_bpermute_b32 v83, v83, v82
	s_and_saveexec_b64 s[6:7], s[2:3]
	s_cbranch_execz .LBB0_759
	s_waitcnt lgkmcnt(1)
	v_add_f32_e32 v85, v80, v81
	v_lshlrev_b64 v[80:81], 2, v[156:157]
	s_waitcnt lgkmcnt(0)
	v_add_f32_e32 v84, v82, v83
	v_lshl_add_u64 v[82:83], s[46:47], 0, v[80:81]
	v_lshl_add_u64 v[80:81], s[50:51], 0, v[80:81]
	global_atomic_add_f32 v[82:83], v85, off
	global_atomic_add_f32 v[80:81], v84, off

; __device__ __forceinline__ unsigned cvt_pk_bf16(float lo, float hi) { unsigned r; asm volatile("v_cvt_pk_bf16_f32 %0, %1, %2" : "=v"(r) : "v"(lo), "v"(hi)); return r; }
;     __device__ __forceinline__ void operator()(const f32x4 (&acc)[2][2][4][2], const Unit& u, int wr, int wc, int fr, int fq) const {
;     ...
;             for (int m = 0; m < 4; ++m) {
;                 if (ai == 1 && !whole) continue;
;                 const int row = row0 + ai * HALF + m * 16;
;                 const float rs = rsv[ai][m];
;                 float s1 = 0.f, s2 = 0.f;
;                 bf16_t* rowp = BLK ? O + ((size_t)u.pm * (ldc >> 6) + (size_t)(col0 >> 6)) * 16384 + (size_t)((col0 >> 5) & 1) * 8192 + (size_t)(row - u.pm * BM) * 32 + (col0 & 31) : O + (size_t)row * ldc + col0;
; #pragma unroll
;                 for (int bj = 0; bj < 2; ++bj) {
;                     if (bj == 1 && !whole) continue;
;                     f32x4 v0 = acc[ai][bj][m][0] * rs, v1 = acc[ai][bj][m][1] * rs;
;                     if (ACT == 1) {
; #pragma unroll
;                         for (int j = 0; j < 4; ++j) { const float a = fmaxf(v0[j], 0.f), b = fmaxf(v1[j], 0.f); v0[j] = a * a; v1[j] = b * b; }
;                     }
;                     u32x4 w; w.x = cvt_pk_bf16(v0[0], v0[1]); w.y = cvt_pk_bf16(v0[2], v0[3]); w.z = cvt_pk_bf16(v1[0], v1[1]); w.w = cvt_pk_bf16(v1[2], v1[3]);
;                     *(u32x4*)(rowp + (BLK ? bj * 2 * 16384 : bj * HALF)) = w;
;                     if (STATS) { s1 += (v0[0] + v0[1]) + (v0[2] + v0[3]) + (v1[0] + v1[1]) + (v1[2] + v1[3]);
;                         s2 += (v0[0] * v0[0] + v0[1] * v0[1]) + (v0[2] * v0[2] + v0[3] * v0[3]) + (v1[0] * v1[0] + v1[1] * v1[1]) + (v1[2] * v1[2] + v1[3] * v1[3]); }
;                 }
;                 if (STATS && u.pn >= stat_pn0) {
;                     s1 += __shfl_xor(s1, 16); s1 += __shfl_xor(s1, 32); s2 += __shfl_xor(s2, 16); s2 += __shfl_xor(s2, 32);
;                     if (fq == 0) { atomicAdd(st1 + row, s1); atomicAdd(st2 + row, s2); }
;                 }
.LBB0_760:
	v_fmamk_f32 v80, v231, 0x3a800000, v168
	v_rsq_f32_e32 v84, v80
	s_waitcnt lgkmcnt(1)
	v_mov_b64_e32 v[80:81], s[34:35]
	v_mad_i64_i32 v[80:81], s[6:7], v154, s93, v[80:81]
	v_lshl_add_u64 v[86:87], v[148:149], 1, v[80:81]
	v_pk_mul_f32 v[78:79], v[78:79], v[84:85] op_sel_hi:[1,0]
	v_pk_mul_f32 v[76:77], v[76:77], v[84:85] op_sel_hi:[1,0]
	v_pk_mul_f32 v[74:75], v[74:75], v[84:85] op_sel_hi:[1,0]
	v_pk_mul_f32 v[72:73], v[72:73], v[84:85] op_sel_hi:[1,0]
	v_cvt_pk_bf16_f32 v80, v76, v77
	v_cvt_pk_bf16_f32 v81, v78, v79
	v_pk_mul_f32 v[70:71], v[70:71], v[84:85] op_sel_hi:[1,0]
	v_cvt_pk_bf16_f32 v82, v72, v73
	s_waitcnt lgkmcnt(0)
	v_cvt_pk_bf16_f32 v83, v74, v75
	v_pk_mul_f32 v[68:69], v[68:69], v[84:85] op_sel_hi:[1,0]
	v_pk_mul_f32 v[66:67], v[66:67], v[84:85] op_sel_hi:[1,0]
	v_pk_mul_f32 v[64:65], v[64:65], v[84:85] op_sel_hi:[1,0]
	s_and_b64 vcc, exec, s[0:1]
	global_store_dwordx4 v[86:87], v[80:83], off
	s_nop 1
	v_cvt_pk_bf16_f32 v80, v68, v69
	v_cvt_pk_bf16_f32 v81, v70, v71
	v_cvt_pk_bf16_f32 v82, v64, v65
	v_cvt_pk_bf16_f32 v83, v66, v67
	global_store_dwordx4 v[86:87], v[80:83], off offset:256
	s_cbranch_vccnz .LBB0_764
	s_nop 0
	v_mul_f32_e32 v81, v77, v77
	v_mul_f32_e32 v82, v79, v79
	v_fmac_f32_e32 v81, v76, v76
	v_fmac_f32_e32 v82, v78, v78
	v_add_f32_e32 v81, v81, v82
	v_mul_f32_e32 v82, v73, v73
	v_mul_f32_e32 v80, v75, v75
	v_fmac_f32_e32 v82, v72, v72
	v_fmac_f32_e32 v80, v74, v74
	v_add_f32_e32 v81, v82, v81
	v_add_f32_e32 v80, v80, v81
	v_mul_f32_e32 v81, v67, v67
	v_mul_f32_e32 v82, v69, v69
	v_mul_f32_e32 v83, v71, v71
	v_fmac_f32_e32 v81, v66, v66
	v_fmac_f32_e32 v82, v68, v68
	v_fmac_f32_e32 v83, v70, v70
	v_add_f32_e32 v66, v66, v67
	v_add_f32_e32 v67, v68, v69
	v_add_f32_e32 v68, v70, v71
	v_add_f32_e32 v82, v82, v83
	v_mul_f32_e32 v83, v65, v65
	v_add_f32_e32 v74, v74, v75
	v_add_f32_e32 v75, v76, v77
	v_add_f32_e32 v76, v78, v79
	v_add_f32_e32 v67, v67, v68
	v_add_f32_e32 v65, v64, v65
	v_add_f32_e32 v75, v75, v76
	v_add_f32_e32 v72, v72, v73
	v_add_f32_e32 v65, v65, v67
	v_and_b32_e32 v67, 64, v169
	v_add_f32_e32 v72, v72, v75
	v_add_f32_e32 v65, v66, v65
	v_xor_b32_e32 v66, 16, v169
	v_add_u32_e32 v67, 64, v67
	v_add_f32_e32 v72, v74, v72
	v_cmp_lt_i32_e32 vcc, v66, v67
	v_add_f32_e32 v72, 0, v72
	v_add_f32_e32 v65, v65, v72
	v_cndmask_b32_e32 v66, v169, v66, vcc
	v_lshlrev_b32_e32 v66, 2, v66
	v_fmac_f32_e32 v83, v64, v64
	ds_bpermute_b32 v68, v66, v65
	v_add_f32_e32 v64, v83, v82
	v_add_f32_e32 v64, v81, v64
	v_add_f32_e32 v69, v80, v64
	ds_bpermute_b32 v66, v66, v69
	s_waitcnt lgkmcnt(1)
	v_add_f32_e32 v64, v65, v68
	v_xor_b32_e32 v65, 32, v169
	v_cmp_lt_i32_e32 vcc, v65, v67
	s_waitcnt lgkmcnt(0)
	v_add_f32_e32 v66, v69, v66
	v_cndmask_b32_e32 v65, v169, v65, vcc
	v_lshlrev_b32_e32 v67, 2, v65
	ds_bpermute_b32 v65, v67, v64
	ds_bpermute_b32 v67, v67, v66
	s_and_saveexec_b64 s[6:7], s[2:3]
	s_cbranch_execz .LBB0_763
	s_waitcnt lgkmcnt(1)
	v_add_f32_e32 v69, v64, v65
	v_lshlrev_b64 v[64:65], 2, v[154:155]
	s_waitcnt lgkmcnt(0)
	v_add_f32_e32 v68, v66, v67
	v_lshl_add_u64 v[66:67], s[46:47], 0, v[64:65]
	v_lshl_add_u64 v[64:65], s[50:51], 0, v[64:65]
	global_atomic_add_f32 v[66:67], v69, off
	global_atomic_add_f32 v[64:65], v68, off

; __device__ __forceinline__ unsigned cvt_pk_bf16(float lo, float hi) { unsigned r; asm volatile("v_cvt_pk_bf16_f32 %0, %1, %2" : "=v"(r) : "v"(lo), "v"(hi)); return r; }
;     __device__ __forceinline__ void operator()(const f32x4 (&acc)[2][2][4][2], const Unit& u, int wr, int wc, int fr, int fq) const {
;     ...
;             for (int m = 0; m < 4; ++m) {
;                 if (ai == 1 && !whole) continue;
;                 const int row = row0 + ai * HALF + m * 16;
;                 const float rs = rsv[ai][m];
;                 float s1 = 0.f, s2 = 0.f;
;                 bf16_t* rowp = BLK ? O + ((size_t)u.pm * (ldc >> 6) + (size_t)(col0 >> 6)) * 16384 + (size_t)((col0 >> 5) & 1) * 8192 + (size_t)(row - u.pm * BM) * 32 + (col0 & 31) : O + (size_t)row * ldc + col0;
; #pragma unroll
;                 for (int bj = 0; bj < 2; ++bj) {
;                     if (bj == 1 && !whole) continue;
;                     f32x4 v0 = acc[ai][bj][m][0] * rs, v1 = acc[ai][bj][m][1] * rs;
;                     if (ACT == 1) {
; #pragma unroll
;                         for (int j = 0; j < 4; ++j) { const float a = fmaxf(v0[j], 0.f), b = fmaxf(v1[j], 0.f); v0[j] = a * a; v1[j] = b * b; }
;                     }
;                     u32x4 w; w.x = cvt_pk_bf16(v0[0], v0[1]); w.y = cvt_pk_bf16(v0[2], v0[3]); w.z = cvt_pk_bf16(v1[0], v1[1]); w.w = cvt_pk_bf16(v1[2], v1[3]);
;                     *(u32x4*)(rowp + (BLK ? bj * 2 * 16384 : bj * HALF)) = w;
;                     if (STATS) { s1 += (v0[0] + v0[1]) + (v0[2] + v0[3]) + (v1[0] + v1[1]) + (v1[2] + v1[3]);
;                         s2 += (v0[0] * v0[0] + v0[1] * v0[1]) + (v0[2] * v0[2] + v0[3] * v0[3]) + (v1[0] * v1[0] + v1[1] * v1[1]) + (v1[2] * v1[2] + v1[3] * v1[3]); }
;                 }
;                 if (STATS && u.pn >= stat_pn0) {
;                     s1 += __shfl_xor(s1, 16); s1 += __shfl_xor(s1, 32); s2 += __shfl_xor(s2, 16); s2 += __shfl_xor(s2, 32);
;                     if (fq == 0) { atomicAdd(st1 + row, s1); atomicAdd(st2 + row, s2); }
;                 }
.LBB0_764:
	v_fmamk_f32 v64, v232, 0x3a800000, v168
	v_rsq_f32_e32 v68, v64
	s_waitcnt lgkmcnt(1)
	v_mov_b64_e32 v[64:65], s[34:35]
	v_mad_i64_i32 v[64:65], s[6:7], v152, s93, v[64:65]
	v_lshl_add_u64 v[70:71], v[148:149], 1, v[64:65]
	v_pk_mul_f32 v[62:63], v[62:63], v[68:69] op_sel_hi:[1,0]
	v_pk_mul_f32 v[60:61], v[60:61], v[68:69] op_sel_hi:[1,0]
	v_pk_mul_f32 v[58:59], v[58:59], v[68:69] op_sel_hi:[1,0]
	v_pk_mul_f32 v[56:57], v[56:57], v[68:69] op_sel_hi:[1,0]
	v_cvt_pk_bf16_f32 v64, v60, v61
	v_cvt_pk_bf16_f32 v65, v62, v63
	v_pk_mul_f32 v[54:55], v[54:55], v[68:69] op_sel_hi:[1,0]
	v_cvt_pk_bf16_f32 v66, v56, v57
	s_waitcnt lgkmcnt(0)
	v_cvt_pk_bf16_f32 v67, v58, v59
	v_pk_mul_f32 v[52:53], v[52:53], v[68:69] op_sel_hi:[1,0]
	v_pk_mul_f32 v[50:51], v[50:51], v[68:69] op_sel_hi:[1,0]
	v_pk_mul_f32 v[48:49], v[48:49], v[68:69] op_sel_hi:[1,0]
	s_and_b64 vcc, exec, s[0:1]
	global_store_dwordx4 v[70:71], v[64:67], off
	s_nop 1
	v_cvt_pk_bf16_f32 v64, v52, v53
	v_cvt_pk_bf16_f32 v65, v54, v55
	v_cvt_pk_bf16_f32 v66, v48, v49
	v_cvt_pk_bf16_f32 v67, v50, v51
	global_store_dwordx4 v[70:71], v[64:67], off offset:256
	s_cbranch_vccnz .LBB0_768
	s_nop 0
	v_mul_f32_e32 v65, v61, v61
	v_mul_f32_e32 v66, v63, v63
	v_fmac_f32_e32 v65, v60, v60
	v_fmac_f32_e32 v66, v62, v62
	v_add_f32_e32 v65, v65, v66
	v_mul_f32_e32 v66, v57, v57
	v_mul_f32_e32 v64, v59, v59
	v_fmac_f32_e32 v66, v56, v56
	v_fmac_f32_e32 v64, v58, v58
	v_add_f32_e32 v65, v66, v65
	v_add_f32_e32 v64, v64, v65
	v_mul_f32_e32 v65, v51, v51
	v_mul_f32_e32 v66, v53, v53
	v_mul_f32_e32 v67, v55, v55
	v_fmac_f32_e32 v65, v50, v50
	v_fmac_f32_e32 v66, v52, v52
	v_fmac_f32_e32 v67, v54, v54
	v_add_f32_e32 v50, v50, v51
	v_add_f32_e32 v51, v52, v53
	v_add_f32_e32 v52, v54, v55
	v_add_f32_e32 v66, v66, v67
	v_mul_f32_e32 v67, v49, v49
	v_add_f32_e32 v58, v58, v59
	v_add_f32_e32 v59, v60, v61
	v_add_f32_e32 v60, v62, v63
	v_add_f32_e32 v51, v51, v52
	v_add_f32_e32 v49, v48, v49
	v_add_f32_e32 v59, v59, v60
	v_add_f32_e32 v56, v56, v57
	v_add_f32_e32 v49, v49, v51
	v_and_b32_e32 v51, 64, v169
	v_add_f32_e32 v56, v56, v59
	v_add_f32_e32 v49, v50, v49
	v_xor_b32_e32 v50, 16, v169
	v_add_u32_e32 v51, 64, v51
	v_add_f32_e32 v56, v58, v56
	v_cmp_lt_i32_e32 vcc, v50, v51
	v_add_f32_e32 v56, 0, v56
	v_add_f32_e32 v49, v49, v56
	v_cndmask_b32_e32 v50, v169, v50, vcc
	v_lshlrev_b32_e32 v50, 2, v50
	v_fmac_f32_e32 v67, v48, v48
	ds_bpermute_b32 v52, v50, v49
	v_add_f32_e32 v48, v67, v66
	v_add_f32_e32 v48, v65, v48
	v_add_f32_e32 v53, v64, v48
	ds_bpermute_b32 v50, v50, v53
	s_waitcnt lgkmcnt(1)
	v_add_f32_e32 v48, v49, v52
	v_xor_b32_e32 v49, 32, v169
	v_cmp_lt_i32_e32 vcc, v49, v51
	s_waitcnt lgkmcnt(0)
	v_add_f32_e32 v50, v53, v50
	v_cndmask_b32_e32 v49, v169, v49, vcc
	v_lshlrev_b32_e32 v51, 2, v49
	ds_bpermute_b32 v49, v51, v48
	ds_bpermute_b32 v51, v51, v50
	s_and_saveexec_b64 s[6:7], s[2:3]
	s_cbranch_execz .LBB0_767
	s_waitcnt lgkmcnt(1)
	v_add_f32_e32 v53, v48, v49
	v_lshlrev_b64 v[48:49], 2, v[152:153]
	s_waitcnt lgkmcnt(0)
	v_add_f32_e32 v52, v50, v51
	v_lshl_add_u64 v[50:51], s[46:47], 0, v[48:49]
	v_lshl_add_u64 v[48:49], s[50:51], 0, v[48:49]
	global_atomic_add_f32 v[50:51], v53, off
	global_atomic_add_f32 v[48:49], v52, off

; __device__ __forceinline__ unsigned cvt_pk_bf16(float lo, float hi) { unsigned r; asm volatile("v_cvt_pk_bf16_f32 %0, %1, %2" : "=v"(r) : "v"(lo), "v"(hi)); return r; }
;     __device__ __forceinline__ void operator()(const f32x4 (&acc)[2][2][4][2], const Unit& u, int wr, int wc, int fr, int fq) const {
;     ...
;             for (int m = 0; m < 4; ++m) {
;                 if (ai == 1 && !whole) continue;
;                 const int row = row0 + ai * HALF + m * 16;
;                 const float rs = rsv[ai][m];
;                 float s1 = 0.f, s2 = 0.f;
;                 bf16_t* rowp = BLK ? O + ((size_t)u.pm * (ldc >> 6) + (size_t)(col0 >> 6)) * 16384 + (size_t)((col0 >> 5) & 1) * 8192 + (size_t)(row - u.pm * BM) * 32 + (col0 & 31) : O + (size_t)row * ldc + col0;
; #pragma unroll
;                 for (int bj = 0; bj < 2; ++bj) {
;                     if (bj == 1 && !whole) continue;
;                     f32x4 v0 = acc[ai][bj][m][0] * rs, v1 = acc[ai][bj][m][1] * rs;
;                     if (ACT == 1) {
; #pragma unroll
;                         for (int j = 0; j < 4; ++j) { const float a = fmaxf(v0[j], 0.f), b = fmaxf(v1[j], 0.f); v0[j] = a * a; v1[j] = b * b; }
;                     }
;                     u32x4 w; w.x = cvt_pk_bf16(v0[0], v0[1]); w.y = cvt_pk_bf16(v0[2], v0[3]); w.z = cvt_pk_bf16(v1[0], v1[1]); w.w = cvt_pk_bf16(v1[2], v1[3]);
;                     *(u32x4*)(rowp + (BLK ? bj * 2 * 16384 : bj * HALF)) = w;
;                     if (STATS) { s1 += (v0[0] + v0[1]) + (v0[2] + v0[3]) + (v1[0] + v1[1]) + (v1[2] + v1[3]);
;                         s2 += (v0[0] * v0[0] + v0[1] * v0[1]) + (v0[2] * v0[2] + v0[3] * v0[3]) + (v1[0] * v1[0] + v1[1] * v1[1]) + (v1[2] * v1[2] + v1[3] * v1[3]); }
;                 }
;                 if (STATS && u.pn >= stat_pn0) {
;                     s1 += __shfl_xor(s1, 16); s1 += __shfl_xor(s1, 32); s2 += __shfl_xor(s2, 16); s2 += __shfl_xor(s2, 32);
;                     if (fq == 0) { atomicAdd(st1 + row, s1); atomicAdd(st2 + row, s2); }
;                 }
.LBB0_768:
	v_fmamk_f32 v48, v233, 0x3a800000, v168
	v_rsq_f32_e32 v52, v48
	s_waitcnt lgkmcnt(1)
	v_mov_b64_e32 v[48:49], s[34:35]
	v_mad_i64_i32 v[48:49], s[6:7], v150, s93, v[48:49]
	v_lshl_add_u64 v[54:55], v[148:149], 1, v[48:49]
	v_pk_mul_f32 v[46:47], v[46:47], v[52:53] op_sel_hi:[1,0]
	v_pk_mul_f32 v[44:45], v[44:45], v[52:53] op_sel_hi:[1,0]
	v_pk_mul_f32 v[42:43], v[42:43], v[52:53] op_sel_hi:[1,0]
	v_pk_mul_f32 v[40:41], v[40:41], v[52:53] op_sel_hi:[1,0]
	v_cvt_pk_bf16_f32 v48, v44, v45
	v_cvt_pk_bf16_f32 v49, v46, v47
	v_pk_mul_f32 v[38:39], v[38:39], v[52:53] op_sel_hi:[1,0]
	v_cvt_pk_bf16_f32 v50, v40, v41
	s_waitcnt lgkmcnt(0)
	v_cvt_pk_bf16_f32 v51, v42, v43
	v_pk_mul_f32 v[36:37], v[36:37], v[52:53] op_sel_hi:[1,0]
	v_pk_mul_f32 v[34:35], v[34:35], v[52:53] op_sel_hi:[1,0]
	v_pk_mul_f32 v[32:33], v[32:33], v[52:53] op_sel_hi:[1,0]
	s_and_b64 vcc, exec, s[0:1]
	global_store_dwordx4 v[54:55], v[48:51], off
	s_nop 1
	v_cvt_pk_bf16_f32 v48, v36, v37
	v_cvt_pk_bf16_f32 v49, v38, v39
	v_cvt_pk_bf16_f32 v50, v32, v33
	v_cvt_pk_bf16_f32 v51, v34, v35
	global_store_dwordx4 v[54:55], v[48:51], off offset:256
	s_cbranch_vccnz .LBB0_772
	s_nop 0
	v_mul_f32_e32 v49, v45, v45
	v_mul_f32_e32 v50, v47, v47
	v_fmac_f32_e32 v49, v44, v44
	v_fmac_f32_e32 v50, v46, v46
	v_add_f32_e32 v49, v49, v50
	v_mul_f32_e32 v50, v41, v41
	v_mul_f32_e32 v48, v43, v43
	v_fmac_f32_e32 v50, v40, v40
	v_fmac_f32_e32 v48, v42, v42
	v_add_f32_e32 v49, v50, v49
	v_add_f32_e32 v48, v48, v49
	v_mul_f32_e32 v49, v35, v35
	v_mul_f32_e32 v50, v37, v37
	v_mul_f32_e32 v51, v39, v39
	v_fmac_f32_e32 v49, v34, v34
	v_fmac_f32_e32 v50, v36, v36
	v_fmac_f32_e32 v51, v38, v38
	v_add_f32_e32 v34, v34, v35
	v_add_f32_e32 v35, v36, v37
	v_add_f32_e32 v36, v38, v39
	v_add_f32_e32 v50, v50, v51
	v_mul_f32_e32 v51, v33, v33
	v_add_f32_e32 v42, v42, v43
	v_add_f32_e32 v43, v44, v45
	v_add_f32_e32 v44, v46, v47
	v_add_f32_e32 v35, v35, v36
	v_add_f32_e32 v33, v32, v33
	v_add_f32_e32 v43, v43, v44
	v_add_f32_e32 v40, v40, v41
	v_add_f32_e32 v33, v33, v35
	v_and_b32_e32 v35, 64, v169
	v_add_f32_e32 v40, v40, v43
	v_add_f32_e32 v33, v34, v33
	v_xor_b32_e32 v34, 16, v169
	v_add_u32_e32 v35, 64, v35
	v_add_f32_e32 v40, v42, v40
	v_cmp_lt_i32_e32 vcc, v34, v35
	v_add_f32_e32 v40, 0, v40
	v_add_f32_e32 v33, v33, v40
	v_cndmask_b32_e32 v34, v169, v34, vcc
	v_lshlrev_b32_e32 v34, 2, v34
	v_fmac_f32_e32 v51, v32, v32
	ds_bpermute_b32 v36, v34, v33
	v_add_f32_e32 v32, v51, v50
	v_add_f32_e32 v32, v49, v32
	v_add_f32_e32 v37, v48, v32
	ds_bpermute_b32 v34, v34, v37
	s_waitcnt lgkmcnt(1)
	v_add_f32_e32 v32, v33, v36
	v_xor_b32_e32 v33, 32, v169
	v_cmp_lt_i32_e32 vcc, v33, v35
	s_waitcnt lgkmcnt(0)
	v_add_f32_e32 v34, v37, v34
	v_cndmask_b32_e32 v33, v169, v33, vcc
	v_lshlrev_b32_e32 v35, 2, v33
	ds_bpermute_b32 v33, v35, v32
	ds_bpermute_b32 v35, v35, v34
	s_and_saveexec_b64 s[6:7], s[2:3]
	s_cbranch_execz .LBB0_771
	s_waitcnt lgkmcnt(1)
	v_add_f32_e32 v37, v32, v33
	v_lshlrev_b64 v[32:33], 2, v[150:151]
	s_waitcnt lgkmcnt(0)
	v_add_f32_e32 v36, v34, v35
	v_lshl_add_u64 v[34:35], s[46:47], 0, v[32:33]
	v_lshl_add_u64 v[32:33], s[50:51], 0, v[32:33]
	global_atomic_add_f32 v[34:35], v37, off
	global_atomic_add_f32 v[32:33], v36, off

; __device__ __forceinline__ unsigned cvt_pk_bf16(float lo, float hi) { unsigned r; asm volatile("v_cvt_pk_bf16_f32 %0, %1, %2" : "=v"(r) : "v"(lo), "v"(hi)); return r; }
;     __device__ __forceinline__ void operator()(const f32x4 (&acc)[2][2][4][2], const Unit& u, int wr, int wc, int fr, int fq) const {
;     ...
;             for (int m = 0; m < 4; ++m) {
;                 if (ai == 1 && !whole) continue;
;                 const int row = row0 + ai * HALF + m * 16;
;                 const float rs = rsv[ai][m];
;                 float s1 = 0.f, s2 = 0.f;
;                 bf16_t* rowp = BLK ? O + ((size_t)u.pm * (ldc >> 6) + (size_t)(col0 >> 6)) * 16384 + (size_t)((col0 >> 5) & 1) * 8192 + (size_t)(row - u.pm * BM) * 32 + (col0 & 31) : O + (size_t)row * ldc + col0;
; #pragma unroll
;                 for (int bj = 0; bj < 2; ++bj) {
;                     if (bj == 1 && !whole) continue;
;                     f32x4 v0 = acc[ai][bj][m][0] * rs, v1 = acc[ai][bj][m][1] * rs;
;                     if (ACT == 1) {
; #pragma unroll
;                         for (int j = 0; j < 4; ++j) { const float a = fmaxf(v0[j], 0.f), b = fmaxf(v1[j], 0.f); v0[j] = a * a; v1[j] = b * b; }
;                     }
;                     u32x4 w; w.x = cvt_pk_bf16(v0[0], v0[1]); w.y = cvt_pk_bf16(v0[2], v0[3]); w.z = cvt_pk_bf16(v1[0], v1[1]); w.w = cvt_pk_bf16(v1[2], v1[3]);
;                     *(u32x4*)(rowp + (BLK ? bj * 2 * 16384 : bj * HALF)) = w;
;                     if (STATS) { s1 += (v0[0] + v0[1]) + (v0[2] + v0[3]) + (v1[0] + v1[1]) + (v1[2] + v1[3]);
;                         s2 += (v0[0] * v0[0] + v0[1] * v0[1]) + (v0[2] * v0[2] + v0[3] * v0[3]) + (v1[0] * v1[0] + v1[1] * v1[1]) + (v1[2] * v1[2] + v1[3] * v1[3]); }
;                 }
;                 if (STATS && u.pn >= stat_pn0) {
;                     s1 += __shfl_xor(s1, 16); s1 += __shfl_xor(s1, 32); s2 += __shfl_xor(s2, 16); s2 += __shfl_xor(s2, 32);
;                     if (fq == 0) { atomicAdd(st1 + row, s1); atomicAdd(st2 + row, s2); }
;                 }
.LBB0_772:
	v_fmamk_f32 v32, v234, 0x3a800000, v168
	v_rsq_f32_e32 v36, v32
	s_waitcnt lgkmcnt(1)
	v_mov_b64_e32 v[32:33], s[34:35]
	v_mad_i64_i32 v[32:33], s[6:7], v146, s93, v[32:33]
	v_lshl_add_u64 v[38:39], v[148:149], 1, v[32:33]
	v_pk_mul_f32 v[30:31], v[30:31], v[36:37] op_sel_hi:[1,0]
	v_pk_mul_f32 v[28:29], v[28:29], v[36:37] op_sel_hi:[1,0]
	v_pk_mul_f32 v[26:27], v[26:27], v[36:37] op_sel_hi:[1,0]
	v_pk_mul_f32 v[24:25], v[24:25], v[36:37] op_sel_hi:[1,0]
	v_cvt_pk_bf16_f32 v32, v28, v29
	v_cvt_pk_bf16_f32 v33, v30, v31
	v_pk_mul_f32 v[22:23], v[22:23], v[36:37] op_sel_hi:[1,0]
	v_cvt_pk_bf16_f32 v34, v24, v25
	s_waitcnt lgkmcnt(0)
	v_cvt_pk_bf16_f32 v35, v26, v27
	v_pk_mul_f32 v[20:21], v[20:21], v[36:37] op_sel_hi:[1,0]
	v_pk_mul_f32 v[18:19], v[18:19], v[36:37] op_sel_hi:[1,0]
	v_pk_mul_f32 v[16:17], v[16:17], v[36:37] op_sel_hi:[1,0]
	s_and_b64 vcc, exec, s[0:1]
	global_store_dwordx4 v[38:39], v[32:35], off
	s_nop 1
	v_cvt_pk_bf16_f32 v32, v20, v21
	v_cvt_pk_bf16_f32 v33, v22, v23
	v_cvt_pk_bf16_f32 v34, v16, v17
	v_cvt_pk_bf16_f32 v35, v18, v19
	global_store_dwordx4 v[38:39], v[32:35], off offset:256
	s_cbranch_vccnz .LBB0_776
	s_nop 0
	v_mul_f32_e32 v33, v29, v29
	v_mul_f32_e32 v34, v31, v31
	v_fmac_f32_e32 v33, v28, v28
	v_fmac_f32_e32 v34, v30, v30
	v_add_f32_e32 v33, v33, v34
	v_mul_f32_e32 v34, v25, v25
	v_mul_f32_e32 v32, v27, v27
	v_fmac_f32_e32 v34, v24, v24
	v_fmac_f32_e32 v32, v26, v26
	v_add_f32_e32 v33, v34, v33
	v_add_f32_e32 v32, v32, v33
	v_mul_f32_e32 v33, v19, v19
	v_mul_f32_e32 v34, v21, v21
	v_mul_f32_e32 v35, v23, v23
	v_fmac_f32_e32 v33, v18, v18
	v_fmac_f32_e32 v34, v20, v20
	v_fmac_f32_e32 v35, v22, v22
	v_add_f32_e32 v18, v18, v19
	v_add_f32_e32 v19, v20, v21
	v_add_f32_e32 v20, v22, v23
	v_add_f32_e32 v34, v34, v35
	v_mul_f32_e32 v35, v17, v17
	v_add_f32_e32 v26, v26, v27
	v_add_f32_e32 v27, v28, v29
	v_add_f32_e32 v28, v30, v31
	v_add_f32_e32 v19, v19, v20
	v_add_f32_e32 v17, v16, v17
	v_add_f32_e32 v27, v27, v28
	v_add_f32_e32 v24, v24, v25
	v_add_f32_e32 v17, v17, v19
	v_and_b32_e32 v19, 64, v169
	v_add_f32_e32 v24, v24, v27
	v_add_f32_e32 v17, v18, v17
	v_xor_b32_e32 v18, 16, v169
	v_add_u32_e32 v19, 64, v19
	v_add_f32_e32 v24, v26, v24
	v_cmp_lt_i32_e32 vcc, v18, v19
	v_add_f32_e32 v24, 0, v24
	v_add_f32_e32 v17, v17, v24
	v_cndmask_b32_e32 v18, v169, v18, vcc
	v_lshlrev_b32_e32 v18, 2, v18
	v_fmac_f32_e32 v35, v16, v16
	ds_bpermute_b32 v20, v18, v17
	v_add_f32_e32 v16, v35, v34
	v_add_f32_e32 v16, v33, v16
	v_add_f32_e32 v21, v32, v16
	ds_bpermute_b32 v18, v18, v21
	s_waitcnt lgkmcnt(1)
	v_add_f32_e32 v16, v17, v20
	v_xor_b32_e32 v17, 32, v169
	v_cmp_lt_i32_e32 vcc, v17, v19
	s_waitcnt lgkmcnt(0)
	v_add_f32_e32 v18, v21, v18
	v_cndmask_b32_e32 v17, v169, v17, vcc
	v_lshlrev_b32_e32 v19, 2, v17
	ds_bpermute_b32 v17, v19, v16
	ds_bpermute_b32 v19, v19, v18
	s_and_saveexec_b64 s[6:7], s[2:3]
	s_cbranch_execz .LBB0_775
	s_waitcnt lgkmcnt(1)
	v_add_f32_e32 v21, v16, v17
	v_lshlrev_b64 v[16:17], 2, v[146:147]
	s_waitcnt lgkmcnt(0)
	v_add_f32_e32 v20, v18, v19
	v_lshl_add_u64 v[18:19], s[46:47], 0, v[16:17]
	v_lshl_add_u64 v[16:17], s[50:51], 0, v[16:17]
	global_atomic_add_f32 v[18:19], v21, off
	global_atomic_add_f32 v[16:17], v20, off

; __device__ __forceinline__ unsigned cvt_pk_bf16(float lo, float hi) { unsigned r; asm volatile("v_cvt_pk_bf16_f32 %0, %1, %2" : "=v"(r) : "v"(lo), "v"(hi)); return r; }
;     __device__ __forceinline__ void operator()(const f32x4 (&acc)[2][2][4][2], const Unit& u, int wr, int wc, int fr, int fq) const {
;     ...
;             for (int m = 0; m < 4; ++m) {
;                 if (ai == 1 && !whole) continue;
;                 const int row = row0 + ai * HALF + m * 16;
;                 const float rs = rsv[ai][m];
;                 float s1 = 0.f, s2 = 0.f;
;                 bf16_t* rowp = BLK ? O + ((size_t)u.pm * (ldc >> 6) + (size_t)(col0 >> 6)) * 16384 + (size_t)((col0 >> 5) & 1) * 8192 + (size_t)(row - u.pm * BM) * 32 + (col0 & 31) : O + (size_t)row * ldc + col0;
; #pragma unroll
;                 for (int bj = 0; bj < 2; ++bj) {
;                     if (bj == 1 && !whole) continue;
;                     f32x4 v0 = acc[ai][bj][m][0] * rs, v1 = acc[ai][bj][m][1] * rs;
;                     if (ACT == 1) {
; #pragma unroll
;                         for (int j = 0; j < 4; ++j) { const float a = fmaxf(v0[j], 0.f), b = fmaxf(v1[j], 0.f); v0[j] = a * a; v1[j] = b * b; }
;                     }
;                     u32x4 w; w.x = cvt_pk_bf16(v0[0], v0[1]); w.y = cvt_pk_bf16(v0[2], v0[3]); w.z = cvt_pk_bf16(v1[0], v1[1]); w.w = cvt_pk_bf16(v1[2], v1[3]);
;                     *(u32x4*)(rowp + (BLK ? bj * 2 * 16384 : bj * HALF)) = w;
;                     if (STATS) { s1 += (v0[0] + v0[1]) + (v0[2] + v0[3]) + (v1[0] + v1[1]) + (v1[2] + v1[3]);
;                         s2 += (v0[0] * v0[0] + v0[1] * v0[1]) + (v0[2] * v0[2] + v0[3] * v0[3]) + (v1[0] * v1[0] + v1[1] * v1[1]) + (v1[2] * v1[2] + v1[3] * v1[3]); }
;                 }
;                 if (STATS && u.pn >= stat_pn0) {
;                     s1 += __shfl_xor(s1, 16); s1 += __shfl_xor(s1, 32); s2 += __shfl_xor(s2, 16); s2 += __shfl_xor(s2, 32);
;                     if (fq == 0) { atomicAdd(st1 + row, s1); atomicAdd(st2 + row, s2); }
;                 }
.LBB0_776:
	v_fmamk_f32 v16, v235, 0x3a800000, v168
	v_rsq_f32_e32 v20, v16
	s_waitcnt lgkmcnt(1)
	v_mov_b64_e32 v[16:17], s[34:35]
	v_mad_i64_i32 v[16:17], s[6:7], v144, s93, v[16:17]
	v_lshl_add_u64 v[22:23], v[148:149], 1, v[16:17]
	v_pk_mul_f32 v[14:15], v[14:15], v[20:21] op_sel_hi:[1,0]
	v_pk_mul_f32 v[12:13], v[12:13], v[20:21] op_sel_hi:[1,0]
	v_pk_mul_f32 v[10:11], v[10:11], v[20:21] op_sel_hi:[1,0]
	v_pk_mul_f32 v[8:9], v[8:9], v[20:21] op_sel_hi:[1,0]
	v_cvt_pk_bf16_f32 v16, v12, v13
	v_cvt_pk_bf16_f32 v17, v14, v15
	v_pk_mul_f32 v[6:7], v[6:7], v[20:21] op_sel_hi:[1,0]
	v_cvt_pk_bf16_f32 v18, v8, v9
	s_waitcnt lgkmcnt(0)
	v_cvt_pk_bf16_f32 v19, v10, v11
	v_pk_mul_f32 v[4:5], v[4:5], v[20:21] op_sel_hi:[1,0]
	v_pk_mul_f32 v[2:3], v[2:3], v[20:21] op_sel_hi:[1,0]
	v_pk_mul_f32 v[0:1], v[0:1], v[20:21] op_sel_hi:[1,0]
	s_and_b64 vcc, exec, s[0:1]
	global_store_dwordx4 v[22:23], v[16:19], off
	s_nop 1
	v_cvt_pk_bf16_f32 v16, v4, v5
	v_cvt_pk_bf16_f32 v17, v6, v7
	v_cvt_pk_bf16_f32 v18, v0, v1
	v_cvt_pk_bf16_f32 v19, v2, v3
	global_store_dwordx4 v[22:23], v[16:19], off offset:256
	s_cbranch_vccnz .LBB0_780
	s_nop 0
	v_mul_f32_e32 v17, v13, v13
	v_mul_f32_e32 v18, v15, v15
	v_fmac_f32_e32 v17, v12, v12
	v_fmac_f32_e32 v18, v14, v14
	v_add_f32_e32 v17, v17, v18
	v_mul_f32_e32 v18, v9, v9
	v_mul_f32_e32 v16, v11, v11
	v_fmac_f32_e32 v18, v8, v8
	v_fmac_f32_e32 v16, v10, v10
	v_add_f32_e32 v17, v18, v17
	v_add_f32_e32 v16, v16, v17
	v_mul_f32_e32 v17, v3, v3
	v_mul_f32_e32 v18, v5, v5
	v_mul_f32_e32 v19, v7, v7
	v_fmac_f32_e32 v17, v2, v2
	v_fmac_f32_e32 v18, v4, v4
	v_fmac_f32_e32 v19, v6, v6
	v_add_f32_e32 v2, v2, v3
	v_add_f32_e32 v3, v4, v5
	v_add_f32_e32 v4, v6, v7
	v_add_f32_e32 v18, v18, v19
	v_mul_f32_e32 v19, v1, v1
	v_add_f32_e32 v10, v10, v11
	v_add_f32_e32 v11, v12, v13
	v_add_f32_e32 v12, v14, v15
	v_add_f32_e32 v3, v3, v4
	v_add_f32_e32 v1, v0, v1
	v_add_f32_e32 v11, v11, v12
	v_add_f32_e32 v8, v8, v9
	v_add_f32_e32 v1, v1, v3
	v_and_b32_e32 v3, 64, v169
	v_add_f32_e32 v8, v8, v11
	v_add_f32_e32 v1, v2, v1
	v_xor_b32_e32 v2, 16, v169
	v_add_u32_e32 v3, 64, v3
	v_add_f32_e32 v8, v10, v8
	v_cmp_lt_i32_e32 vcc, v2, v3
	v_add_f32_e32 v8, 0, v8
	v_add_f32_e32 v1, v1, v8
	v_cndmask_b32_e32 v2, v169, v2, vcc
	v_lshlrev_b32_e32 v2, 2, v2
	v_fmac_f32_e32 v19, v0, v0
	ds_bpermute_b32 v4, v2, v1
	v_add_f32_e32 v0, v19, v18
	v_add_f32_e32 v0, v17, v0
	v_add_f32_e32 v5, v16, v0
	ds_bpermute_b32 v2, v2, v5
	s_waitcnt lgkmcnt(1)
	v_add_f32_e32 v0, v1, v4
	v_xor_b32_e32 v1, 32, v169
	v_cmp_lt_i32_e32 vcc, v1, v3
	s_waitcnt lgkmcnt(0)
	v_add_f32_e32 v2, v5, v2
	v_cndmask_b32_e32 v1, v169, v1, vcc
	v_lshlrev_b32_e32 v3, 2, v1
	ds_bpermute_b32 v1, v3, v0
	ds_bpermute_b32 v3, v3, v2
	s_and_saveexec_b64 s[0:1], s[2:3]
	s_cbranch_execz .LBB0_779
	s_waitcnt lgkmcnt(1)
	v_add_f32_e32 v5, v0, v1
	v_lshlrev_b64 v[0:1], 2, v[144:145]
	s_waitcnt lgkmcnt(0)
	v_add_f32_e32 v4, v2, v3
	v_lshl_add_u64 v[2:3], s[46:47], 0, v[0:1]
	v_lshl_add_u64 v[0:1], s[50:51], 0, v[0:1]
	global_atomic_add_f32 v[2:3], v5, off
	global_atomic_add_f32 v[0:1], v4, off

;     __device__ __forceinline__ void operator()(const f32x4 (&acc)[2][2][4][2], const Unit& u, int wr, int wc, int fr, int fq) const {
;     ...
;         const int row0 = u.pm * BM + wr * 64 + fr + (u.qa > 0 ? HALF : 0), col0 = u.pn * BM + wc * 32 + 8 * fq + (u.qb > 0 ? HALF : 0);
;         float rsv[2][4];
; #pragma unroll
;         for (int ai = 0; ai < 2; ++ai)
; #pragma unroll
;             for (int m = 0; m < 4; ++m) rsv[ai][m] = ss[row0 + ai * HALF + m * 16];
; template <class Epi, class Sched, bool ALIGN_EPI = false, bool SP2 = false>
; __device__ __forceinline__ void gemm_phase(PG8_LAS unsigned char* lds, const Gemm g, const Sched& S, const Epi& E) {
;     ...
;         for (int a = 0; a < 2; ++a)
; #pragma unroll
;             for (int b = 0; b < 2; ++b)
; #pragma unroll
;                 for (int m = 0; m < 4; ++m)
; #pragma unroll
;                     for (int n = 0; n < 2; ++n) acc[a][b][m][n] = (f32x4){0.f, 0.f, 0.f, 0.f};
.LBB0_1200:
	s_bfe_u32 s29, s28, 0x10001
	s_and_b64 s[6:7], s[2:3], exec
	s_cselect_b32 s83, -1, s29
	s_and_b32 s18, s18, 1
	s_and_b64 s[6:7], s[2:3], exec
	s_cselect_b32 s84, -1, s18
	s_cmpk_lt_u32 s28, 0x100
	s_cselect_b64 s[6:7], -1, 0
	s_ashr_i32 s39, s38, 31
	s_or_b64 s[42:43], s[2:3], s[6:7]
	s_lshl_b64 s[2:3], s[38:39], 19
	s_add_u32 s2, s30, s2
	s_addc_u32 s3, s31, s3
	s_cmp_gt_i32 s83, 0
	s_cselect_b32 s6, 0x40000, 0
	s_add_u32 s40, s2, s6
	s_addc_u32 s41, s3, 0
	s_and_b64 s[2:3], s[42:43], exec
	s_cselect_b32 s39, s41, s51
	s_cselect_b32 s47, s40, s50
	s_ashr_i32 s37, s36, 31
	s_lshl_b64 s[2:3], s[36:37], 19
	s_add_u32 s2, s22, s2
	s_addc_u32 s3, s23, s3
	s_cmp_gt_i32 s84, 0
	s_cselect_b32 s6, 0x40000, 0
	s_add_u32 s44, s2, s6
	s_addc_u32 s45, s3, 0
	s_and_b64 s[2:3], s[42:43], exec
	s_cselect_b32 s37, s45, s53
	s_cselect_b32 s90, s44, s52
	s_cmp_lt_i32 s86, 0
	v_mov_b32_e32 v2, v201
	v_mov_b32_e32 v3, v201
	s_cselect_b64 s[54:55], -1, 0
	v_mov_b32_e32 v0, v201
	v_mov_b32_e32 v1, v201
	v_mov_b32_e32 v88, 0
	s_cmp_gt_i32 s38, 63
	v_mov_b64_e32 v[6:7], v[2:3]
	v_mov_b64_e32 v[18:19], v[2:3]
	v_mov_b64_e32 v[22:23], v[2:3]
	v_mov_b64_e32 v[34:35], v[2:3]
	v_mov_b64_e32 v[38:39], v[2:3]
	v_mov_b64_e32 v[50:51], v[2:3]
	v_mov_b64_e32 v[54:55], v[2:3]
	v_mov_b64_e32 v[10:11], v[2:3]
	v_mov_b64_e32 v[14:15], v[2:3]
	v_mov_b64_e32 v[26:27], v[2:3]
	v_mov_b64_e32 v[30:31], v[2:3]
	v_mov_b64_e32 v[42:43], v[2:3]
	v_mov_b64_e32 v[46:47], v[2:3]
	v_mov_b64_e32 v[58:59], v[2:3]
	v_mov_b64_e32 v[62:63], v[2:3]
	v_mov_b64_e32 v[66:67], v[2:3]
	v_mov_b64_e32 v[70:71], v[2:3]
	v_mov_b64_e32 v[74:75], v[2:3]
	v_mov_b64_e32 v[78:79], v[2:3]
	v_mov_b64_e32 v[82:83], v[2:3]
	v_mov_b64_e32 v[86:87], v[2:3]
	v_mov_b64_e32 v[94:95], v[2:3]
	v_mov_b64_e32 v[98:99], v[2:3]
	s_mov_b32 s87, 0
	s_cselect_b64 s[56:57], -1, 0
	v_mov_b64_e32 v[4:5], v[0:1]
	v_mov_b64_e32 v[16:17], v[0:1]
	v_mov_b64_e32 v[20:21], v[0:1]
	v_mov_b64_e32 v[32:33], v[0:1]
	v_mov_b64_e32 v[36:37], v[0:1]
	v_mov_b64_e32 v[48:49], v[0:1]
	v_mov_b64_e32 v[52:53], v[0:1]
	v_mov_b64_e32 v[8:9], v[0:1]
	v_mov_b64_e32 v[12:13], v[0:1]
	v_mov_b64_e32 v[24:25], v[0:1]
	v_mov_b64_e32 v[28:29], v[0:1]
	v_mov_b64_e32 v[40:41], v[0:1]
	v_mov_b64_e32 v[44:45], v[0:1]
	v_mov_b64_e32 v[56:57], v[0:1]
	v_mov_b64_e32 v[60:61], v[0:1]
	v_mov_b64_e32 v[64:65], v[0:1]
	v_mov_b64_e32 v[68:69], v[0:1]
	v_mov_b64_e32 v[72:73], v[0:1]
	v_mov_b64_e32 v[76:77], v[0:1]
	v_mov_b64_e32 v[80:81], v[0:1]
	v_mov_b64_e32 v[84:85], v[0:1]
	v_mov_b64_e32 v[92:93], v[0:1]
	v_mov_b64_e32 v[96:97], v[0:1]
	v_mov_b32_e32 v89, v88
	v_mov_b32_e32 v90, v88
	v_mov_b32_e32 v91, v88
	v_mov_b32_e32 v100, v88
	v_mov_b32_e32 v101, v88
	v_mov_b32_e32 v102, v88
	v_mov_b32_e32 v103, v88
	v_mov_b32_e32 v104, v88
	v_mov_b32_e32 v105, v88
	v_mov_b32_e32 v106, v88
	v_mov_b32_e32 v107, v88
	v_mov_b32_e32 v108, v88
	v_mov_b32_e32 v109, v88
	v_mov_b32_e32 v110, v88
	v_mov_b32_e32 v111, v88
	v_mov_b32_e32 v112, v88
	v_mov_b32_e32 v113, v88
	v_mov_b32_e32 v114, v88
	v_mov_b32_e32 v115, v88
	v_mov_b32_e32 v116, v88
	v_mov_b32_e32 v117, v88
	v_mov_b32_e32 v118, v88
	v_mov_b32_e32 v119, v88
	v_mov_b32_e32 v120, v88
	v_mov_b32_e32 v121, v88
	v_mov_b32_e32 v122, v88
	v_mov_b32_e32 v123, v88
	v_mov_b32_e32 v124, v88
	v_mov_b32_e32 v125, v88
	v_mov_b32_e32 v126, v88
	v_mov_b32_e32 v127, v88
	s_lshl_b32 s6, s46, 8
	s_cmp_gt_i32 s86, 0
	s_cselect_b32 s7, 0x80, 0
	s_or_b32 s6, s7, s6
	v_add_u32_e32 v236, s6, v210
	v_ashrrev_i32_e32 v237, 31, v236
	v_lshl_add_u64 v[236:237], v[236:237], 2, s[4:5]
	global_load_dword v228, v[236:237], off
	global_load_dword v229, v[236:237], off offset:64
	global_load_dword v230, v[236:237], off offset:128
	global_load_dword v231, v[236:237], off offset:192
	global_load_dword v232, v[236:237], off offset:512
	global_load_dword v233, v[236:237], off offset:576
	global_load_dword v234, v[236:237], off offset:640
	global_load_dword v235, v[236:237], off offset:704

; __device__ __forceinline__ unsigned cvt_pk_bf16(float lo, float hi) { unsigned r; asm volatile("v_cvt_pk_bf16_f32 %0, %1, %2" : "=v"(r) : "v"(lo), "v"(hi)); return r; }
;     __device__ __forceinline__ void operator()(const f32x4 (&acc)[2][2][4][2], const Unit& u, int wr, int wc, int fr, int fq) const {
;     ...
;         for (int ai = 0; ai < 2; ++ai)
; #pragma unroll
;             for (int m = 0; m < 4; ++m) {
;                 if (ai == 1 && !whole) continue;
;                 const int row = row0 + ai * HALF + m * 16;
;                 const float rs = rsv[ai][m];
;                 float s1 = 0.f, s2 = 0.f;
;                 bf16_t* rowp = BLK ? O + ((size_t)u.pm * (ldc >> 6) + (size_t)(col0 >> 6)) * 16384 + (size_t)((col0 >> 5) & 1) * 8192 + (size_t)(row - u.pm * BM) * 32 + (col0 & 31) : O + (size_t)row * ldc + col0;
; #pragma unroll
;                 for (int bj = 0; bj < 2; ++bj) {
;                     if (bj == 1 && !whole) continue;
;                     f32x4 v0 = acc[ai][bj][m][0] * rs, v1 = acc[ai][bj][m][1] * rs;
;                     if (ACT == 1) {
; #pragma unroll
;                         for (int j = 0; j < 4; ++j) { const float a = fmaxf(v0[j], 0.f), b = fmaxf(v1[j], 0.f); v0[j] = a * a; v1[j] = b * b; }
;                     }
;                     u32x4 w; w.x = cvt_pk_bf16(v0[0], v0[1]); w.y = cvt_pk_bf16(v0[2], v0[3]); w.z = cvt_pk_bf16(v1[0], v1[1]); w.w = cvt_pk_bf16(v1[2], v1[3]);
;                     *(u32x4*)(rowp + (BLK ? bj * 2 * 16384 : bj * HALF)) = w;
.LBB0_1221:
	s_lshl_b32 s6, s46, 8
	s_cmp_gt_i32 s86, 0
	s_cselect_b32 s7, 0x80, 0
	s_or_b32 s18, s7, s6
	v_add_u32_e32 v128, s18, v210
	v_ashrrev_i32_e32 v129, 31, v128
	v_lshl_add_u64 v[130:131], v[128:129], 2, s[4:5]
	v_or_b32_e32 v140, 16, v128
	v_or_b32_e32 v138, 32, v128
	v_or_b32_e32 v136, 48, v128
	v_add_u32_e32 v134, 0x80, v128
	v_add_u32_e32 v132, 0x90, v128
	v_add_u32_e32 v130, 0xa0, v128
	v_add_u32_e32 v128, 0xb0, v128
	v_ashrrev_i32_e32 v141, 31, v140
	v_ashrrev_i32_e32 v139, 31, v138
	v_ashrrev_i32_e32 v137, 31, v136
	v_ashrrev_i32_e32 v135, 31, v134
	v_ashrrev_i32_e32 v133, 31, v132
	v_ashrrev_i32_e32 v131, 31, v130
	v_ashrrev_i32_e32 v129, 31, v128
	v_lshl_add_u64 v[142:143], v[140:141], 2, s[4:5]
	v_lshl_add_u64 v[144:145], v[138:139], 2, s[4:5]
	v_lshl_add_u64 v[146:147], v[136:137], 2, s[4:5]
	v_lshl_add_u64 v[148:149], v[134:135], 2, s[4:5]
	v_lshl_add_u64 v[150:151], v[132:133], 2, s[4:5]
	v_lshl_add_u64 v[152:153], v[130:131], 2, s[4:5]
	v_lshl_add_u64 v[154:155], v[128:129], 2, s[4:5]
	s_lshl_b32 s18, s48, 8
	s_or_b32 s18, s18, s66
	s_cmp_gt_i32 s85, 0
	v_add_u32_e32 v142, s7, v210
	s_cselect_b32 s7, 0x80, 0
	s_ashr_i32 s47, s46, 31
	s_or_b32 s7, s7, s18
	s_lshl_b64 s[28:29], s[46:47], 21
	s_ashr_i32 s46, s7, 6
	s_ashr_i32 s47, s46, 31
	s_lshl_b64 s[46:47], s[46:47], 15
	s_add_u32 s7, s34, s28
	s_addc_u32 s18, s35, s29
	s_add_u32 s7, s7, s46
	s_addc_u32 s18, s18, s47
	v_ashrrev_i32_e32 v143, 31, v142
	s_add_u32 s46, s7, s81
	v_lshlrev_b64 v[142:143], 6, v[142:143]
	s_addc_u32 s47, s18, 0
	v_lshl_add_u64 v[142:143], s[46:47], 0, v[142:143]
	v_lshl_add_u64 v[142:143], v[142:143], 0, v[200:201]
	s_and_b64 vcc, exec, s[2:3]
	v_fmamk_f32 v144, v228, 0x3a800000, v211
	v_rsq_f32_e32 v144, v144
	s_nop 0
	v_pk_mul_f32 v[126:127], v[126:127], v[144:145] op_sel_hi:[1,0]
	v_pk_mul_f32 v[124:125], v[124:125], v[144:145] op_sel_hi:[1,0]
	v_pk_mul_f32 v[122:123], v[122:123], v[144:145] op_sel_hi:[1,0]
	v_pk_mul_f32 v[120:121], v[120:121], v[144:145] op_sel_hi:[1,0]
	v_max_f32_e32 v125, 0, v125
	v_max_f32_e32 v120, 0, v120
	v_max_f32_e32 v121, 0, v121
	v_max_f32_e32 v126, 0, v126
	v_max_f32_e32 v122, 0, v122
	v_max_f32_e32 v127, 0, v127
	v_max_f32_e32 v123, 0, v123
	v_max_f32_e32 v124, 0, v124
	v_mul_f32_e32 v145, v120, v120
	v_mul_f32_e32 v120, v125, v125
	v_mul_f32_e32 v125, v121, v121
	v_mul_f32_e32 v121, v126, v126
	v_mul_f32_e32 v126, v122, v122
	v_mul_f32_e32 v122, v127, v127
	v_mul_f32_e32 v123, v123, v123
	v_mul_f32_e32 v124, v124, v124
	v_cvt_pk_bf16_f32 v120, v124, v120
	v_cvt_pk_bf16_f32 v121, v121, v122
	v_cvt_pk_bf16_f32 v122, v145, v125
	v_cvt_pk_bf16_f32 v123, v126, v123
	global_store_dwordx4 v[142:143], v[120:123], off
	s_cbranch_vccnz .LBB0_1223
	v_mov_b32_e32 v145, v144
	v_mov_b32_e32 v120, v144
	v_mov_b32_e32 v121, v144
	v_pk_mul_f32 v[92:93], v[92:93], v[144:145]
	v_pk_mul_f32 v[96:97], v[96:97], v[144:145]
	v_pk_mul_f32 v[94:95], v[94:95], v[120:121]
	v_max_f32_e32 v92, 0, v92
	v_pk_mul_f32 v[98:99], v[98:99], v[120:121]
	v_max_f32_e32 v96, 0, v96
	v_mul_f32_e32 v120, v92, v92
	v_max_f32_e32 v92, 0, v97
	v_max_f32_e32 v93, 0, v93
	v_max_f32_e32 v94, 0, v94
	v_mul_f32_e32 v96, v96, v96
	v_mul_f32_e32 v92, v92, v92
	v_mul_f32_e32 v97, v93, v93
	v_max_f32_e32 v93, 0, v98
	v_mul_f32_e32 v98, v94, v94
	v_max_f32_e32 v94, 0, v99
	v_mul_f32_e32 v93, v93, v93
	v_max_f32_e32 v95, 0, v95
	v_mul_f32_e32 v94, v94, v94
	v_cvt_pk_bf16_f32 v92, v96, v92
	v_add_co_u32_e32 v96, vcc, 0x10000, v142
	v_mul_f32_e32 v95, v95, v95
	v_cvt_pk_bf16_f32 v93, v93, v94
	v_cvt_pk_bf16_f32 v94, v120, v97
	s_nop 0
	v_addc_co_u32_e32 v97, vcc, 0, v143, vcc
	v_cvt_pk_bf16_f32 v95, v98, v95
	global_store_dwordx4 v[96:97], v[92:95], off
.LBB0_1223:
	s_nop 1
	v_fmamk_f32 v92, v229, 0x3a800000, v211
	v_rsq_f32_e32 v94, v92
	v_subrev_u32_e32 v92, s6, v140
	v_ashrrev_i32_e32 v93, 31, v92
	v_lshlrev_b64 v[92:93], 6, v[92:93]
	v_pk_mul_f32 v[96:97], v[118:119], v[94:95] op_sel_hi:[1,0]
	v_pk_mul_f32 v[98:99], v[116:117], v[94:95] op_sel_hi:[1,0]
	v_pk_mul_f32 v[112:113], v[112:113], v[94:95] op_sel_hi:[1,0]
	v_lshl_add_u64 v[92:93], s[46:47], 0, v[92:93]
	v_pk_mul_f32 v[114:115], v[114:115], v[94:95] op_sel_hi:[1,0]
	v_max_f32_e32 v95, 0, v98
	v_max_f32_e32 v98, 0, v112
	v_max_f32_e32 v99, 0, v99
	v_max_f32_e32 v96, 0, v96
	v_lshl_add_u64 v[92:93], v[92:93], 0, v[200:201]
	v_mul_f32_e32 v98, v98, v98
	v_max_f32_e32 v112, 0, v113
	v_mul_f32_e32 v99, v99, v99
	v_max_f32_e32 v113, 0, v114
	v_mul_f32_e32 v114, v96, v96
	v_max_f32_e32 v96, 0, v97
	v_max_f32_e32 v97, 0, v115
	s_and_b64 vcc, exec, s[2:3]
	v_mul_f32_e32 v95, v95, v95
	v_mul_f32_e32 v112, v112, v112
	v_mul_f32_e32 v113, v113, v113
	v_mul_f32_e32 v115, v96, v96
	v_mul_f32_e32 v116, v97, v97
	v_cvt_pk_bf16_f32 v96, v95, v99
	v_cvt_pk_bf16_f32 v97, v114, v115
	v_cvt_pk_bf16_f32 v98, v98, v112
	v_cvt_pk_bf16_f32 v99, v113, v116
	global_store_dwordx4 v[92:93], v[96:99], off
	s_cbranch_vccnz .LBB0_1225
	v_mov_b32_e32 v95, v94
	v_mov_b32_e32 v96, v94
	v_mov_b32_e32 v97, v94
	v_pk_mul_f32 v[80:81], v[80:81], v[94:95]
	v_pk_mul_f32 v[84:85], v[84:85], v[94:95]
	v_pk_mul_f32 v[82:83], v[82:83], v[96:97]
	v_max_f32_e32 v80, 0, v80
	v_pk_mul_f32 v[86:87], v[86:87], v[96:97]
	v_max_f32_e32 v84, 0, v84
	v_mul_f32_e32 v94, v80, v80
	v_max_f32_e32 v80, 0, v85
	v_max_f32_e32 v81, 0, v81
	v_max_f32_e32 v82, 0, v82
	v_mul_f32_e32 v84, v84, v84
	v_mul_f32_e32 v80, v80, v80
	v_mul_f32_e32 v85, v81, v81
	v_max_f32_e32 v81, 0, v86
	v_mul_f32_e32 v86, v82, v82
	v_max_f32_e32 v82, 0, v87
	v_mul_f32_e32 v81, v81, v81
	v_max_f32_e32 v83, 0, v83
	v_mul_f32_e32 v82, v82, v82
	v_cvt_pk_bf16_f32 v80, v84, v80
	v_add_co_u32_e32 v84, vcc, 0x10000, v92
	v_mul_f32_e32 v83, v83, v83
	v_cvt_pk_bf16_f32 v81, v81, v82
	v_cvt_pk_bf16_f32 v82, v94, v85
	s_nop 0
	v_addc_co_u32_e32 v85, vcc, 0, v93, vcc
	v_cvt_pk_bf16_f32 v83, v86, v83
	global_store_dwordx4 v[84:85], v[80:83], off
; __device__ __forceinline__ unsigned cvt_pk_bf16(float lo, float hi) { unsigned r; asm volatile("v_cvt_pk_bf16_f32 %0, %1, %2" : "=v"(r) : "v"(lo), "v"(hi)); return r; }
;     __device__ __forceinline__ void operator()(const f32x4 (&acc)[2][2][4][2], const Unit& u, int wr, int wc, int fr, int fq) const {
;     ...
;         for (int ai = 0; ai < 2; ++ai)
; #pragma unroll
;             for (int m = 0; m < 4; ++m) {
;                 if (ai == 1 && !whole) continue;
;                 const int row = row0 + ai * HALF + m * 16;
;                 const float rs = rsv[ai][m];
;                 float s1 = 0.f, s2 = 0.f;
;                 bf16_t* rowp = BLK ? O + ((size_t)u.pm * (ldc >> 6) + (size_t)(col0 >> 6)) * 16384 + (size_t)((col0 >> 5) & 1) * 8192 + (size_t)(row - u.pm * BM) * 32 + (col0 & 31) : O + (size_t)row * ldc + col0;
; #pragma unroll
;                 for (int bj = 0; bj < 2; ++bj) {
;                     if (bj == 1 && !whole) continue;
;                     f32x4 v0 = acc[ai][bj][m][0] * rs, v1 = acc[ai][bj][m][1] * rs;
;                     if (ACT == 1) {
; #pragma unroll
;                         for (int j = 0; j < 4; ++j) { const float a = fmaxf(v0[j], 0.f), b = fmaxf(v1[j], 0.f); v0[j] = a * a; v1[j] = b * b; }
;                     }
;                     u32x4 w; w.x = cvt_pk_bf16(v0[0], v0[1]); w.y = cvt_pk_bf16(v0[2], v0[3]); w.z = cvt_pk_bf16(v1[0], v1[1]); w.w = cvt_pk_bf16(v1[2], v1[3]);
;                     *(u32x4*)(rowp + (BLK ? bj * 2 * 16384 : bj * HALF)) = w;
.LBB0_1225:
	s_nop 1
	v_fmamk_f32 v80, v230, 0x3a800000, v211
	v_rsq_f32_e32 v82, v80
	v_subrev_u32_e32 v80, s6, v138
	v_ashrrev_i32_e32 v81, 31, v80
	v_lshlrev_b64 v[80:81], 6, v[80:81]
	v_pk_mul_f32 v[84:85], v[110:111], v[82:83] op_sel_hi:[1,0]
	v_pk_mul_f32 v[86:87], v[108:109], v[82:83] op_sel_hi:[1,0]
	v_pk_mul_f32 v[94:95], v[104:105], v[82:83] op_sel_hi:[1,0]
	v_lshl_add_u64 v[80:81], s[46:47], 0, v[80:81]
	v_pk_mul_f32 v[92:93], v[106:107], v[82:83] op_sel_hi:[1,0]
	v_max_f32_e32 v83, 0, v86
	v_max_f32_e32 v86, 0, v94
	v_max_f32_e32 v87, 0, v87
	v_max_f32_e32 v84, 0, v84
	v_lshl_add_u64 v[80:81], v[80:81], 0, v[200:201]
	v_mul_f32_e32 v86, v86, v86
	v_max_f32_e32 v94, 0, v95
	v_mul_f32_e32 v87, v87, v87
	v_max_f32_e32 v92, 0, v92
	v_mul_f32_e32 v95, v84, v84
	v_max_f32_e32 v84, 0, v85
	v_max_f32_e32 v85, 0, v93
	s_and_b64 vcc, exec, s[2:3]
	v_mul_f32_e32 v83, v83, v83
	v_mul_f32_e32 v94, v94, v94
	v_mul_f32_e32 v92, v92, v92
	v_mul_f32_e32 v93, v84, v84
	v_mul_f32_e32 v96, v85, v85
	v_cvt_pk_bf16_f32 v84, v83, v87
	v_cvt_pk_bf16_f32 v85, v95, v93
	v_cvt_pk_bf16_f32 v86, v86, v94
	v_cvt_pk_bf16_f32 v87, v92, v96
	global_store_dwordx4 v[80:81], v[84:87], off
	s_cbranch_vccnz .LBB0_1227
	v_mov_b32_e32 v83, v82
	v_mov_b32_e32 v84, v82
	v_mov_b32_e32 v85, v82
	v_pk_mul_f32 v[72:73], v[72:73], v[82:83]
	v_pk_mul_f32 v[76:77], v[76:77], v[82:83]
	v_pk_mul_f32 v[74:75], v[74:75], v[84:85]
	v_max_f32_e32 v72, 0, v72
	v_pk_mul_f32 v[78:79], v[78:79], v[84:85]
	v_max_f32_e32 v76, 0, v76
	v_mul_f32_e32 v82, v72, v72
	v_max_f32_e32 v72, 0, v77
	v_max_f32_e32 v73, 0, v73
	v_max_f32_e32 v74, 0, v74
	v_mul_f32_e32 v76, v76, v76
	v_mul_f32_e32 v72, v72, v72
	v_mul_f32_e32 v77, v73, v73
	v_max_f32_e32 v73, 0, v78
	v_mul_f32_e32 v78, v74, v74
	v_max_f32_e32 v74, 0, v79
	v_mul_f32_e32 v73, v73, v73
	v_max_f32_e32 v75, 0, v75
	v_mul_f32_e32 v74, v74, v74
	v_cvt_pk_bf16_f32 v72, v76, v72
	v_add_co_u32_e32 v76, vcc, 0x10000, v80
	v_mul_f32_e32 v75, v75, v75
	v_cvt_pk_bf16_f32 v73, v73, v74
	v_cvt_pk_bf16_f32 v74, v82, v77
	s_nop 0
	v_addc_co_u32_e32 v77, vcc, 0, v81, vcc
	v_cvt_pk_bf16_f32 v75, v78, v75
	global_store_dwordx4 v[76:77], v[72:75], off
.LBB0_1227:
	s_nop 1
	v_fmamk_f32 v72, v231, 0x3a800000, v211
	v_rsq_f32_e32 v76, v72
	v_subrev_u32_e32 v72, s6, v136
	v_ashrrev_i32_e32 v73, 31, v72
	v_lshlrev_b64 v[72:73], 6, v[72:73]
	v_lshl_add_u64 v[72:73], s[46:47], 0, v[72:73]
	v_pk_mul_f32 v[78:79], v[100:101], v[76:77] op_sel_hi:[1,0]
	v_pk_mul_f32 v[82:83], v[88:89], v[76:77] op_sel_hi:[1,0]
	v_lshl_add_u64 v[74:75], v[72:73], 0, v[200:201]
	v_pk_mul_f32 v[72:73], v[102:103], v[76:77] op_sel_hi:[1,0]
	v_pk_mul_f32 v[80:81], v[90:91], v[76:77] op_sel_hi:[1,0]
	v_max_f32_e32 v77, 0, v78
	v_max_f32_e32 v78, 0, v82
	v_mul_f32_e32 v82, v78, v78
	v_max_f32_e32 v78, 0, v79
	v_max_f32_e32 v79, 0, v83
	v_mul_f32_e32 v83, v79, v79
	v_max_f32_e32 v79, 0, v80
	v_mul_f32_e32 v84, v79, v79
	v_max_f32_e32 v79, 0, v81
	v_mul_f32_e32 v78, v78, v78
	v_max_f32_e32 v72, 0, v72
	v_max_f32_e32 v73, 0, v73
	v_mul_f32_e32 v81, v79, v79
	s_and_b64 vcc, exec, s[2:3]
	v_mul_f32_e32 v77, v77, v77
	v_mul_f32_e32 v72, v72, v72
	v_mul_f32_e32 v73, v73, v73
	v_cvt_pk_bf16_f32 v78, v77, v78
	v_cvt_pk_bf16_f32 v79, v72, v73
	v_cvt_pk_bf16_f32 v80, v82, v83
	v_cvt_pk_bf16_f32 v81, v84, v81
	global_store_dwordx4 v[74:75], v[78:81], off
	s_cbranch_vccz .LBB0_1229
	s_andn2_b64 vcc, exec, s[42:43]
	s_mov_b64 s[2:3], -1
	s_cbranch_vccnz .LBB0_1191
	s_branch .LBB0_1230
.LBB0_1229:
	v_mov_b32_e32 v77, v76
	v_mov_b32_e32 v84, v76
	v_mov_b32_e32 v85, v76
	v_pk_mul_f32 v[64:65], v[64:65], v[76:77]
	v_fmamk_f32 v72, v232, 0x3a800000, v211
	v_pk_mul_f32 v[68:69], v[68:69], v[76:77]
	v_pk_mul_f32 v[66:67], v[66:67], v[84:85]
	v_max_f32_e32 v64, 0, v64
	v_rsq_f32_e32 v78, v72
	v_pk_mul_f32 v[70:71], v[70:71], v[84:85]
	v_max_f32_e32 v68, 0, v68
	v_mul_f32_e32 v73, v64, v64
	v_max_f32_e32 v64, 0, v69
	v_max_f32_e32 v65, 0, v65
	v_max_f32_e32 v66, 0, v66
	v_mul_f32_e32 v68, v68, v68
	v_mul_f32_e32 v64, v64, v64
	v_mul_f32_e32 v69, v65, v65
	v_max_f32_e32 v65, 0, v70
	v_mul_f32_e32 v70, v66, v66
	v_max_f32_e32 v66, 0, v71
	v_mul_f32_e32 v65, v65, v65
	v_max_f32_e32 v67, 0, v67
	v_mul_f32_e32 v66, v66, v66
	v_cvt_pk_bf16_f32 v64, v68, v64
	v_add_co_u32_e32 v68, vcc, s65, v74
	v_mul_f32_e32 v67, v67, v67
	v_cvt_pk_bf16_f32 v65, v65, v66
	v_cvt_pk_bf16_f32 v66, v73, v69
	s_nop 0
	v_addc_co_u32_e32 v69, vcc, 0, v75, vcc
	v_cvt_pk_bf16_f32 v67, v70, v67
	global_store_dwordx4 v[68:69], v[64:67], off
	v_pk_mul_f32 v[56:57], v[56:57], v[78:79] op_sel_hi:[1,0]
	v_pk_mul_f32 v[60:61], v[60:61], v[78:79] op_sel_hi:[1,0]
	v_subrev_u32_e32 v64, s6, v134
	v_ashrrev_i32_e32 v65, 31, v64
	v_pk_mul_f32 v[58:59], v[58:59], v[78:79] op_sel_hi:[1,0]
	v_max_f32_e32 v56, 0, v56
	v_lshlrev_b64 v[64:65], 6, v[64:65]
	v_pk_mul_f32 v[62:63], v[62:63], v[78:79] op_sel_hi:[1,0]
	v_mul_f32_e32 v66, v56, v56
	v_max_f32_e32 v56, 0, v61
	v_max_f32_e32 v57, 0, v57
	v_max_f32_e32 v58, 0, v58
	v_lshl_add_u64 v[64:65], s[46:47], 0, v[64:65]
	v_max_f32_e32 v60, 0, v60
	v_mul_f32_e32 v56, v56, v56
	v_mul_f32_e32 v61, v57, v57
	v_max_f32_e32 v57, 0, v62
	v_mul_f32_e32 v62, v58, v58
	v_max_f32_e32 v58, 0, v63
	v_max_f32_e32 v59, 0, v59
	v_pk_mul_f32 v[48:49], v[48:49], v[78:79] op_sel_hi:[1,0]
	v_fmamk_f32 v72, v233, 0x3a800000, v211
	v_lshl_add_u64 v[64:65], v[64:65], 0, v[200:201]
	v_mul_f32_e32 v60, v60, v60
	v_mul_f32_e32 v57, v57, v57
	v_mul_f32_e32 v58, v58, v58
	v_mul_f32_e32 v59, v59, v59
	v_cvt_pk_bf16_f32 v56, v60, v56
	v_pk_mul_f32 v[52:53], v[52:53], v[78:79] op_sel_hi:[1,0]
	v_pk_mul_f32 v[50:51], v[50:51], v[78:79] op_sel_hi:[1,0]
; __device__ __forceinline__ unsigned cvt_pk_bf16(float lo, float hi) { unsigned r; asm volatile("v_cvt_pk_bf16_f32 %0, %1, %2" : "=v"(r) : "v"(lo), "v"(hi)); return r; }
;     __device__ __forceinline__ void operator()(const f32x4 (&acc)[2][2][4][2], const Unit& u, int wr, int wc, int fr, int fq) const {
;     ...
;             for (int m = 0; m < 4; ++m) rsv[ai][m] = __builtin_amdgcn_rsqf(rsv[ai][m] * (1.0f / 1024.0f) + RMS_EPS);
; #pragma unroll
;         for (int ai = 0; ai < 2; ++ai)
; #pragma unroll
;             for (int m = 0; m < 4; ++m) {
;                 if (ai == 1 && !whole) continue;
;                 const int row = row0 + ai * HALF + m * 16;
;                 const float rs = rsv[ai][m];
;                 float s1 = 0.f, s2 = 0.f;
;                 bf16_t* rowp = BLK ? O + ((size_t)u.pm * (ldc >> 6) + (size_t)(col0 >> 6)) * 16384 + (size_t)((col0 >> 5) & 1) * 8192 + (size_t)(row - u.pm * BM) * 32 + (col0 & 31) : O + (size_t)row * ldc + col0;
; #pragma unroll
;                 for (int bj = 0; bj < 2; ++bj) {
;                     if (bj == 1 && !whole) continue;
;                     f32x4 v0 = acc[ai][bj][m][0] * rs, v1 = acc[ai][bj][m][1] * rs;
;                     if (ACT == 1) {
; #pragma unroll
;                         for (int j = 0; j < 4; ++j) { const float a = fmaxf(v0[j], 0.f), b = fmaxf(v1[j], 0.f); v0[j] = a * a; v1[j] = b * b; }
;                     }
;                     u32x4 w; w.x = cvt_pk_bf16(v0[0], v0[1]); w.y = cvt_pk_bf16(v0[2], v0[3]); w.z = cvt_pk_bf16(v1[0], v1[1]); w.w = cvt_pk_bf16(v1[2], v1[3]);
;                     *(u32x4*)(rowp + (BLK ? bj * 2 * 16384 : bj * HALF)) = w;
	v_max_f32_e32 v48, 0, v48
	v_rsq_f32_e32 v80, v72
	v_cvt_pk_bf16_f32 v57, v57, v58
	v_cvt_pk_bf16_f32 v58, v66, v61
	v_cvt_pk_bf16_f32 v59, v62, v59
	global_store_dwordx4 v[64:65], v[56:59], off
	v_pk_mul_f32 v[54:55], v[54:55], v[78:79] op_sel_hi:[1,0]
	v_max_f32_e32 v52, 0, v52
	v_mul_f32_e32 v56, v48, v48
	v_max_f32_e32 v48, 0, v53
	v_max_f32_e32 v49, 0, v49
	v_max_f32_e32 v50, 0, v50
	v_mul_f32_e32 v52, v52, v52
	v_mul_f32_e32 v48, v48, v48
	v_mul_f32_e32 v53, v49, v49
	v_max_f32_e32 v49, 0, v54
	v_mul_f32_e32 v54, v50, v50
	v_max_f32_e32 v50, 0, v55
	v_mul_f32_e32 v49, v49, v49
	v_max_f32_e32 v51, 0, v51
	v_mul_f32_e32 v50, v50, v50
	v_cvt_pk_bf16_f32 v48, v52, v48
	v_add_co_u32_e32 v52, vcc, s65, v64
	v_mul_f32_e32 v51, v51, v51
	v_cvt_pk_bf16_f32 v49, v49, v50
	v_cvt_pk_bf16_f32 v50, v56, v53
	s_nop 0
	v_addc_co_u32_e32 v53, vcc, 0, v65, vcc
	v_cvt_pk_bf16_f32 v51, v54, v51
	global_store_dwordx4 v[52:53], v[48:51], off
	v_pk_mul_f32 v[40:41], v[40:41], v[80:81] op_sel_hi:[1,0]
	v_pk_mul_f32 v[44:45], v[44:45], v[80:81] op_sel_hi:[1,0]
	v_subrev_u32_e32 v48, s6, v132
	v_ashrrev_i32_e32 v49, 31, v48
	v_pk_mul_f32 v[42:43], v[42:43], v[80:81] op_sel_hi:[1,0]
	v_max_f32_e32 v40, 0, v40
	v_lshlrev_b64 v[48:49], 6, v[48:49]
	v_pk_mul_f32 v[46:47], v[46:47], v[80:81] op_sel_hi:[1,0]
	v_mul_f32_e32 v50, v40, v40
	v_max_f32_e32 v40, 0, v45
	v_max_f32_e32 v41, 0, v41
	v_max_f32_e32 v42, 0, v42
	v_lshl_add_u64 v[48:49], s[46:47], 0, v[48:49]
	v_max_f32_e32 v44, 0, v44
	v_mul_f32_e32 v40, v40, v40
	v_mul_f32_e32 v45, v41, v41
	v_max_f32_e32 v41, 0, v46
	v_mul_f32_e32 v46, v42, v42
	v_max_f32_e32 v42, 0, v47
	v_max_f32_e32 v43, 0, v43
	v_pk_mul_f32 v[32:33], v[32:33], v[80:81] op_sel_hi:[1,0]
	v_fmamk_f32 v72, v234, 0x3a800000, v211
	v_lshl_add_u64 v[48:49], v[48:49], 0, v[200:201]
	v_mul_f32_e32 v44, v44, v44
	v_mul_f32_e32 v41, v41, v41
	v_mul_f32_e32 v42, v42, v42
	v_mul_f32_e32 v43, v43, v43
	v_cvt_pk_bf16_f32 v40, v44, v40
	v_pk_mul_f32 v[36:37], v[36:37], v[80:81] op_sel_hi:[1,0]
	v_pk_mul_f32 v[34:35], v[34:35], v[80:81] op_sel_hi:[1,0]
	v_max_f32_e32 v32, 0, v32
	v_rsq_f32_e32 v82, v72
	v_cvt_pk_bf16_f32 v41, v41, v42
	v_cvt_pk_bf16_f32 v42, v50, v45
	v_cvt_pk_bf16_f32 v43, v46, v43
	global_store_dwordx4 v[48:49], v[40:43], off
	v_pk_mul_f32 v[38:39], v[38:39], v[80:81] op_sel_hi:[1,0]
	v_max_f32_e32 v36, 0, v36
	v_mul_f32_e32 v40, v32, v32
	v_max_f32_e32 v32, 0, v37
	v_max_f32_e32 v33, 0, v33
	v_max_f32_e32 v34, 0, v34
	v_mul_f32_e32 v36, v36, v36
	v_mul_f32_e32 v32, v32, v32
	v_mul_f32_e32 v37, v33, v33
	v_max_f32_e32 v33, 0, v38
	v_mul_f32_e32 v38, v34, v34
	v_max_f32_e32 v34, 0, v39
	v_mul_f32_e32 v33, v33, v33
	v_max_f32_e32 v35, 0, v35
	v_mul_f32_e32 v34, v34, v34
	v_cvt_pk_bf16_f32 v32, v36, v32
	v_add_co_u32_e32 v36, vcc, s65, v48
	v_mul_f32_e32 v35, v35, v35
	v_cvt_pk_bf16_f32 v33, v33, v34
	v_cvt_pk_bf16_f32 v34, v40, v37
	s_nop 0
	v_addc_co_u32_e32 v37, vcc, 0, v49, vcc
	v_cvt_pk_bf16_f32 v35, v38, v35
	global_store_dwordx4 v[36:37], v[32:35], off
	v_pk_mul_f32 v[24:25], v[24:25], v[82:83] op_sel_hi:[1,0]
	v_pk_mul_f32 v[28:29], v[28:29], v[82:83] op_sel_hi:[1,0]
	v_subrev_u32_e32 v32, s6, v130
	v_ashrrev_i32_e32 v33, 31, v32
	v_pk_mul_f32 v[26:27], v[26:27], v[82:83] op_sel_hi:[1,0]
	v_max_f32_e32 v24, 0, v24
	v_lshlrev_b64 v[32:33], 6, v[32:33]
	v_pk_mul_f32 v[30:31], v[30:31], v[82:83] op_sel_hi:[1,0]
	v_mul_f32_e32 v34, v24, v24
	v_max_f32_e32 v24, 0, v29
	v_max_f32_e32 v25, 0, v25
	v_max_f32_e32 v26, 0, v26
	v_lshl_add_u64 v[32:33], s[46:47], 0, v[32:33]
; __device__ __forceinline__ unsigned cvt_pk_bf16(float lo, float hi) { unsigned r; asm volatile("v_cvt_pk_bf16_f32 %0, %1, %2" : "=v"(r) : "v"(lo), "v"(hi)); return r; }
;     __device__ __forceinline__ void operator()(const f32x4 (&acc)[2][2][4][2], const Unit& u, int wr, int wc, int fr, int fq) const {
;     ...
;             for (int m = 0; m < 4; ++m) rsv[ai][m] = __builtin_amdgcn_rsqf(rsv[ai][m] * (1.0f / 1024.0f) + RMS_EPS);
; #pragma unroll
;         for (int ai = 0; ai < 2; ++ai)
; #pragma unroll
;             for (int m = 0; m < 4; ++m) {
;                 if (ai == 1 && !whole) continue;
;                 const int row = row0 + ai * HALF + m * 16;
;                 const float rs = rsv[ai][m];
;                 float s1 = 0.f, s2 = 0.f;
;                 bf16_t* rowp = BLK ? O + ((size_t)u.pm * (ldc >> 6) + (size_t)(col0 >> 6)) * 16384 + (size_t)((col0 >> 5) & 1) * 8192 + (size_t)(row - u.pm * BM) * 32 + (col0 & 31) : O + (size_t)row * ldc + col0;
; #pragma unroll
;                 for (int bj = 0; bj < 2; ++bj) {
;                     if (bj == 1 && !whole) continue;
;                     f32x4 v0 = acc[ai][bj][m][0] * rs, v1 = acc[ai][bj][m][1] * rs;
;                     if (ACT == 1) {
; #pragma unroll
;                         for (int j = 0; j < 4; ++j) { const float a = fmaxf(v0[j], 0.f), b = fmaxf(v1[j], 0.f); v0[j] = a * a; v1[j] = b * b; }
;                     }
;                     u32x4 w; w.x = cvt_pk_bf16(v0[0], v0[1]); w.y = cvt_pk_bf16(v0[2], v0[3]); w.z = cvt_pk_bf16(v1[0], v1[1]); w.w = cvt_pk_bf16(v1[2], v1[3]);
;                     *(u32x4*)(rowp + (BLK ? bj * 2 * 16384 : bj * HALF)) = w;
	v_max_f32_e32 v28, 0, v28
	v_mul_f32_e32 v24, v24, v24
	v_mul_f32_e32 v29, v25, v25
	v_max_f32_e32 v25, 0, v30
	v_mul_f32_e32 v30, v26, v26
	v_max_f32_e32 v26, 0, v31
	v_max_f32_e32 v27, 0, v27
	v_pk_mul_f32 v[16:17], v[16:17], v[82:83] op_sel_hi:[1,0]
	v_fmamk_f32 v72, v235, 0x3a800000, v211
	v_lshl_add_u64 v[32:33], v[32:33], 0, v[200:201]
	v_mul_f32_e32 v28, v28, v28
	v_mul_f32_e32 v25, v25, v25
	v_mul_f32_e32 v26, v26, v26
	v_mul_f32_e32 v27, v27, v27
	v_cvt_pk_bf16_f32 v24, v28, v24
	v_pk_mul_f32 v[20:21], v[20:21], v[82:83] op_sel_hi:[1,0]
	v_pk_mul_f32 v[18:19], v[18:19], v[82:83] op_sel_hi:[1,0]
	v_max_f32_e32 v16, 0, v16
	v_rsq_f32_e32 v72, v72
	v_cvt_pk_bf16_f32 v25, v25, v26
	v_cvt_pk_bf16_f32 v26, v34, v29
	v_cvt_pk_bf16_f32 v27, v30, v27
	global_store_dwordx4 v[32:33], v[24:27], off
	v_pk_mul_f32 v[22:23], v[22:23], v[82:83] op_sel_hi:[1,0]
	v_max_f32_e32 v20, 0, v20
	v_mul_f32_e32 v24, v16, v16
	v_max_f32_e32 v16, 0, v21
	v_max_f32_e32 v17, 0, v17
	v_max_f32_e32 v18, 0, v18
	v_mul_f32_e32 v20, v20, v20
	v_mul_f32_e32 v16, v16, v16
	v_mul_f32_e32 v21, v17, v17
	v_max_f32_e32 v17, 0, v22
	v_mul_f32_e32 v22, v18, v18
	v_max_f32_e32 v18, 0, v23
	v_mul_f32_e32 v17, v17, v17
	v_max_f32_e32 v19, 0, v19
	v_mul_f32_e32 v18, v18, v18
	v_cvt_pk_bf16_f32 v16, v20, v16
	v_add_co_u32_e32 v20, vcc, s65, v32
	v_mul_f32_e32 v19, v19, v19
	v_cvt_pk_bf16_f32 v17, v17, v18
	v_cvt_pk_bf16_f32 v18, v24, v21
	s_nop 0
	v_addc_co_u32_e32 v21, vcc, 0, v33, vcc
	v_cvt_pk_bf16_f32 v19, v22, v19
	global_store_dwordx4 v[20:21], v[16:19], off
	v_pk_mul_f32 v[8:9], v[8:9], v[72:73] op_sel_hi:[1,0]
	v_pk_mul_f32 v[12:13], v[12:13], v[72:73] op_sel_hi:[1,0]
	v_subrev_u32_e32 v16, s6, v128
	v_ashrrev_i32_e32 v17, 31, v16
	v_pk_mul_f32 v[10:11], v[10:11], v[72:73] op_sel_hi:[1,0]
	v_max_f32_e32 v8, 0, v8
	v_lshlrev_b64 v[16:17], 6, v[16:17]
	v_pk_mul_f32 v[14:15], v[14:15], v[72:73] op_sel_hi:[1,0]
	v_mul_f32_e32 v18, v8, v8
	v_max_f32_e32 v8, 0, v13
	v_max_f32_e32 v9, 0, v9
	v_max_f32_e32 v10, 0, v10
	v_lshl_add_u64 v[16:17], s[46:47], 0, v[16:17]
	v_max_f32_e32 v12, 0, v12
	v_mul_f32_e32 v8, v8, v8
	v_mul_f32_e32 v13, v9, v9
	v_max_f32_e32 v9, 0, v14
	v_mul_f32_e32 v14, v10, v10
	v_max_f32_e32 v10, 0, v15
	v_max_f32_e32 v11, 0, v11
	v_pk_mul_f32 v[0:1], v[0:1], v[72:73] op_sel_hi:[1,0]
	v_lshl_add_u64 v[16:17], v[16:17], 0, v[200:201]
	v_mul_f32_e32 v12, v12, v12
	v_mul_f32_e32 v9, v9, v9
	v_mul_f32_e32 v10, v10, v10
	v_mul_f32_e32 v11, v11, v11
	v_cvt_pk_bf16_f32 v8, v12, v8
	v_pk_mul_f32 v[4:5], v[4:5], v[72:73] op_sel_hi:[1,0]
	v_pk_mul_f32 v[2:3], v[2:3], v[72:73] op_sel_hi:[1,0]
	v_max_f32_e32 v0, 0, v0
	v_cvt_pk_bf16_f32 v9, v9, v10
	v_cvt_pk_bf16_f32 v10, v18, v13
	v_cvt_pk_bf16_f32 v11, v14, v11
	global_store_dwordx4 v[16:17], v[8:11], off
	v_pk_mul_f32 v[6:7], v[6:7], v[72:73] op_sel_hi:[1,0]
	v_max_f32_e32 v4, 0, v4
	v_mul_f32_e32 v8, v0, v0
	v_max_f32_e32 v0, 0, v5
	v_max_f32_e32 v1, 0, v1
	v_max_f32_e32 v2, 0, v2
	v_mul_f32_e32 v4, v4, v4
	v_mul_f32_e32 v0, v0, v0
	v_mul_f32_e32 v5, v1, v1
	v_max_f32_e32 v1, 0, v6
	v_mul_f32_e32 v6, v2, v2
	v_max_f32_e32 v2, 0, v7
	v_mul_f32_e32 v1, v1, v1
	v_max_f32_e32 v3, 0, v3
	v_mul_f32_e32 v2, v2, v2
	v_cvt_pk_bf16_f32 v0, v4, v0
	v_add_co_u32_e32 v4, vcc, 0x10000, v16
	v_mul_f32_e32 v3, v3, v3
	v_cvt_pk_bf16_f32 v1, v1, v2
	v_cvt_pk_bf16_f32 v2, v8, v5
	s_nop 0
	v_addc_co_u32_e32 v5, vcc, 0, v17, vcc
	v_cvt_pk_bf16_f32 v3, v6, v3
	global_store_dwordx4 v[4:5], v[0:3], off
	s_andn2_b64 vcc, exec, s[42:43]
	s_mov_b64 s[2:3], -1
	s_cbranch_vccnz .LBB0_1191
